# strategy 7.4: K-loop setprio flips deleted, one static s_setprio 1 for waves 4-7 at entry
# baseline (speedup 1.0000x reference)
; __device__ __forceinline__ int opaque_tid() { int t = threadIdx.x; asm volatile("" : "+v"(t)); return t; }
; #define LAS __attribute__((address_space(3)))
; template <class Epi, class Sched, bool ALIGN_EPI = false, bool SP2 = false>
; __device__ __forceinline__ void gemm_phase(PG8_LAS unsigned char* lds, const Gemm g, const Sched& S, const Epi& E) {
;     const int tid = opaque_tid(), wid = __builtin_amdgcn_readfirstlane(tid >> 6), lane = tid & 63, wr = wid >> 2, wc = wid & 3, fr = lane & 15, fq = lane >> 4;
; __global__ void __launch_bounds__(NTHREADS, 2) hybrid_fwd(Params P) {
;     extern __shared__ __attribute__((aligned(16))) unsigned char lds_raw[];
;     LAS unsigned char* lds = (LAS unsigned char*)lds_raw;
;     cg::grid_group grid = cg::this_grid();
;     unsigned char* ws = P.ws;
;     volatile LAS unsigned* bst = (volatile LAS unsigned*)(lds + LDS_BYTES - 64);
;     if (threadIdx.x == 0) { bst[0] = 0u; bst[1] = 0u; }
;     __syncthreads();
_Z10hybrid_fwd6Params:
	s_load_dword s96, s[0:1], 0xa0
	s_load_dwordx4 s[88:91], s[0:1], 0x80
	s_load_dwordx2 s[84:85], s[0:1], 0x98
	s_mov_b32 s66, s2
	s_add_u32 s2, s0, 0x98
	v_and_b32_e32 v172, 0x3ff, v0
	s_addc_u32 s3, s1, 0
	v_cmp_eq_u32_e64 s[86:87], 0, v172
	s_nop 0
	v_readfirstlane_b32 s33, v172
	s_nop 3
	s_lshr_b32 s33, s33, 6
	s_cmp_ge_u32 s33, 4
	s_cbranch_scc0 .Lprio_done
	s_setprio 1
.Lprio_done:
	s_and_saveexec_b64 s[4:5], s[86:87]
	s_cbranch_execz .LBB0_2
	s_add_i32 s6, 0, 0x24fc0
	v_mov_b32_e32 v1, 0
	v_mov_b32_e32 v2, s6
	s_add_i32 s6, 0, 0x24fc4
	ds_write_b32 v2, v1
	v_mov_b32_e32 v2, s6
	ds_write_b32 v2, v1

; #define PG8_STAGE(bufoff, gbase, voff) do { _Pragma("unroll") for (int _i = 0; _i < 2; ++_i) \
;         __builtin_amdgcn_global_load_lds((const unsigned*)((const char*)(gbase) + (voff)[_i]), (PG8_LAS unsigned*)(lds + (bufoff) + ldsw + _i * 8192), 16, 0, 0); } while (0)
; #define PG8_LDA(dst, b, h) do { _Pragma("unroll") for (int m = 0; m < 4; ++m) _Pragma("unroll") for (int k = 0; k < 2; ++k) dst[m][k] = *(const PG8_LAS bf16x8*)(lds + PG8_SA(b, h) + aoff + m * 2048 + k * 1024); } while (0)
; #define PG8_LDB(dst, b, h) do { _Pragma("unroll") for (int n = 0; n < 2; ++n) _Pragma("unroll") for (int k = 0; k < 2; ++k) dst[n][k] = *(const PG8_LAS bf16x8*)(lds + PG8_SB(b, h) + boff + n * 2048 + k * 1024); } while (0)
; #define PG8_MMA(ai, bj, At, Bt) do { __builtin_amdgcn_s_setprio(1); _Pragma("unroll") for (int m = 0; m < 4; ++m) _Pragma("unroll") for (int n = 0; n < 2; ++n) _Pragma("unroll") for (int k = 0; k < 2; ++k) \
;         acc[ai][bj][m][n] = __builtin_amdgcn_mfma_f32_16x16x32_bf16(Bt[n][k], At[m][k], acc[ai][bj][m][n], 0, 0, 0); __builtin_amdgcn_s_setprio(0); } while (0)
; #define PG8_WAIT_V(n) asm volatile("s_waitcnt vmcnt(" #n ")" ::: "memory")
; #define PG8_WAIT_L(n) asm volatile("s_waitcnt lgkmcnt(" #n ")" ::: "memory")
; #define PG8_BAR __builtin_amdgcn_s_barrier()
; #define PG8_SCHED __builtin_amdgcn_sched_barrier(0)
; template <class Epi, class Sched, bool ALIGN_EPI = false, bool SP2 = false>
; __device__ __forceinline__ void gemm_phase(PG8_LAS unsigned char* lds, const Gemm g, const Sched& S, const Epi& E) {
;     ...
;             PG8_LDB(B0, 0, 0); PG8_LDB(B1, 0, 1); PG8_SCHED; PG8_LDA(At, 0, 0); PG8_STAGE(PG8_SA(1, 1), a1 + hstep, voffA);
;             PG8_WAIT_V(8); PG8_WAIT_L(0); PG8_BAR; PG8_MMA(0, 0, At, B0); PG8_MMA(0, 1, At, B1); PG8_BAR; PG8_SCHED;
;             PG8_LDA(At, 0, 1); PG8_STAGE(PG8_SB(0, 0), b2, voffB); PG8_STAGE(PG8_SB(0, 1), b2 + hstep, voffB); PG8_STAGE(PG8_SA(0, 0), a2, voffA);
;             PG8_WAIT_V(8); PG8_WAIT_L(0); PG8_BAR; PG8_MMA(1, 0, At, B0); PG8_MMA(1, 1, At, B1); PG8_BAR; PG8_SCHED;
.LBB0_289:
	ds_read_b128 v[146:149], v156
	ds_read_b128 v[160:163], v156 offset:1024
	ds_read_b128 v[164:167], v156 offset:2048
	ds_read_b128 v[168:171], v156 offset:3072
	ds_read_b128 v[180:183], v157
	ds_read_b128 v[184:187], v157 offset:1024
	ds_read_b128 v[188:191], v157 offset:2048
	ds_read_b128 v[192:195], v157 offset:3072
	s_add_u32 s24, s22, 0xfff80080
	s_addc_u32 s25, s23, -1
	s_cmp_eq_u32 s50, 28
	s_cselect_b32 s27, s15, s25
	s_cselect_b32 s26, s46, s24
	s_cselect_b32 s25, s13, s49
	s_cselect_b32 s24, s47, s48
	v_lshl_add_u64 v[150:151], s[22:23], 0, v[138:139]
	s_add_i32 m0, s21, 0xc000
	ds_read_b128 v[196:199], v158
	ds_read_b128 v[200:203], v158 offset:1024
	ds_read_b128 v[204:207], v158 offset:2048
	ds_read_b128 v[208:211], v158 offset:3072
	ds_read_b128 v[212:215], v158 offset:4096
	ds_read_b128 v[216:219], v158 offset:5120
	ds_read_b128 v[220:223], v158 offset:6144
	ds_read_b128 v[224:227], v158 offset:7168
	global_load_lds_dwordx4 v[150:151], off
	v_lshl_add_u64 v[150:151], s[22:23], 0, v[140:141]
	s_add_i32 m0, s21, 0xe000
	s_nop 0
	global_load_lds_dwordx4 v[150:151], off
	s_waitcnt vmcnt(8)
	s_waitcnt lgkmcnt(0)
	s_barrier
	s_waitcnt lgkmcnt(0)
	v_mfma_f32_16x16x32_bf16 v[124:127], v[146:149], v[196:199], v[124:127]
	v_mfma_f32_16x16x32_bf16 v[120:123], v[164:167], v[196:199], v[120:123]
	v_mfma_f32_16x16x32_bf16 v[116:119], v[146:149], v[204:207], v[116:119]
	v_mfma_f32_16x16x32_bf16 v[108:111], v[164:167], v[204:207], v[108:111]
	v_mfma_f32_16x16x32_bf16 v[100:103], v[146:149], v[212:215], v[100:103]
	v_mfma_f32_16x16x32_bf16 v[92:95], v[164:167], v[212:215], v[92:95]
	v_mfma_f32_16x16x32_bf16 v[84:87], v[146:149], v[220:223], v[84:87]
	v_mfma_f32_16x16x32_bf16 v[76:79], v[164:167], v[220:223], v[76:79]
	v_mfma_f32_16x16x32_bf16 v[124:127], v[160:163], v[200:203], v[124:127]
	v_mfma_f32_16x16x32_bf16 v[120:123], v[168:171], v[200:203], v[120:123]
	v_mfma_f32_16x16x32_bf16 v[116:119], v[160:163], v[208:211], v[116:119]
	v_mfma_f32_16x16x32_bf16 v[108:111], v[168:171], v[208:211], v[108:111]
	v_mfma_f32_16x16x32_bf16 v[100:103], v[160:163], v[216:219], v[100:103]
	v_mfma_f32_16x16x32_bf16 v[92:95], v[168:171], v[216:219], v[92:95]
	v_mfma_f32_16x16x32_bf16 v[84:87], v[160:163], v[224:227], v[84:87]
	v_mfma_f32_16x16x32_bf16 v[76:79], v[168:171], v[224:227], v[76:79]
	v_mfma_f32_16x16x32_bf16 v[112:115], v[180:183], v[196:199], v[112:115]
	v_mfma_f32_16x16x32_bf16 v[104:107], v[188:191], v[196:199], v[104:107]
	v_mfma_f32_16x16x32_bf16 v[96:99], v[180:183], v[204:207], v[96:99]
	v_mfma_f32_16x16x32_bf16 v[88:91], v[188:191], v[204:207], v[88:91]
	v_mfma_f32_16x16x32_bf16 v[80:83], v[180:183], v[212:215], v[80:83]
	v_mfma_f32_16x16x32_bf16 v[72:75], v[188:191], v[212:215], v[72:75]
	v_mfma_f32_16x16x32_bf16 v[68:71], v[180:183], v[220:223], v[68:71]
	v_mfma_f32_16x16x32_bf16 v[64:67], v[188:191], v[220:223], v[64:67]
	v_mfma_f32_16x16x32_bf16 v[112:115], v[184:187], v[200:203], v[112:115]
	v_mfma_f32_16x16x32_bf16 v[104:107], v[192:195], v[200:203], v[104:107]
	v_mfma_f32_16x16x32_bf16 v[96:99], v[184:187], v[208:211], v[96:99]
	v_mfma_f32_16x16x32_bf16 v[88:91], v[192:195], v[208:211], v[88:91]
	v_mfma_f32_16x16x32_bf16 v[80:83], v[184:187], v[216:219], v[80:83]
	v_mfma_f32_16x16x32_bf16 v[72:75], v[192:195], v[216:219], v[72:75]
	v_mfma_f32_16x16x32_bf16 v[68:71], v[184:187], v[224:227], v[68:71]
	v_mfma_f32_16x16x32_bf16 v[64:67], v[192:195], v[224:227], v[64:67]
	s_barrier
	s_add_i32 s51, s40, s30
	v_lshl_add_u64 v[150:151], s[24:25], 0, v[134:135]
	s_mov_b32 m0, s51
	ds_read_b128 v[196:199], v158 offset:16384
	ds_read_b128 v[200:203], v158 offset:17408
	ds_read_b128 v[204:207], v158 offset:18432
	ds_read_b128 v[208:211], v158 offset:19456
	ds_read_b128 v[212:215], v158 offset:20480
	ds_read_b128 v[216:219], v158 offset:21504
	ds_read_b128 v[220:223], v158 offset:22528
	ds_read_b128 v[224:227], v158 offset:23552
	global_load_lds_dwordx4 v[150:151], off
	s_add_i32 m0, s51, 0x2000
	s_add_u32 s52, s24, 0x80000
	v_lshl_add_u64 v[228:229], s[24:25], 0, v[130:131]
	s_addc_u32 s53, s25, 0
	s_add_i32 s51, s41, s30
	global_load_lds_dwordx4 v[228:229], off
	v_lshl_add_u64 v[230:231], s[52:53], 0, v[134:135]
	s_mov_b32 m0, s51
	v_lshl_add_u64 v[232:233], s[26:27], 0, v[132:133]
	global_load_lds_dwordx4 v[230:231], off
	v_lshl_add_u64 v[230:231], s[52:53], 0, v[130:131]
	s_add_i32 m0, s51, 0x2000
	s_nop 0
	global_load_lds_dwordx4 v[230:231], off
	v_lshl_add_u64 v[230:231], s[26:27], 0, v[136:137]
	s_mov_b32 m0, s21
	s_nop 0
	global_load_lds_dwordx4 v[230:231], off
	s_mov_b32 m0, s33
	s_nop 0
	global_load_lds_dwordx4 v[232:233], off
	s_waitcnt vmcnt(8)
	s_waitcnt lgkmcnt(0)
	s_barrier
; #define PG8_STAGE(bufoff, gbase, voff) do { _Pragma("unroll") for (int _i = 0; _i < 2; ++_i) \
;         __builtin_amdgcn_global_load_lds((const unsigned*)((const char*)(gbase) + (voff)[_i]), (PG8_LAS unsigned*)(lds + (bufoff) + ldsw + _i * 8192), 16, 0, 0); } while (0)
; #define PG8_LDA(dst, b, h) do { _Pragma("unroll") for (int m = 0; m < 4; ++m) _Pragma("unroll") for (int k = 0; k < 2; ++k) dst[m][k] = *(const PG8_LAS bf16x8*)(lds + PG8_SA(b, h) + aoff + m * 2048 + k * 1024); } while (0)
; #define PG8_LDB(dst, b, h) do { _Pragma("unroll") for (int n = 0; n < 2; ++n) _Pragma("unroll") for (int k = 0; k < 2; ++k) dst[n][k] = *(const PG8_LAS bf16x8*)(lds + PG8_SB(b, h) + boff + n * 2048 + k * 1024); } while (0)
; #define PG8_MMA(ai, bj, At, Bt) do { __builtin_amdgcn_s_setprio(1); _Pragma("unroll") for (int m = 0; m < 4; ++m) _Pragma("unroll") for (int n = 0; n < 2; ++n) _Pragma("unroll") for (int k = 0; k < 2; ++k) \
;         acc[ai][bj][m][n] = __builtin_amdgcn_mfma_f32_16x16x32_bf16(Bt[n][k], At[m][k], acc[ai][bj][m][n], 0, 0, 0); __builtin_amdgcn_s_setprio(0); } while (0)
; #define PG8_WAIT_V(n) asm volatile("s_waitcnt vmcnt(" #n ")" ::: "memory")
; #define PG8_WAIT_L(n) asm volatile("s_waitcnt lgkmcnt(" #n ")" ::: "memory")
; #define PG8_BAR __builtin_amdgcn_s_barrier()
; #define PG8_SCHED __builtin_amdgcn_sched_barrier(0)
; template <class Epi, class Sched, bool ALIGN_EPI = false, bool SP2 = false>
; __device__ __forceinline__ void gemm_phase(PG8_LAS unsigned char* lds, const Gemm g, const Sched& S, const Epi& E) {
;     ...
;             PG8_WAIT_V(8); PG8_WAIT_L(0); PG8_BAR; PG8_MMA(1, 0, At, B0); PG8_MMA(1, 1, At, B1); PG8_BAR; PG8_SCHED;
;             PG8_LDB(B0, 1, 0); PG8_LDB(B1, 1, 1); PG8_SCHED; PG8_LDA(At, 1, 0); PG8_STAGE(PG8_SA(0, 1), a2 + hstep, voffA);
;             PG8_WAIT_V(8); PG8_WAIT_L(0); PG8_BAR; PG8_MMA(0, 0, At, B0); PG8_MMA(0, 1, At, B1); PG8_BAR; PG8_SCHED;
	s_waitcnt lgkmcnt(0)
	v_mfma_f32_16x16x32_bf16 v[60:63], v[146:149], v[196:199], v[60:63]
	v_mfma_f32_16x16x32_bf16 v[56:59], v[164:167], v[196:199], v[56:59]
	v_mfma_f32_16x16x32_bf16 v[52:55], v[146:149], v[204:207], v[52:55]
	v_mfma_f32_16x16x32_bf16 v[44:47], v[164:167], v[204:207], v[44:47]
	v_mfma_f32_16x16x32_bf16 v[36:39], v[146:149], v[212:215], v[36:39]
	v_mfma_f32_16x16x32_bf16 v[28:31], v[164:167], v[212:215], v[28:31]
	v_mfma_f32_16x16x32_bf16 v[20:23], v[146:149], v[220:223], v[20:23]
	v_mfma_f32_16x16x32_bf16 v[12:15], v[164:167], v[220:223], v[12:15]
	v_mfma_f32_16x16x32_bf16 v[60:63], v[160:163], v[200:203], v[60:63]
	v_mfma_f32_16x16x32_bf16 v[56:59], v[168:171], v[200:203], v[56:59]
	v_mfma_f32_16x16x32_bf16 v[52:55], v[160:163], v[208:211], v[52:55]
	v_mfma_f32_16x16x32_bf16 v[44:47], v[168:171], v[208:211], v[44:47]
	v_mfma_f32_16x16x32_bf16 v[36:39], v[160:163], v[216:219], v[36:39]
	v_mfma_f32_16x16x32_bf16 v[28:31], v[168:171], v[216:219], v[28:31]
	v_mfma_f32_16x16x32_bf16 v[20:23], v[160:163], v[224:227], v[20:23]
	v_mfma_f32_16x16x32_bf16 v[12:15], v[168:171], v[224:227], v[12:15]
	v_mfma_f32_16x16x32_bf16 v[48:51], v[180:183], v[196:199], v[48:51]
	v_mfma_f32_16x16x32_bf16 v[40:43], v[188:191], v[196:199], v[40:43]
	v_mfma_f32_16x16x32_bf16 v[32:35], v[180:183], v[204:207], v[32:35]
	v_mfma_f32_16x16x32_bf16 v[24:27], v[188:191], v[204:207], v[24:27]
	v_mfma_f32_16x16x32_bf16 v[16:19], v[180:183], v[212:215], v[16:19]
	v_mfma_f32_16x16x32_bf16 v[8:11], v[188:191], v[212:215], v[8:11]
	v_mfma_f32_16x16x32_bf16 v[4:7], v[180:183], v[220:223], v[4:7]
	v_mfma_f32_16x16x32_bf16 v[0:3], v[188:191], v[220:223], v[0:3]
	v_mfma_f32_16x16x32_bf16 v[48:51], v[184:187], v[200:203], v[48:51]
	v_mfma_f32_16x16x32_bf16 v[40:43], v[192:195], v[200:203], v[40:43]
	v_mfma_f32_16x16x32_bf16 v[32:35], v[184:187], v[208:211], v[32:35]
	v_mfma_f32_16x16x32_bf16 v[24:27], v[192:195], v[208:211], v[24:27]
	v_mfma_f32_16x16x32_bf16 v[16:19], v[184:187], v[216:219], v[16:19]
	v_mfma_f32_16x16x32_bf16 v[8:11], v[192:195], v[216:219], v[8:11]
	v_mfma_f32_16x16x32_bf16 v[4:7], v[184:187], v[224:227], v[4:7]
	v_mfma_f32_16x16x32_bf16 v[0:3], v[192:195], v[224:227], v[0:3]
	s_barrier
	s_add_i32 s51, 0, 0x18000
	v_add_u32_e32 v159, s51, v153
	s_add_i32 s52, 0, 0x1c000
	ds_read_b128 v[146:149], v159
	ds_read_b128 v[160:163], v159 offset:1024
	ds_read_b128 v[164:167], v159 offset:2048
	ds_read_b128 v[168:171], v159 offset:3072
	v_add_u32_e32 v159, s52, v153
	ds_read_b128 v[180:183], v159
	ds_read_b128 v[184:187], v159 offset:1024
	ds_read_b128 v[188:191], v159 offset:2048
	ds_read_b128 v[192:195], v159 offset:3072
	s_add_u32 s26, s26, 0x80000
	s_addc_u32 s27, s27, 0
	s_mov_b32 m0, s34
	v_lshl_add_u64 v[234:235], s[26:27], 0, v[136:137]
	ds_read_b128 v[196:199], v158 offset:32768
	ds_read_b128 v[200:203], v158 offset:33792
	ds_read_b128 v[204:207], v158 offset:34816
	ds_read_b128 v[208:211], v158 offset:35840
	ds_read_b128 v[212:215], v158 offset:36864
	ds_read_b128 v[216:219], v158 offset:37888
	ds_read_b128 v[220:223], v158 offset:38912
	ds_read_b128 v[224:227], v158 offset:39936
	global_load_lds_dwordx4 v[234:235], off
	v_lshl_add_u64 v[234:235], s[26:27], 0, v[132:133]
	s_mov_b32 m0, s35
	s_nop 0
	global_load_lds_dwordx4 v[234:235], off
	s_waitcnt vmcnt(8)
	s_waitcnt lgkmcnt(0)
	s_barrier
	s_waitcnt lgkmcnt(0)
	v_mfma_f32_16x16x32_bf16 v[124:127], v[146:149], v[196:199], v[124:127]
	v_mfma_f32_16x16x32_bf16 v[120:123], v[164:167], v[196:199], v[120:123]
	v_mfma_f32_16x16x32_bf16 v[116:119], v[146:149], v[204:207], v[116:119]
	v_mfma_f32_16x16x32_bf16 v[108:111], v[164:167], v[204:207], v[108:111]
	v_mfma_f32_16x16x32_bf16 v[100:103], v[146:149], v[212:215], v[100:103]
	v_mfma_f32_16x16x32_bf16 v[92:95], v[164:167], v[212:215], v[92:95]
	v_mfma_f32_16x16x32_bf16 v[84:87], v[146:149], v[220:223], v[84:87]
	v_mfma_f32_16x16x32_bf16 v[76:79], v[164:167], v[220:223], v[76:79]
	v_mfma_f32_16x16x32_bf16 v[124:127], v[160:163], v[200:203], v[124:127]
	v_mfma_f32_16x16x32_bf16 v[120:123], v[168:171], v[200:203], v[120:123]
	v_mfma_f32_16x16x32_bf16 v[116:119], v[160:163], v[208:211], v[116:119]
	v_mfma_f32_16x16x32_bf16 v[108:111], v[168:171], v[208:211], v[108:111]
	v_mfma_f32_16x16x32_bf16 v[100:103], v[160:163], v[216:219], v[100:103]
	v_mfma_f32_16x16x32_bf16 v[92:95], v[168:171], v[216:219], v[92:95]
	v_mfma_f32_16x16x32_bf16 v[84:87], v[160:163], v[224:227], v[84:87]
	v_mfma_f32_16x16x32_bf16 v[76:79], v[168:171], v[224:227], v[76:79]
	v_mfma_f32_16x16x32_bf16 v[112:115], v[180:183], v[196:199], v[112:115]
	v_mfma_f32_16x16x32_bf16 v[104:107], v[188:191], v[196:199], v[104:107]
	v_mfma_f32_16x16x32_bf16 v[96:99], v[180:183], v[204:207], v[96:99]
	v_mfma_f32_16x16x32_bf16 v[88:91], v[188:191], v[204:207], v[88:91]
	v_mfma_f32_16x16x32_bf16 v[80:83], v[180:183], v[212:215], v[80:83]
	v_mfma_f32_16x16x32_bf16 v[72:75], v[188:191], v[212:215], v[72:75]
	v_mfma_f32_16x16x32_bf16 v[68:71], v[180:183], v[220:223], v[68:71]
	v_mfma_f32_16x16x32_bf16 v[64:67], v[188:191], v[220:223], v[64:67]
	v_mfma_f32_16x16x32_bf16 v[112:115], v[184:187], v[200:203], v[112:115]
	v_mfma_f32_16x16x32_bf16 v[104:107], v[192:195], v[200:203], v[104:107]
	v_mfma_f32_16x16x32_bf16 v[96:99], v[184:187], v[208:211], v[96:99]
	v_mfma_f32_16x16x32_bf16 v[88:91], v[192:195], v[208:211], v[88:91]
	v_mfma_f32_16x16x32_bf16 v[80:83], v[184:187], v[216:219], v[80:83]
	v_mfma_f32_16x16x32_bf16 v[72:75], v[192:195], v[216:219], v[72:75]
	v_mfma_f32_16x16x32_bf16 v[68:71], v[184:187], v[224:227], v[68:71]
	v_mfma_f32_16x16x32_bf16 v[64:67], v[192:195], v[224:227], v[64:67]
	s_barrier
; #define PG8_STAGE(bufoff, gbase, voff) do { _Pragma("unroll") for (int _i = 0; _i < 2; ++_i) \
;         __builtin_amdgcn_global_load_lds((const unsigned*)((const char*)(gbase) + (voff)[_i]), (PG8_LAS unsigned*)(lds + (bufoff) + ldsw + _i * 8192), 16, 0, 0); } while (0)
; #define PG8_LDA(dst, b, h) do { _Pragma("unroll") for (int m = 0; m < 4; ++m) _Pragma("unroll") for (int k = 0; k < 2; ++k) dst[m][k] = *(const PG8_LAS bf16x8*)(lds + PG8_SA(b, h) + aoff + m * 2048 + k * 1024); } while (0)
; #define PG8_MMA(ai, bj, At, Bt) do { __builtin_amdgcn_s_setprio(1); _Pragma("unroll") for (int m = 0; m < 4; ++m) _Pragma("unroll") for (int n = 0; n < 2; ++n) _Pragma("unroll") for (int k = 0; k < 2; ++k) \
;         acc[ai][bj][m][n] = __builtin_amdgcn_mfma_f32_16x16x32_bf16(Bt[n][k], At[m][k], acc[ai][bj][m][n], 0, 0, 0); __builtin_amdgcn_s_setprio(0); } while (0)
; #define PG8_WAIT_V(n) asm volatile("s_waitcnt vmcnt(" #n ")" ::: "memory")
; #define PG8_WAIT_L(n) asm volatile("s_waitcnt lgkmcnt(" #n ")" ::: "memory")
; #define PG8_BAR __builtin_amdgcn_s_barrier()
; #define PG8_SCHED __builtin_amdgcn_sched_barrier(0)
; template <class Epi, class Sched, bool ALIGN_EPI = false, bool SP2 = false>
; __device__ __forceinline__ void gemm_phase(PG8_LAS unsigned char* lds, const Gemm g, const Sched& S, const Epi& E) {
;     ...
;             PG8_LDA(At, 1, 1); PG8_STAGE(PG8_SB(1, 0), b3, voffB); PG8_STAGE(PG8_SB(1, 1), b3 + hstep, voffB); PG8_STAGE(PG8_SA(1, 0), a3, voffA);
;             PG8_WAIT_V(8); PG8_WAIT_L(0); PG8_BAR; PG8_MMA(1, 0, At, B0); PG8_MMA(1, 1, At, B1); PG8_BAR; PG8_SCHED;
;     ...
;         if constexpr (ALIGN_EPI) { if (wr == 0) PG8_BAR; }
	s_add_i32 s26, s51, s30
	v_lshl_add_u64 v[150:151], v[150:151], 0, s[2:3]
	s_mov_b32 m0, s26
	ds_read_b128 v[196:199], v158 offset:49152
	ds_read_b128 v[200:203], v158 offset:50176
	ds_read_b128 v[204:207], v158 offset:51200
	ds_read_b128 v[208:211], v158 offset:52224
	ds_read_b128 v[212:215], v158 offset:53248
	ds_read_b128 v[216:219], v158 offset:54272
	ds_read_b128 v[220:223], v158 offset:55296
	ds_read_b128 v[224:227], v158 offset:56320
	global_load_lds_dwordx4 v[150:151], off
	s_add_i32 m0, s26, 0x2000
	s_add_u32 s24, s24, 0x80080
	v_lshl_add_u64 v[150:151], v[228:229], 0, s[2:3]
	s_addc_u32 s25, s25, 0
	s_add_i32 s26, s52, s30
	global_load_lds_dwordx4 v[150:151], off
	v_lshl_add_u64 v[150:151], s[24:25], 0, v[134:135]
	s_mov_b32 m0, s26
	s_nop 0
	global_load_lds_dwordx4 v[150:151], off
	v_lshl_add_u64 v[150:151], s[24:25], 0, v[130:131]
	s_add_i32 m0, s26, 0x2000
	s_nop 0
	global_load_lds_dwordx4 v[150:151], off
	v_lshl_add_u64 v[150:151], v[230:231], 0, s[2:3]
	s_mov_b32 m0, s36
	s_nop 0
	global_load_lds_dwordx4 v[150:151], off
	v_lshl_add_u64 v[150:151], v[232:233], 0, s[2:3]
	s_mov_b32 m0, s37
	s_nop 0
	global_load_lds_dwordx4 v[150:151], off
	s_waitcnt vmcnt(8)
	s_waitcnt lgkmcnt(0)
	s_barrier
	s_waitcnt lgkmcnt(0)
	v_mfma_f32_16x16x32_bf16 v[60:63], v[146:149], v[196:199], v[60:63]
	v_mfma_f32_16x16x32_bf16 v[56:59], v[164:167], v[196:199], v[56:59]
	v_mfma_f32_16x16x32_bf16 v[52:55], v[146:149], v[204:207], v[52:55]
	v_mfma_f32_16x16x32_bf16 v[44:47], v[164:167], v[204:207], v[44:47]
	v_mfma_f32_16x16x32_bf16 v[36:39], v[146:149], v[212:215], v[36:39]
	v_mfma_f32_16x16x32_bf16 v[28:31], v[164:167], v[212:215], v[28:31]
	v_mfma_f32_16x16x32_bf16 v[20:23], v[146:149], v[220:223], v[20:23]
	v_mfma_f32_16x16x32_bf16 v[12:15], v[164:167], v[220:223], v[12:15]
	v_mfma_f32_16x16x32_bf16 v[60:63], v[160:163], v[200:203], v[60:63]
	v_mfma_f32_16x16x32_bf16 v[56:59], v[168:171], v[200:203], v[56:59]
	v_mfma_f32_16x16x32_bf16 v[52:55], v[160:163], v[208:211], v[52:55]
	v_mfma_f32_16x16x32_bf16 v[44:47], v[168:171], v[208:211], v[44:47]
	v_mfma_f32_16x16x32_bf16 v[36:39], v[160:163], v[216:219], v[36:39]
	v_mfma_f32_16x16x32_bf16 v[28:31], v[168:171], v[216:219], v[28:31]
	v_mfma_f32_16x16x32_bf16 v[20:23], v[160:163], v[224:227], v[20:23]
	v_mfma_f32_16x16x32_bf16 v[12:15], v[168:171], v[224:227], v[12:15]
	v_mfma_f32_16x16x32_bf16 v[48:51], v[180:183], v[196:199], v[48:51]
	v_mfma_f32_16x16x32_bf16 v[40:43], v[188:191], v[196:199], v[40:43]
	v_mfma_f32_16x16x32_bf16 v[32:35], v[180:183], v[204:207], v[32:35]
	v_mfma_f32_16x16x32_bf16 v[24:27], v[188:191], v[204:207], v[24:27]
	v_mfma_f32_16x16x32_bf16 v[16:19], v[180:183], v[212:215], v[16:19]
	v_mfma_f32_16x16x32_bf16 v[8:11], v[188:191], v[212:215], v[8:11]
	v_mfma_f32_16x16x32_bf16 v[4:7], v[180:183], v[220:223], v[4:7]
	v_mfma_f32_16x16x32_bf16 v[0:3], v[188:191], v[220:223], v[0:3]
	v_mfma_f32_16x16x32_bf16 v[48:51], v[184:187], v[200:203], v[48:51]
	v_mfma_f32_16x16x32_bf16 v[40:43], v[192:195], v[200:203], v[40:43]
	v_mfma_f32_16x16x32_bf16 v[32:35], v[184:187], v[208:211], v[32:35]
	v_mfma_f32_16x16x32_bf16 v[24:27], v[192:195], v[208:211], v[24:27]
	v_mfma_f32_16x16x32_bf16 v[16:19], v[184:187], v[216:219], v[16:19]
	v_mfma_f32_16x16x32_bf16 v[8:11], v[192:195], v[216:219], v[8:11]
	v_mfma_f32_16x16x32_bf16 v[4:7], v[184:187], v[224:227], v[4:7]
	v_mfma_f32_16x16x32_bf16 v[0:3], v[192:195], v[224:227], v[0:3]
	s_barrier
	s_add_i32 s50, s50, 2
	s_add_u32 s22, s22, 0x100
	s_addc_u32 s23, s23, 0
	s_add_u32 s48, s48, 0x100
	s_addc_u32 s49, s49, 0
	s_cmp_gt_u32 s50, 29
	s_cbranch_scc0 .LBB0_289
	s_and_b64 vcc, exec, s[4:5]
	s_cbranch_vccz .LBB0_292
	s_barrier

; #define PG8_STAGE(bufoff, gbase, voff) do { _Pragma("unroll") for (int _i = 0; _i < 2; ++_i) \
;         __builtin_amdgcn_global_load_lds((const unsigned*)((const char*)(gbase) + (voff)[_i]), (PG8_LAS unsigned*)(lds + (bufoff) + ldsw + _i * 8192), 16, 0, 0); } while (0)
; #define PG8_LDA(dst, b, h) do { _Pragma("unroll") for (int m = 0; m < 4; ++m) _Pragma("unroll") for (int k = 0; k < 2; ++k) dst[m][k] = *(const PG8_LAS bf16x8*)(lds + PG8_SA(b, h) + aoff + m * 2048 + k * 1024); } while (0)
; #define PG8_LDB(dst, b, h) do { _Pragma("unroll") for (int n = 0; n < 2; ++n) _Pragma("unroll") for (int k = 0; k < 2; ++k) dst[n][k] = *(const PG8_LAS bf16x8*)(lds + PG8_SB(b, h) + boff + n * 2048 + k * 1024); } while (0)
; #define PG8_MMA(ai, bj, At, Bt) do { __builtin_amdgcn_s_setprio(1); _Pragma("unroll") for (int m = 0; m < 4; ++m) _Pragma("unroll") for (int n = 0; n < 2; ++n) _Pragma("unroll") for (int k = 0; k < 2; ++k) \
;         acc[ai][bj][m][n] = __builtin_amdgcn_mfma_f32_16x16x32_bf16(Bt[n][k], At[m][k], acc[ai][bj][m][n], 0, 0, 0); __builtin_amdgcn_s_setprio(0); } while (0)
; #define PG8_WAIT_V(n) asm volatile("s_waitcnt vmcnt(" #n ")" ::: "memory")
; #define PG8_WAIT_L(n) asm volatile("s_waitcnt lgkmcnt(" #n ")" ::: "memory")
; #define PG8_BAR __builtin_amdgcn_s_barrier()
; #define PG8_SCHED __builtin_amdgcn_sched_barrier(0)
; template <class Epi, class Sched, bool ALIGN_EPI = false, bool SP2 = false>
; __device__ __forceinline__ void gemm_phase(PG8_LAS unsigned char* lds, const Gemm g, const Sched& S, const Epi& E) {
;     ...
;             PG8_LDB(B0, 0, 0); PG8_LDB(B1, 0, 1); PG8_SCHED; PG8_LDA(At, 0, 0); PG8_STAGE(PG8_SA(1, 1), a1 + hstep, voffA);
;             PG8_WAIT_V(8); PG8_WAIT_L(0); PG8_BAR; PG8_MMA(0, 0, At, B0); PG8_MMA(0, 1, At, B1); PG8_BAR; PG8_SCHED;
;             PG8_LDA(At, 0, 1); PG8_STAGE(PG8_SB(0, 0), b2, voffB); PG8_STAGE(PG8_SB(0, 1), b2 + hstep, voffB); PG8_STAGE(PG8_SA(0, 0), a2, voffA);
;             PG8_WAIT_V(8); PG8_WAIT_L(0); PG8_BAR; PG8_MMA(1, 0, At, B0); PG8_MMA(1, 1, At, B1); PG8_BAR; PG8_SCHED;
.LBB0_585:
	ds_read_b128 v[142:145], v149
	ds_read_b128 v[152:155], v149 offset:1024
	ds_read_b128 v[156:159], v149 offset:2048
	ds_read_b128 v[160:163], v149 offset:3072
	ds_read_b128 v[164:167], v150
	ds_read_b128 v[168:171], v150 offset:1024
	ds_read_b128 v[180:183], v150 offset:2048
	ds_read_b128 v[184:187], v150 offset:3072
	s_add_u32 s26, s24, 0xfff80080
	s_addc_u32 s27, s25, -1
	s_cmp_eq_u32 s51, 28
	s_cselect_b32 s29, s17, s27
	s_cselect_b32 s28, s23, s26
	s_cselect_b32 s27, s13, s50
	s_cselect_b32 s26, s48, s49
	v_lshl_add_u64 v[220:221], s[24:25], 0, v[134:135]
	s_add_i32 m0, s34, 0xc000
	ds_read_b128 v[188:191], v151
	ds_read_b128 v[192:195], v151 offset:1024
	ds_read_b128 v[196:199], v151 offset:2048
	ds_read_b128 v[200:203], v151 offset:3072
	ds_read_b128 v[204:207], v151 offset:4096
	ds_read_b128 v[208:211], v151 offset:5120
	ds_read_b128 v[212:215], v151 offset:6144
	ds_read_b128 v[216:219], v151 offset:7168
	global_load_lds_dwordx4 v[220:221], off
	v_lshl_add_u64 v[220:221], s[24:25], 0, v[136:137]
	s_add_i32 m0, s34, 0xe000
	s_nop 0
	global_load_lds_dwordx4 v[220:221], off
	s_waitcnt vmcnt(8)
	s_waitcnt lgkmcnt(0)
	s_barrier
	s_waitcnt lgkmcnt(0)
	v_mfma_f32_16x16x32_bf16 v[124:127], v[142:145], v[188:191], v[124:127]
	v_mfma_f32_16x16x32_bf16 v[120:123], v[156:159], v[188:191], v[120:123]
	v_mfma_f32_16x16x32_bf16 v[108:111], v[142:145], v[196:199], v[108:111]
	v_mfma_f32_16x16x32_bf16 v[104:107], v[156:159], v[196:199], v[104:107]
	v_mfma_f32_16x16x32_bf16 v[92:95], v[142:145], v[204:207], v[92:95]
	v_mfma_f32_16x16x32_bf16 v[88:91], v[156:159], v[204:207], v[88:91]
	v_mfma_f32_16x16x32_bf16 v[76:79], v[142:145], v[212:215], v[76:79]
	v_mfma_f32_16x16x32_bf16 v[72:75], v[156:159], v[212:215], v[72:75]
	v_mfma_f32_16x16x32_bf16 v[124:127], v[152:155], v[192:195], v[124:127]
	v_mfma_f32_16x16x32_bf16 v[120:123], v[160:163], v[192:195], v[120:123]
	v_mfma_f32_16x16x32_bf16 v[108:111], v[152:155], v[200:203], v[108:111]
	v_mfma_f32_16x16x32_bf16 v[104:107], v[160:163], v[200:203], v[104:107]
	v_mfma_f32_16x16x32_bf16 v[92:95], v[152:155], v[208:211], v[92:95]
	v_mfma_f32_16x16x32_bf16 v[88:91], v[160:163], v[208:211], v[88:91]
	v_mfma_f32_16x16x32_bf16 v[76:79], v[152:155], v[216:219], v[76:79]
	v_mfma_f32_16x16x32_bf16 v[72:75], v[160:163], v[216:219], v[72:75]
	v_mfma_f32_16x16x32_bf16 v[116:119], v[164:167], v[188:191], v[116:119]
	v_mfma_f32_16x16x32_bf16 v[112:115], v[180:183], v[188:191], v[112:115]
	v_mfma_f32_16x16x32_bf16 v[100:103], v[164:167], v[196:199], v[100:103]
	v_mfma_f32_16x16x32_bf16 v[96:99], v[180:183], v[196:199], v[96:99]
	v_mfma_f32_16x16x32_bf16 v[84:87], v[164:167], v[204:207], v[84:87]
	v_mfma_f32_16x16x32_bf16 v[80:83], v[180:183], v[204:207], v[80:83]
	v_mfma_f32_16x16x32_bf16 v[68:71], v[164:167], v[212:215], v[68:71]
	v_mfma_f32_16x16x32_bf16 v[64:67], v[180:183], v[212:215], v[64:67]
	v_mfma_f32_16x16x32_bf16 v[116:119], v[168:171], v[192:195], v[116:119]
	v_mfma_f32_16x16x32_bf16 v[112:115], v[184:187], v[192:195], v[112:115]
	v_mfma_f32_16x16x32_bf16 v[100:103], v[168:171], v[200:203], v[100:103]
	v_mfma_f32_16x16x32_bf16 v[96:99], v[184:187], v[200:203], v[96:99]
	v_mfma_f32_16x16x32_bf16 v[84:87], v[168:171], v[208:211], v[84:87]
	v_mfma_f32_16x16x32_bf16 v[80:83], v[184:187], v[208:211], v[80:83]
	v_mfma_f32_16x16x32_bf16 v[68:71], v[168:171], v[216:219], v[68:71]
	v_mfma_f32_16x16x32_bf16 v[64:67], v[184:187], v[216:219], v[64:67]
	s_barrier
	s_add_i32 s52, s45, s33
	v_lshl_add_u64 v[220:221], s[26:27], 0, v[130:131]
	s_mov_b32 m0, s52
	ds_read_b128 v[188:191], v151 offset:16384
	ds_read_b128 v[192:195], v151 offset:17408
	ds_read_b128 v[196:199], v151 offset:18432
	ds_read_b128 v[200:203], v151 offset:19456
	ds_read_b128 v[204:207], v151 offset:20480
	ds_read_b128 v[208:211], v151 offset:21504
	ds_read_b128 v[212:215], v151 offset:22528
	ds_read_b128 v[216:219], v151 offset:23552
	global_load_lds_dwordx4 v[220:221], off
	s_add_i32 m0, s52, 0x2000
	s_add_u32 s52, s26, 0x80000
	v_lshl_add_u64 v[222:223], s[26:27], 0, v[132:133]
	s_addc_u32 s53, s27, 0
	s_add_i32 s54, s46, s33
	global_load_lds_dwordx4 v[222:223], off
	v_lshl_add_u64 v[224:225], s[52:53], 0, v[130:131]
	s_mov_b32 m0, s54
	v_lshl_add_u64 v[226:227], s[28:29], 0, v[132:133]
	global_load_lds_dwordx4 v[224:225], off
	v_lshl_add_u64 v[224:225], s[52:53], 0, v[132:133]
	s_add_i32 m0, s54, 0x2000
	s_nop 0
	global_load_lds_dwordx4 v[224:225], off
	v_lshl_add_u64 v[224:225], s[28:29], 0, v[130:131]
	s_mov_b32 m0, s34
	s_nop 0
	global_load_lds_dwordx4 v[224:225], off
	s_mov_b32 m0, s35
	s_nop 0
	global_load_lds_dwordx4 v[226:227], off
	s_waitcnt vmcnt(8)
	s_waitcnt lgkmcnt(0)
	s_barrier
; #define PG8_STAGE(bufoff, gbase, voff) do { _Pragma("unroll") for (int _i = 0; _i < 2; ++_i) \
;         __builtin_amdgcn_global_load_lds((const unsigned*)((const char*)(gbase) + (voff)[_i]), (PG8_LAS unsigned*)(lds + (bufoff) + ldsw + _i * 8192), 16, 0, 0); } while (0)
; #define PG8_LDA(dst, b, h) do { _Pragma("unroll") for (int m = 0; m < 4; ++m) _Pragma("unroll") for (int k = 0; k < 2; ++k) dst[m][k] = *(const PG8_LAS bf16x8*)(lds + PG8_SA(b, h) + aoff + m * 2048 + k * 1024); } while (0)
; #define PG8_LDB(dst, b, h) do { _Pragma("unroll") for (int n = 0; n < 2; ++n) _Pragma("unroll") for (int k = 0; k < 2; ++k) dst[n][k] = *(const PG8_LAS bf16x8*)(lds + PG8_SB(b, h) + boff + n * 2048 + k * 1024); } while (0)
; #define PG8_MMA(ai, bj, At, Bt) do { __builtin_amdgcn_s_setprio(1); _Pragma("unroll") for (int m = 0; m < 4; ++m) _Pragma("unroll") for (int n = 0; n < 2; ++n) _Pragma("unroll") for (int k = 0; k < 2; ++k) \
;         acc[ai][bj][m][n] = __builtin_amdgcn_mfma_f32_16x16x32_bf16(Bt[n][k], At[m][k], acc[ai][bj][m][n], 0, 0, 0); __builtin_amdgcn_s_setprio(0); } while (0)
; #define PG8_WAIT_V(n) asm volatile("s_waitcnt vmcnt(" #n ")" ::: "memory")
; #define PG8_WAIT_L(n) asm volatile("s_waitcnt lgkmcnt(" #n ")" ::: "memory")
; #define PG8_BAR __builtin_amdgcn_s_barrier()
; #define PG8_SCHED __builtin_amdgcn_sched_barrier(0)
; template <class Epi, class Sched, bool ALIGN_EPI = false, bool SP2 = false>
; __device__ __forceinline__ void gemm_phase(PG8_LAS unsigned char* lds, const Gemm g, const Sched& S, const Epi& E) {
;     ...
;             PG8_WAIT_V(8); PG8_WAIT_L(0); PG8_BAR; PG8_MMA(1, 0, At, B0); PG8_MMA(1, 1, At, B1); PG8_BAR; PG8_SCHED;
;             PG8_LDB(B0, 1, 0); PG8_LDB(B1, 1, 1); PG8_SCHED; PG8_LDA(At, 1, 0); PG8_STAGE(PG8_SA(0, 1), a2 + hstep, voffA);
;             PG8_WAIT_V(8); PG8_WAIT_L(0); PG8_BAR; PG8_MMA(0, 0, At, B0); PG8_MMA(0, 1, At, B1); PG8_BAR; PG8_SCHED;
	s_waitcnt lgkmcnt(0)
	v_mfma_f32_16x16x32_bf16 v[60:63], v[142:145], v[188:191], v[60:63]
	v_mfma_f32_16x16x32_bf16 v[56:59], v[156:159], v[188:191], v[56:59]
	v_mfma_f32_16x16x32_bf16 v[44:47], v[142:145], v[196:199], v[44:47]
	v_mfma_f32_16x16x32_bf16 v[40:43], v[156:159], v[196:199], v[40:43]
	v_mfma_f32_16x16x32_bf16 v[28:31], v[142:145], v[204:207], v[28:31]
	v_mfma_f32_16x16x32_bf16 v[24:27], v[156:159], v[204:207], v[24:27]
	v_mfma_f32_16x16x32_bf16 v[12:15], v[142:145], v[212:215], v[12:15]
	v_mfma_f32_16x16x32_bf16 v[8:11], v[156:159], v[212:215], v[8:11]
	v_mfma_f32_16x16x32_bf16 v[60:63], v[152:155], v[192:195], v[60:63]
	v_mfma_f32_16x16x32_bf16 v[56:59], v[160:163], v[192:195], v[56:59]
	v_mfma_f32_16x16x32_bf16 v[44:47], v[152:155], v[200:203], v[44:47]
	v_mfma_f32_16x16x32_bf16 v[40:43], v[160:163], v[200:203], v[40:43]
	v_mfma_f32_16x16x32_bf16 v[28:31], v[152:155], v[208:211], v[28:31]
	v_mfma_f32_16x16x32_bf16 v[24:27], v[160:163], v[208:211], v[24:27]
	v_mfma_f32_16x16x32_bf16 v[12:15], v[152:155], v[216:219], v[12:15]
	v_mfma_f32_16x16x32_bf16 v[8:11], v[160:163], v[216:219], v[8:11]
	v_mfma_f32_16x16x32_bf16 v[52:55], v[164:167], v[188:191], v[52:55]
	v_mfma_f32_16x16x32_bf16 v[48:51], v[180:183], v[188:191], v[48:51]
	v_mfma_f32_16x16x32_bf16 v[36:39], v[164:167], v[196:199], v[36:39]
	v_mfma_f32_16x16x32_bf16 v[32:35], v[180:183], v[196:199], v[32:35]
	v_mfma_f32_16x16x32_bf16 v[20:23], v[164:167], v[204:207], v[20:23]
	v_mfma_f32_16x16x32_bf16 v[16:19], v[180:183], v[204:207], v[16:19]
	v_mfma_f32_16x16x32_bf16 v[4:7], v[164:167], v[212:215], v[4:7]
	v_mfma_f32_16x16x32_bf16 v[0:3], v[180:183], v[212:215], v[0:3]
	v_mfma_f32_16x16x32_bf16 v[52:55], v[168:171], v[192:195], v[52:55]
	v_mfma_f32_16x16x32_bf16 v[48:51], v[184:187], v[192:195], v[48:51]
	v_mfma_f32_16x16x32_bf16 v[36:39], v[168:171], v[200:203], v[36:39]
	v_mfma_f32_16x16x32_bf16 v[32:35], v[184:187], v[200:203], v[32:35]
	v_mfma_f32_16x16x32_bf16 v[20:23], v[168:171], v[208:211], v[20:23]
	v_mfma_f32_16x16x32_bf16 v[16:19], v[184:187], v[208:211], v[16:19]
	v_mfma_f32_16x16x32_bf16 v[4:7], v[168:171], v[216:219], v[4:7]
	v_mfma_f32_16x16x32_bf16 v[0:3], v[184:187], v[216:219], v[0:3]
	s_barrier
	s_add_i32 s52, 0, 0x18000
	s_add_i32 s53, 0, 0x1c000
	v_add_u32_e32 v160, s52, v147
	v_add_u32_e32 v179, s53, v147
	ds_read_b128 v[142:145], v160
	ds_read_b128 v[152:155], v160 offset:1024
	ds_read_b128 v[156:159], v160 offset:2048
	ds_read_b128 v[160:163], v160 offset:3072
	ds_read_b128 v[164:167], v179
	ds_read_b128 v[168:171], v179 offset:1024
	ds_read_b128 v[180:183], v179 offset:2048
	ds_read_b128 v[184:187], v179 offset:3072
	s_add_u32 s28, s28, 0x80000
	s_addc_u32 s29, s29, 0
	s_mov_b32 m0, s36
	v_lshl_add_u64 v[228:229], s[28:29], 0, v[130:131]
	ds_read_b128 v[188:191], v151 offset:32768
	ds_read_b128 v[192:195], v151 offset:33792
	ds_read_b128 v[196:199], v151 offset:34816
	ds_read_b128 v[200:203], v151 offset:35840
	ds_read_b128 v[204:207], v151 offset:36864
	ds_read_b128 v[208:211], v151 offset:37888
	ds_read_b128 v[212:215], v151 offset:38912
	ds_read_b128 v[216:219], v151 offset:39936
	global_load_lds_dwordx4 v[228:229], off
	v_lshl_add_u64 v[228:229], s[28:29], 0, v[132:133]
	s_mov_b32 m0, s37
	s_nop 0
	global_load_lds_dwordx4 v[228:229], off
	s_waitcnt vmcnt(8)
	s_waitcnt lgkmcnt(0)
	s_barrier
	s_waitcnt lgkmcnt(0)
	v_mfma_f32_16x16x32_bf16 v[124:127], v[142:145], v[188:191], v[124:127]
	v_mfma_f32_16x16x32_bf16 v[120:123], v[156:159], v[188:191], v[120:123]
	v_mfma_f32_16x16x32_bf16 v[108:111], v[142:145], v[196:199], v[108:111]
	v_mfma_f32_16x16x32_bf16 v[104:107], v[156:159], v[196:199], v[104:107]
	v_mfma_f32_16x16x32_bf16 v[92:95], v[142:145], v[204:207], v[92:95]
	v_mfma_f32_16x16x32_bf16 v[88:91], v[156:159], v[204:207], v[88:91]
	v_mfma_f32_16x16x32_bf16 v[76:79], v[142:145], v[212:215], v[76:79]
	v_mfma_f32_16x16x32_bf16 v[72:75], v[156:159], v[212:215], v[72:75]
	v_mfma_f32_16x16x32_bf16 v[124:127], v[152:155], v[192:195], v[124:127]
	v_mfma_f32_16x16x32_bf16 v[120:123], v[160:163], v[192:195], v[120:123]
	v_mfma_f32_16x16x32_bf16 v[108:111], v[152:155], v[200:203], v[108:111]
	v_mfma_f32_16x16x32_bf16 v[104:107], v[160:163], v[200:203], v[104:107]
	v_mfma_f32_16x16x32_bf16 v[92:95], v[152:155], v[208:211], v[92:95]
	v_mfma_f32_16x16x32_bf16 v[88:91], v[160:163], v[208:211], v[88:91]
	v_mfma_f32_16x16x32_bf16 v[76:79], v[152:155], v[216:219], v[76:79]
	v_mfma_f32_16x16x32_bf16 v[72:75], v[160:163], v[216:219], v[72:75]
	v_mfma_f32_16x16x32_bf16 v[116:119], v[164:167], v[188:191], v[116:119]
	v_mfma_f32_16x16x32_bf16 v[112:115], v[180:183], v[188:191], v[112:115]
	v_mfma_f32_16x16x32_bf16 v[100:103], v[164:167], v[196:199], v[100:103]
	v_mfma_f32_16x16x32_bf16 v[96:99], v[180:183], v[196:199], v[96:99]
	v_mfma_f32_16x16x32_bf16 v[84:87], v[164:167], v[204:207], v[84:87]
	v_mfma_f32_16x16x32_bf16 v[80:83], v[180:183], v[204:207], v[80:83]
	v_mfma_f32_16x16x32_bf16 v[68:71], v[164:167], v[212:215], v[68:71]
	v_mfma_f32_16x16x32_bf16 v[64:67], v[180:183], v[212:215], v[64:67]
	v_mfma_f32_16x16x32_bf16 v[116:119], v[168:171], v[192:195], v[116:119]
	v_mfma_f32_16x16x32_bf16 v[112:115], v[184:187], v[192:195], v[112:115]
	v_mfma_f32_16x16x32_bf16 v[100:103], v[168:171], v[200:203], v[100:103]
	v_mfma_f32_16x16x32_bf16 v[96:99], v[184:187], v[200:203], v[96:99]
	v_mfma_f32_16x16x32_bf16 v[84:87], v[168:171], v[208:211], v[84:87]
	v_mfma_f32_16x16x32_bf16 v[80:83], v[184:187], v[208:211], v[80:83]
	v_mfma_f32_16x16x32_bf16 v[68:71], v[168:171], v[216:219], v[68:71]
	v_mfma_f32_16x16x32_bf16 v[64:67], v[184:187], v[216:219], v[64:67]
	s_barrier
; #define PG8_STAGE(bufoff, gbase, voff) do { _Pragma("unroll") for (int _i = 0; _i < 2; ++_i) \
;         __builtin_amdgcn_global_load_lds((const unsigned*)((const char*)(gbase) + (voff)[_i]), (PG8_LAS unsigned*)(lds + (bufoff) + ldsw + _i * 8192), 16, 0, 0); } while (0)
; #define PG8_LDA(dst, b, h) do { _Pragma("unroll") for (int m = 0; m < 4; ++m) _Pragma("unroll") for (int k = 0; k < 2; ++k) dst[m][k] = *(const PG8_LAS bf16x8*)(lds + PG8_SA(b, h) + aoff + m * 2048 + k * 1024); } while (0)
; #define PG8_MMA(ai, bj, At, Bt) do { __builtin_amdgcn_s_setprio(1); _Pragma("unroll") for (int m = 0; m < 4; ++m) _Pragma("unroll") for (int n = 0; n < 2; ++n) _Pragma("unroll") for (int k = 0; k < 2; ++k) \
;         acc[ai][bj][m][n] = __builtin_amdgcn_mfma_f32_16x16x32_bf16(Bt[n][k], At[m][k], acc[ai][bj][m][n], 0, 0, 0); __builtin_amdgcn_s_setprio(0); } while (0)
; #define PG8_WAIT_V(n) asm volatile("s_waitcnt vmcnt(" #n ")" ::: "memory")
; #define PG8_WAIT_L(n) asm volatile("s_waitcnt lgkmcnt(" #n ")" ::: "memory")
; #define PG8_BAR __builtin_amdgcn_s_barrier()
; #define PG8_SCHED __builtin_amdgcn_sched_barrier(0)
; template <class Epi, class Sched, bool ALIGN_EPI = false, bool SP2 = false>
; __device__ __forceinline__ void gemm_phase(PG8_LAS unsigned char* lds, const Gemm g, const Sched& S, const Epi& E) {
;     ...
;             PG8_LDA(At, 1, 1); PG8_STAGE(PG8_SB(1, 0), b3, voffB); PG8_STAGE(PG8_SB(1, 1), b3 + hstep, voffB); PG8_STAGE(PG8_SA(1, 0), a3, voffA);
;             PG8_WAIT_V(8); PG8_WAIT_L(0); PG8_BAR; PG8_MMA(1, 0, At, B0); PG8_MMA(1, 1, At, B1); PG8_BAR; PG8_SCHED;
;     ...
;         if constexpr (ALIGN_EPI) { if (wr == 0) PG8_BAR; }
	s_add_i32 s28, s52, s33
	v_lshl_add_u64 v[220:221], v[220:221], 0, s[4:5]
	s_mov_b32 m0, s28
	ds_read_b128 v[188:191], v151 offset:49152
	ds_read_b128 v[192:195], v151 offset:50176
	ds_read_b128 v[196:199], v151 offset:51200
	ds_read_b128 v[200:203], v151 offset:52224
	ds_read_b128 v[204:207], v151 offset:53248
	ds_read_b128 v[208:211], v151 offset:54272
	ds_read_b128 v[212:215], v151 offset:55296
	ds_read_b128 v[216:219], v151 offset:56320
	global_load_lds_dwordx4 v[220:221], off
	s_add_i32 m0, s28, 0x2000
	s_add_u32 s26, s26, 0x80080
	v_lshl_add_u64 v[220:221], v[222:223], 0, s[4:5]
	s_addc_u32 s27, s27, 0
	s_add_i32 s28, s53, s33
	global_load_lds_dwordx4 v[220:221], off
	v_lshl_add_u64 v[220:221], s[26:27], 0, v[130:131]
	s_mov_b32 m0, s28
	s_nop 0
	global_load_lds_dwordx4 v[220:221], off
	v_lshl_add_u64 v[220:221], s[26:27], 0, v[132:133]
	s_add_i32 m0, s28, 0x2000
	s_nop 0
	global_load_lds_dwordx4 v[220:221], off
	v_lshl_add_u64 v[220:221], v[224:225], 0, s[4:5]
	s_mov_b32 m0, s41
	s_nop 0
	global_load_lds_dwordx4 v[220:221], off
	v_lshl_add_u64 v[220:221], v[226:227], 0, s[4:5]
	s_mov_b32 m0, s44
	s_nop 0
	global_load_lds_dwordx4 v[220:221], off
	s_waitcnt vmcnt(8)
	s_waitcnt lgkmcnt(0)
	s_barrier
	s_waitcnt lgkmcnt(0)
	v_mfma_f32_16x16x32_bf16 v[60:63], v[142:145], v[188:191], v[60:63]
	v_mfma_f32_16x16x32_bf16 v[56:59], v[156:159], v[188:191], v[56:59]
	v_mfma_f32_16x16x32_bf16 v[44:47], v[142:145], v[196:199], v[44:47]
	v_mfma_f32_16x16x32_bf16 v[40:43], v[156:159], v[196:199], v[40:43]
	v_mfma_f32_16x16x32_bf16 v[28:31], v[142:145], v[204:207], v[28:31]
	v_mfma_f32_16x16x32_bf16 v[24:27], v[156:159], v[204:207], v[24:27]
	v_mfma_f32_16x16x32_bf16 v[12:15], v[142:145], v[212:215], v[12:15]
	v_mfma_f32_16x16x32_bf16 v[8:11], v[156:159], v[212:215], v[8:11]
	v_mfma_f32_16x16x32_bf16 v[60:63], v[152:155], v[192:195], v[60:63]
	v_mfma_f32_16x16x32_bf16 v[56:59], v[160:163], v[192:195], v[56:59]
	v_mfma_f32_16x16x32_bf16 v[44:47], v[152:155], v[200:203], v[44:47]
	v_mfma_f32_16x16x32_bf16 v[40:43], v[160:163], v[200:203], v[40:43]
	v_mfma_f32_16x16x32_bf16 v[28:31], v[152:155], v[208:211], v[28:31]
	v_mfma_f32_16x16x32_bf16 v[24:27], v[160:163], v[208:211], v[24:27]
	v_mfma_f32_16x16x32_bf16 v[12:15], v[152:155], v[216:219], v[12:15]
	v_mfma_f32_16x16x32_bf16 v[8:11], v[160:163], v[216:219], v[8:11]
	v_mfma_f32_16x16x32_bf16 v[52:55], v[164:167], v[188:191], v[52:55]
	v_mfma_f32_16x16x32_bf16 v[48:51], v[180:183], v[188:191], v[48:51]
	v_mfma_f32_16x16x32_bf16 v[36:39], v[164:167], v[196:199], v[36:39]
	v_mfma_f32_16x16x32_bf16 v[32:35], v[180:183], v[196:199], v[32:35]
	v_mfma_f32_16x16x32_bf16 v[20:23], v[164:167], v[204:207], v[20:23]
	v_mfma_f32_16x16x32_bf16 v[16:19], v[180:183], v[204:207], v[16:19]
	v_mfma_f32_16x16x32_bf16 v[4:7], v[164:167], v[212:215], v[4:7]
	v_mfma_f32_16x16x32_bf16 v[0:3], v[180:183], v[212:215], v[0:3]
	v_mfma_f32_16x16x32_bf16 v[52:55], v[168:171], v[192:195], v[52:55]
	v_mfma_f32_16x16x32_bf16 v[48:51], v[184:187], v[192:195], v[48:51]
	v_mfma_f32_16x16x32_bf16 v[36:39], v[168:171], v[200:203], v[36:39]
	v_mfma_f32_16x16x32_bf16 v[32:35], v[184:187], v[200:203], v[32:35]
	v_mfma_f32_16x16x32_bf16 v[20:23], v[168:171], v[208:211], v[20:23]
	v_mfma_f32_16x16x32_bf16 v[16:19], v[184:187], v[208:211], v[16:19]
	v_mfma_f32_16x16x32_bf16 v[4:7], v[168:171], v[216:219], v[4:7]
	v_mfma_f32_16x16x32_bf16 v[0:3], v[184:187], v[216:219], v[0:3]
	s_barrier
	s_add_i32 s51, s51, 2
	s_add_u32 s24, s24, 0x100
	s_addc_u32 s25, s25, 0
	s_add_u32 s49, s49, 0x100
	s_addc_u32 s50, s50, 0
	s_cmp_gt_u32 s51, 29
	s_cbranch_scc0 .LBB0_585
	s_and_b64 vcc, exec, s[6:7]
	s_cbranch_vccz .LBB0_588
	s_barrier

; #define PG8_STAGE(bufoff, gbase, voff) do { _Pragma("unroll") for (int _i = 0; _i < 2; ++_i) \
;         __builtin_amdgcn_global_load_lds((const unsigned*)((const char*)(gbase) + (voff)[_i]), (PG8_LAS unsigned*)(lds + (bufoff) + ldsw + _i * 8192), 16, 0, 0); } while (0)
; #define PG8_LDA(dst, b, h) do { _Pragma("unroll") for (int m = 0; m < 4; ++m) _Pragma("unroll") for (int k = 0; k < 2; ++k) dst[m][k] = *(const PG8_LAS bf16x8*)(lds + PG8_SA(b, h) + aoff + m * 2048 + k * 1024); } while (0)
; #define PG8_LDB(dst, b, h) do { _Pragma("unroll") for (int n = 0; n < 2; ++n) _Pragma("unroll") for (int k = 0; k < 2; ++k) dst[n][k] = *(const PG8_LAS bf16x8*)(lds + PG8_SB(b, h) + boff + n * 2048 + k * 1024); } while (0)
; #define PG8_MMA(ai, bj, At, Bt) do { __builtin_amdgcn_s_setprio(1); _Pragma("unroll") for (int m = 0; m < 4; ++m) _Pragma("unroll") for (int n = 0; n < 2; ++n) _Pragma("unroll") for (int k = 0; k < 2; ++k) \
;         acc[ai][bj][m][n] = __builtin_amdgcn_mfma_f32_16x16x32_bf16(Bt[n][k], At[m][k], acc[ai][bj][m][n], 0, 0, 0); __builtin_amdgcn_s_setprio(0); } while (0)
; #define PG8_WAIT_V(n) asm volatile("s_waitcnt vmcnt(" #n ")" ::: "memory")
; #define PG8_WAIT_L(n) asm volatile("s_waitcnt lgkmcnt(" #n ")" ::: "memory")
; #define PG8_BAR __builtin_amdgcn_s_barrier()
; #define PG8_SCHED __builtin_amdgcn_sched_barrier(0)
; template <class Epi, class Sched, bool ALIGN_EPI = false, bool SP2 = false>
; __device__ __forceinline__ void gemm_phase(PG8_LAS unsigned char* lds, const Gemm g, const Sched& S, const Epi& E) {
;     ...
;             PG8_LDB(B0, 0, 0); PG8_LDB(B1, 0, 1); PG8_SCHED; PG8_LDA(At, 0, 0); PG8_STAGE(PG8_SA(1, 1), a1 + hstep, voffA);
;             PG8_WAIT_V(8); PG8_WAIT_L(0); PG8_BAR; PG8_MMA(0, 0, At, B0); PG8_MMA(0, 1, At, B1); PG8_BAR; PG8_SCHED;
;             PG8_LDA(At, 0, 1); PG8_STAGE(PG8_SB(0, 0), b2, voffB); PG8_STAGE(PG8_SB(0, 1), b2 + hstep, voffB); PG8_STAGE(PG8_SA(0, 0), a2, voffA);
;             PG8_WAIT_V(8); PG8_WAIT_L(0); PG8_BAR; PG8_MMA(1, 0, At, B0); PG8_MMA(1, 1, At, B1); PG8_BAR; PG8_SCHED;
.LBB0_837:
	ds_read_b128 v[146:149], v158
	ds_read_b128 v[150:153], v158 offset:1024
	ds_read_b128 v[162:165], v158 offset:2048
	ds_read_b128 v[166:169], v158 offset:3072
	ds_read_b128 v[180:183], v159
	ds_read_b128 v[184:187], v159 offset:1024
	ds_read_b128 v[188:191], v159 offset:2048
	ds_read_b128 v[192:195], v159 offset:3072
	s_add_u32 s22, s20, 0xfff80080
	s_addc_u32 s23, s21, -1
	s_cmp_eq_u32 s50, 28
	s_cselect_b32 s25, s11, s23
	s_cselect_b32 s24, s46, s22
	s_cselect_b32 s23, s7, s49
	s_cselect_b32 s22, s47, s48
	v_lshl_add_u64 v[170:171], s[20:21], 0, v[138:139]
	s_add_i32 m0, s30, 0xc000
	ds_read_b128 v[196:199], v160
	ds_read_b128 v[200:203], v160 offset:1024
	ds_read_b128 v[204:207], v160 offset:2048
	ds_read_b128 v[208:211], v160 offset:3072
	ds_read_b128 v[212:215], v160 offset:4096
	ds_read_b128 v[216:219], v160 offset:5120
	ds_read_b128 v[220:223], v160 offset:6144
	ds_read_b128 v[224:227], v160 offset:7168
	global_load_lds_dwordx4 v[170:171], off
	v_lshl_add_u64 v[170:171], s[20:21], 0, v[140:141]
	s_add_i32 m0, s30, 0xe000
	s_nop 0
	global_load_lds_dwordx4 v[170:171], off
	s_waitcnt vmcnt(8)
	s_waitcnt lgkmcnt(0)
	s_barrier
	s_waitcnt lgkmcnt(0)
	v_mfma_f32_16x16x32_bf16 v[124:127], v[146:149], v[196:199], v[124:127]
	v_mfma_f32_16x16x32_bf16 v[116:119], v[162:165], v[196:199], v[116:119]
	v_mfma_f32_16x16x32_bf16 v[108:111], v[146:149], v[204:207], v[108:111]
	v_mfma_f32_16x16x32_bf16 v[100:103], v[162:165], v[204:207], v[100:103]
	v_mfma_f32_16x16x32_bf16 v[92:95], v[146:149], v[212:215], v[92:95]
	v_mfma_f32_16x16x32_bf16 v[84:87], v[162:165], v[212:215], v[84:87]
	v_mfma_f32_16x16x32_bf16 v[76:79], v[146:149], v[220:223], v[76:79]
	v_mfma_f32_16x16x32_bf16 v[68:71], v[162:165], v[220:223], v[68:71]
	v_mfma_f32_16x16x32_bf16 v[124:127], v[150:153], v[200:203], v[124:127]
	v_mfma_f32_16x16x32_bf16 v[116:119], v[166:169], v[200:203], v[116:119]
	v_mfma_f32_16x16x32_bf16 v[108:111], v[150:153], v[208:211], v[108:111]
	v_mfma_f32_16x16x32_bf16 v[100:103], v[166:169], v[208:211], v[100:103]
	v_mfma_f32_16x16x32_bf16 v[92:95], v[150:153], v[216:219], v[92:95]
	v_mfma_f32_16x16x32_bf16 v[84:87], v[166:169], v[216:219], v[84:87]
	v_mfma_f32_16x16x32_bf16 v[76:79], v[150:153], v[224:227], v[76:79]
	v_mfma_f32_16x16x32_bf16 v[68:71], v[166:169], v[224:227], v[68:71]
	v_mfma_f32_16x16x32_bf16 v[120:123], v[180:183], v[196:199], v[120:123]
	v_mfma_f32_16x16x32_bf16 v[112:115], v[188:191], v[196:199], v[112:115]
	v_mfma_f32_16x16x32_bf16 v[104:107], v[180:183], v[204:207], v[104:107]
	v_mfma_f32_16x16x32_bf16 v[96:99], v[188:191], v[204:207], v[96:99]
	v_mfma_f32_16x16x32_bf16 v[88:91], v[180:183], v[212:215], v[88:91]
	v_mfma_f32_16x16x32_bf16 v[80:83], v[188:191], v[212:215], v[80:83]
	v_mfma_f32_16x16x32_bf16 v[72:75], v[180:183], v[220:223], v[72:75]
	v_mfma_f32_16x16x32_bf16 v[64:67], v[188:191], v[220:223], v[64:67]
	v_mfma_f32_16x16x32_bf16 v[120:123], v[184:187], v[200:203], v[120:123]
	v_mfma_f32_16x16x32_bf16 v[112:115], v[192:195], v[200:203], v[112:115]
	v_mfma_f32_16x16x32_bf16 v[104:107], v[184:187], v[208:211], v[104:107]
	v_mfma_f32_16x16x32_bf16 v[96:99], v[192:195], v[208:211], v[96:99]
	v_mfma_f32_16x16x32_bf16 v[88:91], v[184:187], v[216:219], v[88:91]
	v_mfma_f32_16x16x32_bf16 v[80:83], v[192:195], v[216:219], v[80:83]
	v_mfma_f32_16x16x32_bf16 v[72:75], v[184:187], v[224:227], v[72:75]
	v_mfma_f32_16x16x32_bf16 v[64:67], v[192:195], v[224:227], v[64:67]
	s_barrier
	s_add_i32 s51, s37, s26
	v_lshl_add_u64 v[170:171], s[22:23], 0, v[134:135]
	s_mov_b32 m0, s51
	ds_read_b128 v[196:199], v160 offset:16384
	ds_read_b128 v[200:203], v160 offset:17408
	ds_read_b128 v[204:207], v160 offset:18432
	ds_read_b128 v[208:211], v160 offset:19456
	ds_read_b128 v[212:215], v160 offset:20480
	ds_read_b128 v[216:219], v160 offset:21504
	ds_read_b128 v[220:223], v160 offset:22528
	ds_read_b128 v[224:227], v160 offset:23552
	global_load_lds_dwordx4 v[170:171], off
	s_add_i32 m0, s51, 0x2000
	s_add_u32 s52, s22, 0x80000
	v_lshl_add_u64 v[228:229], s[22:23], 0, v[130:131]
	s_addc_u32 s53, s23, 0
	s_add_i32 s51, s40, s26
	global_load_lds_dwordx4 v[228:229], off
	v_lshl_add_u64 v[230:231], s[52:53], 0, v[134:135]
	s_mov_b32 m0, s51
	v_lshl_add_u64 v[232:233], s[24:25], 0, v[132:133]
	global_load_lds_dwordx4 v[230:231], off
	v_lshl_add_u64 v[230:231], s[52:53], 0, v[130:131]
	s_add_i32 m0, s51, 0x2000
	s_nop 0
	global_load_lds_dwordx4 v[230:231], off
	v_lshl_add_u64 v[230:231], s[24:25], 0, v[136:137]
	s_mov_b32 m0, s30
	s_nop 0
	global_load_lds_dwordx4 v[230:231], off
	s_mov_b32 m0, s31
	s_nop 0
	global_load_lds_dwordx4 v[232:233], off
	s_waitcnt vmcnt(8)
	s_waitcnt lgkmcnt(0)
	s_barrier
; #define PG8_STAGE(bufoff, gbase, voff) do { _Pragma("unroll") for (int _i = 0; _i < 2; ++_i) \
;         __builtin_amdgcn_global_load_lds((const unsigned*)((const char*)(gbase) + (voff)[_i]), (PG8_LAS unsigned*)(lds + (bufoff) + ldsw + _i * 8192), 16, 0, 0); } while (0)
; #define PG8_LDA(dst, b, h) do { _Pragma("unroll") for (int m = 0; m < 4; ++m) _Pragma("unroll") for (int k = 0; k < 2; ++k) dst[m][k] = *(const PG8_LAS bf16x8*)(lds + PG8_SA(b, h) + aoff + m * 2048 + k * 1024); } while (0)
; #define PG8_LDB(dst, b, h) do { _Pragma("unroll") for (int n = 0; n < 2; ++n) _Pragma("unroll") for (int k = 0; k < 2; ++k) dst[n][k] = *(const PG8_LAS bf16x8*)(lds + PG8_SB(b, h) + boff + n * 2048 + k * 1024); } while (0)
; #define PG8_MMA(ai, bj, At, Bt) do { __builtin_amdgcn_s_setprio(1); _Pragma("unroll") for (int m = 0; m < 4; ++m) _Pragma("unroll") for (int n = 0; n < 2; ++n) _Pragma("unroll") for (int k = 0; k < 2; ++k) \
;         acc[ai][bj][m][n] = __builtin_amdgcn_mfma_f32_16x16x32_bf16(Bt[n][k], At[m][k], acc[ai][bj][m][n], 0, 0, 0); __builtin_amdgcn_s_setprio(0); } while (0)
; #define PG8_WAIT_V(n) asm volatile("s_waitcnt vmcnt(" #n ")" ::: "memory")
; #define PG8_WAIT_L(n) asm volatile("s_waitcnt lgkmcnt(" #n ")" ::: "memory")
; #define PG8_BAR __builtin_amdgcn_s_barrier()
; #define PG8_SCHED __builtin_amdgcn_sched_barrier(0)
; template <class Epi, class Sched, bool ALIGN_EPI = false, bool SP2 = false>
; __device__ __forceinline__ void gemm_phase(PG8_LAS unsigned char* lds, const Gemm g, const Sched& S, const Epi& E) {
;     ...
;             PG8_WAIT_V(8); PG8_WAIT_L(0); PG8_BAR; PG8_MMA(0, 0, At, B0); PG8_MMA(0, 1, At, B1); PG8_BAR; PG8_SCHED;
;             PG8_LDA(At, 0, 1); PG8_STAGE(PG8_SB(0, 0), b2, voffB); PG8_STAGE(PG8_SB(0, 1), b2 + hstep, voffB); PG8_STAGE(PG8_SA(0, 0), a2, voffA);
;             PG8_WAIT_V(8); PG8_WAIT_L(0); PG8_BAR; PG8_MMA(1, 0, At, B0); PG8_MMA(1, 1, At, B1); PG8_BAR; PG8_SCHED;
;             PG8_LDB(B0, 1, 0); PG8_LDB(B1, 1, 1); PG8_SCHED; PG8_LDA(At, 1, 0); PG8_STAGE(PG8_SA(0, 1), a2 + hstep, voffA);
;             PG8_WAIT_V(8); PG8_WAIT_L(0); PG8_BAR; PG8_MMA(0, 0, At, B0); PG8_MMA(0, 1, At, B1); PG8_BAR; PG8_SCHED;
	s_waitcnt lgkmcnt(0)
	v_mfma_f32_16x16x32_bf16 v[60:63], v[146:149], v[196:199], v[60:63]
	v_mfma_f32_16x16x32_bf16 v[52:55], v[162:165], v[196:199], v[52:55]
	v_mfma_f32_16x16x32_bf16 v[44:47], v[146:149], v[204:207], v[44:47]
	v_mfma_f32_16x16x32_bf16 v[36:39], v[162:165], v[204:207], v[36:39]
	v_mfma_f32_16x16x32_bf16 v[28:31], v[146:149], v[212:215], v[28:31]
	v_mfma_f32_16x16x32_bf16 v[20:23], v[162:165], v[212:215], v[20:23]
	v_mfma_f32_16x16x32_bf16 v[12:15], v[146:149], v[220:223], v[12:15]
	v_mfma_f32_16x16x32_bf16 v[4:7], v[162:165], v[220:223], v[4:7]
	v_mfma_f32_16x16x32_bf16 v[60:63], v[150:153], v[200:203], v[60:63]
	v_mfma_f32_16x16x32_bf16 v[52:55], v[166:169], v[200:203], v[52:55]
	v_mfma_f32_16x16x32_bf16 v[44:47], v[150:153], v[208:211], v[44:47]
	v_mfma_f32_16x16x32_bf16 v[36:39], v[166:169], v[208:211], v[36:39]
	v_mfma_f32_16x16x32_bf16 v[28:31], v[150:153], v[216:219], v[28:31]
	v_mfma_f32_16x16x32_bf16 v[20:23], v[166:169], v[216:219], v[20:23]
	v_mfma_f32_16x16x32_bf16 v[12:15], v[150:153], v[224:227], v[12:15]
	v_mfma_f32_16x16x32_bf16 v[4:7], v[166:169], v[224:227], v[4:7]
	v_mfma_f32_16x16x32_bf16 v[56:59], v[180:183], v[196:199], v[56:59]
	v_mfma_f32_16x16x32_bf16 v[48:51], v[188:191], v[196:199], v[48:51]
	v_mfma_f32_16x16x32_bf16 v[40:43], v[180:183], v[204:207], v[40:43]
	v_mfma_f32_16x16x32_bf16 v[32:35], v[188:191], v[204:207], v[32:35]
	v_mfma_f32_16x16x32_bf16 v[24:27], v[180:183], v[212:215], v[24:27]
	v_mfma_f32_16x16x32_bf16 v[16:19], v[188:191], v[212:215], v[16:19]
	v_mfma_f32_16x16x32_bf16 v[8:11], v[180:183], v[220:223], v[8:11]
	v_mfma_f32_16x16x32_bf16 v[0:3], v[188:191], v[220:223], v[0:3]
	v_mfma_f32_16x16x32_bf16 v[56:59], v[184:187], v[200:203], v[56:59]
	v_mfma_f32_16x16x32_bf16 v[48:51], v[192:195], v[200:203], v[48:51]
	v_mfma_f32_16x16x32_bf16 v[40:43], v[184:187], v[208:211], v[40:43]
	v_mfma_f32_16x16x32_bf16 v[32:35], v[192:195], v[208:211], v[32:35]
	v_mfma_f32_16x16x32_bf16 v[24:27], v[184:187], v[216:219], v[24:27]
	v_mfma_f32_16x16x32_bf16 v[16:19], v[192:195], v[216:219], v[16:19]
	v_mfma_f32_16x16x32_bf16 v[8:11], v[184:187], v[224:227], v[8:11]
	v_mfma_f32_16x16x32_bf16 v[0:3], v[192:195], v[224:227], v[0:3]
	s_barrier
	s_add_i32 s51, 0, 0x18000
	v_add_u32_e32 v161, s51, v155
	s_add_i32 s52, 0, 0x1c000
	ds_read_b128 v[146:149], v161
	ds_read_b128 v[150:153], v161 offset:1024
	ds_read_b128 v[162:165], v161 offset:2048
	ds_read_b128 v[166:169], v161 offset:3072
	v_add_u32_e32 v161, s52, v155
	ds_read_b128 v[180:183], v161
	ds_read_b128 v[184:187], v161 offset:1024
	ds_read_b128 v[188:191], v161 offset:2048
	ds_read_b128 v[192:195], v161 offset:3072
	s_add_u32 s24, s24, 0x80000
	s_addc_u32 s25, s25, 0
	s_mov_b32 m0, s33
	v_lshl_add_u64 v[234:235], s[24:25], 0, v[136:137]
	ds_read_b128 v[196:199], v160 offset:32768
	ds_read_b128 v[200:203], v160 offset:33792
	ds_read_b128 v[204:207], v160 offset:34816
	ds_read_b128 v[208:211], v160 offset:35840
	ds_read_b128 v[212:215], v160 offset:36864
	ds_read_b128 v[216:219], v160 offset:37888
	ds_read_b128 v[220:223], v160 offset:38912
	ds_read_b128 v[224:227], v160 offset:39936
	global_load_lds_dwordx4 v[234:235], off
	v_lshl_add_u64 v[234:235], s[24:25], 0, v[132:133]
	s_mov_b32 m0, s34
	s_nop 0
	global_load_lds_dwordx4 v[234:235], off
	s_waitcnt vmcnt(8)
	s_waitcnt lgkmcnt(0)
	s_barrier
	s_waitcnt lgkmcnt(0)
	v_mfma_f32_16x16x32_bf16 v[124:127], v[146:149], v[196:199], v[124:127]
	v_mfma_f32_16x16x32_bf16 v[116:119], v[162:165], v[196:199], v[116:119]
	v_mfma_f32_16x16x32_bf16 v[108:111], v[146:149], v[204:207], v[108:111]
	v_mfma_f32_16x16x32_bf16 v[100:103], v[162:165], v[204:207], v[100:103]
	v_mfma_f32_16x16x32_bf16 v[92:95], v[146:149], v[212:215], v[92:95]
	v_mfma_f32_16x16x32_bf16 v[84:87], v[162:165], v[212:215], v[84:87]
	v_mfma_f32_16x16x32_bf16 v[76:79], v[146:149], v[220:223], v[76:79]
	v_mfma_f32_16x16x32_bf16 v[68:71], v[162:165], v[220:223], v[68:71]
	v_mfma_f32_16x16x32_bf16 v[124:127], v[150:153], v[200:203], v[124:127]
	v_mfma_f32_16x16x32_bf16 v[116:119], v[166:169], v[200:203], v[116:119]
	v_mfma_f32_16x16x32_bf16 v[108:111], v[150:153], v[208:211], v[108:111]
	v_mfma_f32_16x16x32_bf16 v[100:103], v[166:169], v[208:211], v[100:103]
	v_mfma_f32_16x16x32_bf16 v[92:95], v[150:153], v[216:219], v[92:95]
	v_mfma_f32_16x16x32_bf16 v[84:87], v[166:169], v[216:219], v[84:87]
	v_mfma_f32_16x16x32_bf16 v[76:79], v[150:153], v[224:227], v[76:79]
	v_mfma_f32_16x16x32_bf16 v[68:71], v[166:169], v[224:227], v[68:71]
	v_mfma_f32_16x16x32_bf16 v[120:123], v[180:183], v[196:199], v[120:123]
	v_mfma_f32_16x16x32_bf16 v[112:115], v[188:191], v[196:199], v[112:115]
	v_mfma_f32_16x16x32_bf16 v[104:107], v[180:183], v[204:207], v[104:107]
	v_mfma_f32_16x16x32_bf16 v[96:99], v[188:191], v[204:207], v[96:99]
	v_mfma_f32_16x16x32_bf16 v[88:91], v[180:183], v[212:215], v[88:91]
	v_mfma_f32_16x16x32_bf16 v[80:83], v[188:191], v[212:215], v[80:83]
	v_mfma_f32_16x16x32_bf16 v[72:75], v[180:183], v[220:223], v[72:75]
	v_mfma_f32_16x16x32_bf16 v[64:67], v[188:191], v[220:223], v[64:67]
	v_mfma_f32_16x16x32_bf16 v[120:123], v[184:187], v[200:203], v[120:123]
	v_mfma_f32_16x16x32_bf16 v[112:115], v[192:195], v[200:203], v[112:115]
	v_mfma_f32_16x16x32_bf16 v[104:107], v[184:187], v[208:211], v[104:107]
	v_mfma_f32_16x16x32_bf16 v[96:99], v[192:195], v[208:211], v[96:99]
	v_mfma_f32_16x16x32_bf16 v[88:91], v[184:187], v[216:219], v[88:91]
	v_mfma_f32_16x16x32_bf16 v[80:83], v[192:195], v[216:219], v[80:83]
	v_mfma_f32_16x16x32_bf16 v[72:75], v[184:187], v[224:227], v[72:75]
	v_mfma_f32_16x16x32_bf16 v[64:67], v[192:195], v[224:227], v[64:67]
	s_barrier
; #define PG8_STAGE(bufoff, gbase, voff) do { _Pragma("unroll") for (int _i = 0; _i < 2; ++_i) \
;         __builtin_amdgcn_global_load_lds((const unsigned*)((const char*)(gbase) + (voff)[_i]), (PG8_LAS unsigned*)(lds + (bufoff) + ldsw + _i * 8192), 16, 0, 0); } while (0)
; #define PG8_LDA(dst, b, h) do { _Pragma("unroll") for (int m = 0; m < 4; ++m) _Pragma("unroll") for (int k = 0; k < 2; ++k) dst[m][k] = *(const PG8_LAS bf16x8*)(lds + PG8_SA(b, h) + aoff + m * 2048 + k * 1024); } while (0)
; #define PG8_MMA(ai, bj, At, Bt) do { __builtin_amdgcn_s_setprio(1); _Pragma("unroll") for (int m = 0; m < 4; ++m) _Pragma("unroll") for (int n = 0; n < 2; ++n) _Pragma("unroll") for (int k = 0; k < 2; ++k) \
;         acc[ai][bj][m][n] = __builtin_amdgcn_mfma_f32_16x16x32_bf16(Bt[n][k], At[m][k], acc[ai][bj][m][n], 0, 0, 0); __builtin_amdgcn_s_setprio(0); } while (0)
; #define PG8_WAIT_V(n) asm volatile("s_waitcnt vmcnt(" #n ")" ::: "memory")
; #define PG8_WAIT_L(n) asm volatile("s_waitcnt lgkmcnt(" #n ")" ::: "memory")
; #define PG8_BAR __builtin_amdgcn_s_barrier()
; #define PG8_SCHED __builtin_amdgcn_sched_barrier(0)
; template <class Epi, class Sched, bool ALIGN_EPI = false, bool SP2 = false>
; __device__ __forceinline__ void gemm_phase(PG8_LAS unsigned char* lds, const Gemm g, const Sched& S, const Epi& E) {
;     ...
;             PG8_LDA(At, 1, 1); PG8_STAGE(PG8_SB(1, 0), b3, voffB); PG8_STAGE(PG8_SB(1, 1), b3 + hstep, voffB); PG8_STAGE(PG8_SA(1, 0), a3, voffA);
;             PG8_WAIT_V(8); PG8_WAIT_L(0); PG8_BAR; PG8_MMA(1, 0, At, B0); PG8_MMA(1, 1, At, B1); PG8_BAR; PG8_SCHED;
;     ...
;         if constexpr (ALIGN_EPI) { if (wr == 0) PG8_BAR; }
	s_add_i32 s24, s51, s26
	v_lshl_add_u64 v[170:171], v[170:171], 0, s[2:3]
	s_mov_b32 m0, s24
	ds_read_b128 v[196:199], v160 offset:49152
	ds_read_b128 v[200:203], v160 offset:50176
	ds_read_b128 v[204:207], v160 offset:51200
	ds_read_b128 v[208:211], v160 offset:52224
	ds_read_b128 v[212:215], v160 offset:53248
	ds_read_b128 v[216:219], v160 offset:54272
	ds_read_b128 v[220:223], v160 offset:55296
	ds_read_b128 v[224:227], v160 offset:56320
	global_load_lds_dwordx4 v[170:171], off
	s_add_i32 m0, s24, 0x2000
	s_add_u32 s22, s22, 0x80080
	v_lshl_add_u64 v[170:171], v[228:229], 0, s[2:3]
	s_addc_u32 s23, s23, 0
	s_add_i32 s24, s52, s26
	global_load_lds_dwordx4 v[170:171], off
	v_lshl_add_u64 v[170:171], s[22:23], 0, v[134:135]
	s_mov_b32 m0, s24
	s_nop 0
	global_load_lds_dwordx4 v[170:171], off
	v_lshl_add_u64 v[170:171], s[22:23], 0, v[130:131]
	s_add_i32 m0, s24, 0x2000
	s_nop 0
	global_load_lds_dwordx4 v[170:171], off
	v_lshl_add_u64 v[170:171], v[230:231], 0, s[2:3]
	s_mov_b32 m0, s35
	s_nop 0
	global_load_lds_dwordx4 v[170:171], off
	v_lshl_add_u64 v[170:171], v[232:233], 0, s[2:3]
	s_mov_b32 m0, s36
	s_nop 0
	global_load_lds_dwordx4 v[170:171], off
	s_waitcnt vmcnt(8)
	s_waitcnt lgkmcnt(0)
	s_barrier
	s_waitcnt lgkmcnt(0)
	v_mfma_f32_16x16x32_bf16 v[60:63], v[146:149], v[196:199], v[60:63]
	v_mfma_f32_16x16x32_bf16 v[52:55], v[162:165], v[196:199], v[52:55]
	v_mfma_f32_16x16x32_bf16 v[44:47], v[146:149], v[204:207], v[44:47]
	v_mfma_f32_16x16x32_bf16 v[36:39], v[162:165], v[204:207], v[36:39]
	v_mfma_f32_16x16x32_bf16 v[28:31], v[146:149], v[212:215], v[28:31]
	v_mfma_f32_16x16x32_bf16 v[20:23], v[162:165], v[212:215], v[20:23]
	v_mfma_f32_16x16x32_bf16 v[12:15], v[146:149], v[220:223], v[12:15]
	v_mfma_f32_16x16x32_bf16 v[4:7], v[162:165], v[220:223], v[4:7]
	v_mfma_f32_16x16x32_bf16 v[60:63], v[150:153], v[200:203], v[60:63]
	v_mfma_f32_16x16x32_bf16 v[52:55], v[166:169], v[200:203], v[52:55]
	v_mfma_f32_16x16x32_bf16 v[44:47], v[150:153], v[208:211], v[44:47]
	v_mfma_f32_16x16x32_bf16 v[36:39], v[166:169], v[208:211], v[36:39]
	v_mfma_f32_16x16x32_bf16 v[28:31], v[150:153], v[216:219], v[28:31]
	v_mfma_f32_16x16x32_bf16 v[20:23], v[166:169], v[216:219], v[20:23]
	v_mfma_f32_16x16x32_bf16 v[12:15], v[150:153], v[224:227], v[12:15]
	v_mfma_f32_16x16x32_bf16 v[4:7], v[166:169], v[224:227], v[4:7]
	v_mfma_f32_16x16x32_bf16 v[56:59], v[180:183], v[196:199], v[56:59]
	v_mfma_f32_16x16x32_bf16 v[48:51], v[188:191], v[196:199], v[48:51]
	v_mfma_f32_16x16x32_bf16 v[40:43], v[180:183], v[204:207], v[40:43]
	v_mfma_f32_16x16x32_bf16 v[32:35], v[188:191], v[204:207], v[32:35]
	v_mfma_f32_16x16x32_bf16 v[24:27], v[180:183], v[212:215], v[24:27]
	v_mfma_f32_16x16x32_bf16 v[16:19], v[188:191], v[212:215], v[16:19]
	v_mfma_f32_16x16x32_bf16 v[8:11], v[180:183], v[220:223], v[8:11]
	v_mfma_f32_16x16x32_bf16 v[0:3], v[188:191], v[220:223], v[0:3]
	v_mfma_f32_16x16x32_bf16 v[56:59], v[184:187], v[200:203], v[56:59]
	v_mfma_f32_16x16x32_bf16 v[48:51], v[192:195], v[200:203], v[48:51]
	v_mfma_f32_16x16x32_bf16 v[40:43], v[184:187], v[208:211], v[40:43]
	v_mfma_f32_16x16x32_bf16 v[32:35], v[192:195], v[208:211], v[32:35]
	v_mfma_f32_16x16x32_bf16 v[24:27], v[184:187], v[216:219], v[24:27]
	v_mfma_f32_16x16x32_bf16 v[16:19], v[192:195], v[216:219], v[16:19]
	v_mfma_f32_16x16x32_bf16 v[8:11], v[184:187], v[224:227], v[8:11]
	v_mfma_f32_16x16x32_bf16 v[0:3], v[192:195], v[224:227], v[0:3]
	s_barrier
	s_add_i32 s50, s50, 2
	s_add_u32 s20, s20, 0x100
	s_addc_u32 s21, s21, 0
	s_add_u32 s48, s48, 0x100
	s_addc_u32 s49, s49, 0
	s_cmp_gt_u32 s50, 29
	s_cbranch_scc0 .LBB0_837
	s_and_b64 vcc, exec, s[4:5]
	s_cbranch_vccz .LBB0_840
	s_barrier

; #define PG8_STAGE(bufoff, gbase, voff) do { _Pragma("unroll") for (int _i = 0; _i < 2; ++_i) \
;         __builtin_amdgcn_global_load_lds((const unsigned*)((const char*)(gbase) + (voff)[_i]), (PG8_LAS unsigned*)(lds + (bufoff) + ldsw + _i * 8192), 16, 0, 0); } while (0)
; #define PG8_LDA(dst, b, h) do { _Pragma("unroll") for (int m = 0; m < 4; ++m) _Pragma("unroll") for (int k = 0; k < 2; ++k) dst[m][k] = *(const PG8_LAS bf16x8*)(lds + PG8_SA(b, h) + aoff + m * 2048 + k * 1024); } while (0)
; #define PG8_LDB(dst, b, h) do { _Pragma("unroll") for (int n = 0; n < 2; ++n) _Pragma("unroll") for (int k = 0; k < 2; ++k) dst[n][k] = *(const PG8_LAS bf16x8*)(lds + PG8_SB(b, h) + boff + n * 2048 + k * 1024); } while (0)
; #define PG8_MMA(ai, bj, At, Bt) do { __builtin_amdgcn_s_setprio(1); _Pragma("unroll") for (int m = 0; m < 4; ++m) _Pragma("unroll") for (int n = 0; n < 2; ++n) _Pragma("unroll") for (int k = 0; k < 2; ++k) \
;         acc[ai][bj][m][n] = __builtin_amdgcn_mfma_f32_16x16x32_bf16(Bt[n][k], At[m][k], acc[ai][bj][m][n], 0, 0, 0); __builtin_amdgcn_s_setprio(0); } while (0)
; #define PG8_WAIT_V(n) asm volatile("s_waitcnt vmcnt(" #n ")" ::: "memory")
; #define PG8_BAR __builtin_amdgcn_s_barrier()
; template <class Epi, class Sched, bool ALIGN_EPI = false, bool SP2 = false>
; __device__ __forceinline__ void gemm_phase(PG8_LAS unsigned char* lds, const Gemm g, const Sched& S, const Epi& E) {
;     ...
;         for (int t = 0; t < nt; t += 2) {
;             const bool last = (t == nt - 2);
;             const char* a1 = cA + (size_t)(t + 1) * kstep;
;             const char* a2 = last ? nA : cA + (size_t)(t + 2) * kstep; const char* b2 = last ? nB : cB + (size_t)(t + 2) * kstep;
;             const char* a3 = a2 + kstep; const char* b3 = b2 + kstep;
;             if (last && has_next) S.a_ready(nxt);
;             if constexpr (SP2) {
;             PG8_LDB(B0, 0, 0); PG8_LDB(B1, 0, 1); PG8_SCHED; PG8_LDA(At, 0, 0); PG8_STAGE(PG8_SA(1, 1), a1 + hstep, voffA);
;             PG8_WAIT_V(8); PG8_WAIT_L(0); PG8_BAR; PG8_MMA(0, 0, At, B0); PG8_MMA(0, 1, At, B1); PG8_BAR; PG8_SCHED;
;             PG8_LDA(At, 0, 1); PG8_STAGE(PG8_SB(0, 0), b2, voffB); PG8_STAGE(PG8_SB(0, 1), b2 + hstep, voffB); PG8_STAGE(PG8_SA(0, 0), a2, voffA);
;             PG8_WAIT_V(8); PG8_WAIT_L(0); PG8_BAR; PG8_MMA(1, 0, At, B0); PG8_MMA(1, 1, At, B1); PG8_BAR; PG8_SCHED;
.LBB0_1080:
	ds_read_b128 v[142:145], v151
	ds_read_b128 v[154:157], v151 offset:1024
	ds_read_b128 v[158:161], v151 offset:2048
	ds_read_b128 v[162:165], v151 offset:3072
	ds_read_b128 v[166:169], v152
	ds_read_b128 v[180:183], v152 offset:1024
	ds_read_b128 v[184:187], v152 offset:2048
	ds_read_b128 v[188:191], v152 offset:3072
	s_add_u32 s20, s18, 0x100
	s_addc_u32 s21, s19, 0
	s_cmpk_eq_i32 s49, 0x54
	s_cselect_b32 s25, s13, s21
	s_cselect_b32 s24, s12, s20
	s_cselect_b32 s23, s17, s48
	s_cselect_b32 s22, s16, s47
	v_lshl_add_u64 v[146:147], s[18:19], 0, v[134:135]
	s_add_i32 m0, s29, 0xc000
	ds_read_b128 v[192:195], v153
	ds_read_b128 v[196:199], v153 offset:1024
	ds_read_b128 v[200:203], v153 offset:2048
	ds_read_b128 v[204:207], v153 offset:3072
	ds_read_b128 v[208:211], v153 offset:4096
	ds_read_b128 v[212:215], v153 offset:5120
	ds_read_b128 v[216:219], v153 offset:6144
	ds_read_b128 v[220:223], v153 offset:7168
	global_load_lds_dwordx4 v[146:147], off
	v_lshl_add_u64 v[146:147], s[18:19], 0, v[136:137]
	s_add_i32 m0, s29, 0xe000
	s_nop 0
	global_load_lds_dwordx4 v[146:147], off
	s_waitcnt vmcnt(8)
	s_waitcnt lgkmcnt(0)
	s_barrier
	s_waitcnt lgkmcnt(0)
	v_mfma_f32_16x16x32_bf16 v[124:127], v[142:145], v[192:195], v[124:127]
	v_mfma_f32_16x16x32_bf16 v[120:123], v[158:161], v[192:195], v[120:123]
	v_mfma_f32_16x16x32_bf16 v[108:111], v[142:145], v[200:203], v[108:111]
	v_mfma_f32_16x16x32_bf16 v[104:107], v[158:161], v[200:203], v[104:107]
	v_mfma_f32_16x16x32_bf16 v[92:95], v[142:145], v[208:211], v[92:95]
	v_mfma_f32_16x16x32_bf16 v[88:91], v[158:161], v[208:211], v[88:91]
	v_mfma_f32_16x16x32_bf16 v[76:79], v[142:145], v[216:219], v[76:79]
	v_mfma_f32_16x16x32_bf16 v[72:75], v[158:161], v[216:219], v[72:75]
	v_mfma_f32_16x16x32_bf16 v[124:127], v[154:157], v[196:199], v[124:127]
	v_mfma_f32_16x16x32_bf16 v[120:123], v[162:165], v[196:199], v[120:123]
	v_mfma_f32_16x16x32_bf16 v[108:111], v[154:157], v[204:207], v[108:111]
	v_mfma_f32_16x16x32_bf16 v[104:107], v[162:165], v[204:207], v[104:107]
	v_mfma_f32_16x16x32_bf16 v[92:95], v[154:157], v[212:215], v[92:95]
	v_mfma_f32_16x16x32_bf16 v[88:91], v[162:165], v[212:215], v[88:91]
	v_mfma_f32_16x16x32_bf16 v[76:79], v[154:157], v[220:223], v[76:79]
	v_mfma_f32_16x16x32_bf16 v[72:75], v[162:165], v[220:223], v[72:75]
	v_mfma_f32_16x16x32_bf16 v[116:119], v[166:169], v[192:195], v[116:119]
	v_mfma_f32_16x16x32_bf16 v[112:115], v[184:187], v[192:195], v[112:115]
	v_mfma_f32_16x16x32_bf16 v[100:103], v[166:169], v[200:203], v[100:103]
	v_mfma_f32_16x16x32_bf16 v[96:99], v[184:187], v[200:203], v[96:99]
	v_mfma_f32_16x16x32_bf16 v[84:87], v[166:169], v[208:211], v[84:87]
	v_mfma_f32_16x16x32_bf16 v[80:83], v[184:187], v[208:211], v[80:83]
	v_mfma_f32_16x16x32_bf16 v[68:71], v[166:169], v[216:219], v[68:71]
	v_mfma_f32_16x16x32_bf16 v[64:67], v[184:187], v[216:219], v[64:67]
	v_mfma_f32_16x16x32_bf16 v[116:119], v[180:183], v[196:199], v[116:119]
	v_mfma_f32_16x16x32_bf16 v[112:115], v[188:191], v[196:199], v[112:115]
	v_mfma_f32_16x16x32_bf16 v[100:103], v[180:183], v[204:207], v[100:103]
	v_mfma_f32_16x16x32_bf16 v[96:99], v[188:191], v[204:207], v[96:99]
	v_mfma_f32_16x16x32_bf16 v[84:87], v[180:183], v[212:215], v[84:87]
	v_mfma_f32_16x16x32_bf16 v[80:83], v[188:191], v[212:215], v[80:83]
	v_mfma_f32_16x16x32_bf16 v[68:71], v[180:183], v[220:223], v[68:71]
	v_mfma_f32_16x16x32_bf16 v[64:67], v[188:191], v[220:223], v[64:67]
	s_barrier
	s_add_i32 s18, s37, s28
	v_lshl_add_u64 v[146:147], s[22:23], 0, v[130:131]
	s_mov_b32 m0, s18
	ds_read_b128 v[192:195], v153 offset:16384
	ds_read_b128 v[196:199], v153 offset:17408
	ds_read_b128 v[200:203], v153 offset:18432
	ds_read_b128 v[204:207], v153 offset:19456
	ds_read_b128 v[208:211], v153 offset:20480
	ds_read_b128 v[212:215], v153 offset:21504
	ds_read_b128 v[216:219], v153 offset:22528
	ds_read_b128 v[220:223], v153 offset:23552
	global_load_lds_dwordx4 v[146:147], off
	s_add_i32 m0, s18, 0x2000
	s_add_u32 s18, s22, 0x160000
	v_lshl_add_u64 v[170:171], s[22:23], 0, v[132:133]
	s_addc_u32 s19, s23, 0
	s_add_i32 s50, s40, s28
	global_load_lds_dwordx4 v[170:171], off
	v_lshl_add_u64 v[224:225], s[18:19], 0, v[130:131]
	s_mov_b32 m0, s50
	v_lshl_add_u64 v[226:227], s[24:25], 0, v[132:133]
	global_load_lds_dwordx4 v[224:225], off
	v_lshl_add_u64 v[224:225], s[18:19], 0, v[132:133]
	s_add_i32 m0, s50, 0x2000
	s_nop 0
	global_load_lds_dwordx4 v[224:225], off
	v_lshl_add_u64 v[224:225], s[24:25], 0, v[130:131]
	s_mov_b32 m0, s29
	s_nop 0
	global_load_lds_dwordx4 v[224:225], off
	s_mov_b32 m0, s30
	s_nop 0
	global_load_lds_dwordx4 v[226:227], off
	s_waitcnt vmcnt(8)
	s_waitcnt lgkmcnt(0)
	s_barrier
; #define PG8_STAGE(bufoff, gbase, voff) do { _Pragma("unroll") for (int _i = 0; _i < 2; ++_i) \
;         __builtin_amdgcn_global_load_lds((const unsigned*)((const char*)(gbase) + (voff)[_i]), (PG8_LAS unsigned*)(lds + (bufoff) + ldsw + _i * 8192), 16, 0, 0); } while (0)
; #define PG8_LDA(dst, b, h) do { _Pragma("unroll") for (int m = 0; m < 4; ++m) _Pragma("unroll") for (int k = 0; k < 2; ++k) dst[m][k] = *(const PG8_LAS bf16x8*)(lds + PG8_SA(b, h) + aoff + m * 2048 + k * 1024); } while (0)
; #define PG8_LDB(dst, b, h) do { _Pragma("unroll") for (int n = 0; n < 2; ++n) _Pragma("unroll") for (int k = 0; k < 2; ++k) dst[n][k] = *(const PG8_LAS bf16x8*)(lds + PG8_SB(b, h) + boff + n * 2048 + k * 1024); } while (0)
; #define PG8_MMA(ai, bj, At, Bt) do { __builtin_amdgcn_s_setprio(1); _Pragma("unroll") for (int m = 0; m < 4; ++m) _Pragma("unroll") for (int n = 0; n < 2; ++n) _Pragma("unroll") for (int k = 0; k < 2; ++k) \
;         acc[ai][bj][m][n] = __builtin_amdgcn_mfma_f32_16x16x32_bf16(Bt[n][k], At[m][k], acc[ai][bj][m][n], 0, 0, 0); __builtin_amdgcn_s_setprio(0); } while (0)
; #define PG8_WAIT_V(n) asm volatile("s_waitcnt vmcnt(" #n ")" ::: "memory")
; #define PG8_WAIT_L(n) asm volatile("s_waitcnt lgkmcnt(" #n ")" ::: "memory")
; #define PG8_BAR __builtin_amdgcn_s_barrier()
; #define PG8_SCHED __builtin_amdgcn_sched_barrier(0)
; template <class Epi, class Sched, bool ALIGN_EPI = false, bool SP2 = false>
; __device__ __forceinline__ void gemm_phase(PG8_LAS unsigned char* lds, const Gemm g, const Sched& S, const Epi& E) {
;     ...
;             PG8_WAIT_V(8); PG8_WAIT_L(0); PG8_BAR; PG8_MMA(1, 0, At, B0); PG8_MMA(1, 1, At, B1); PG8_BAR; PG8_SCHED;
;             PG8_LDB(B0, 1, 0); PG8_LDB(B1, 1, 1); PG8_SCHED; PG8_LDA(At, 1, 0); PG8_STAGE(PG8_SA(0, 1), a2 + hstep, voffA);
;             PG8_WAIT_V(8); PG8_WAIT_L(0); PG8_BAR; PG8_MMA(0, 0, At, B0); PG8_MMA(0, 1, At, B1); PG8_BAR; PG8_SCHED;
	s_waitcnt lgkmcnt(0)
	v_mfma_f32_16x16x32_bf16 v[60:63], v[142:145], v[192:195], v[60:63]
	v_mfma_f32_16x16x32_bf16 v[56:59], v[158:161], v[192:195], v[56:59]
	v_mfma_f32_16x16x32_bf16 v[44:47], v[142:145], v[200:203], v[44:47]
	v_mfma_f32_16x16x32_bf16 v[40:43], v[158:161], v[200:203], v[40:43]
	v_mfma_f32_16x16x32_bf16 v[28:31], v[142:145], v[208:211], v[28:31]
	v_mfma_f32_16x16x32_bf16 v[24:27], v[158:161], v[208:211], v[24:27]
	v_mfma_f32_16x16x32_bf16 v[12:15], v[142:145], v[216:219], v[12:15]
	v_mfma_f32_16x16x32_bf16 v[8:11], v[158:161], v[216:219], v[8:11]
	v_mfma_f32_16x16x32_bf16 v[60:63], v[154:157], v[196:199], v[60:63]
	v_mfma_f32_16x16x32_bf16 v[56:59], v[162:165], v[196:199], v[56:59]
	v_mfma_f32_16x16x32_bf16 v[44:47], v[154:157], v[204:207], v[44:47]
	v_mfma_f32_16x16x32_bf16 v[40:43], v[162:165], v[204:207], v[40:43]
	v_mfma_f32_16x16x32_bf16 v[28:31], v[154:157], v[212:215], v[28:31]
	v_mfma_f32_16x16x32_bf16 v[24:27], v[162:165], v[212:215], v[24:27]
	v_mfma_f32_16x16x32_bf16 v[12:15], v[154:157], v[220:223], v[12:15]
	v_mfma_f32_16x16x32_bf16 v[8:11], v[162:165], v[220:223], v[8:11]
	v_mfma_f32_16x16x32_bf16 v[52:55], v[166:169], v[192:195], v[52:55]
	v_mfma_f32_16x16x32_bf16 v[48:51], v[184:187], v[192:195], v[48:51]
	v_mfma_f32_16x16x32_bf16 v[36:39], v[166:169], v[200:203], v[36:39]
	v_mfma_f32_16x16x32_bf16 v[32:35], v[184:187], v[200:203], v[32:35]
	v_mfma_f32_16x16x32_bf16 v[20:23], v[166:169], v[208:211], v[20:23]
	v_mfma_f32_16x16x32_bf16 v[16:19], v[184:187], v[208:211], v[16:19]
	v_mfma_f32_16x16x32_bf16 v[4:7], v[166:169], v[216:219], v[4:7]
	v_mfma_f32_16x16x32_bf16 v[0:3], v[184:187], v[216:219], v[0:3]
	v_mfma_f32_16x16x32_bf16 v[52:55], v[180:183], v[196:199], v[52:55]
	v_mfma_f32_16x16x32_bf16 v[48:51], v[188:191], v[196:199], v[48:51]
	v_mfma_f32_16x16x32_bf16 v[36:39], v[180:183], v[204:207], v[36:39]
	v_mfma_f32_16x16x32_bf16 v[32:35], v[188:191], v[204:207], v[32:35]
	v_mfma_f32_16x16x32_bf16 v[20:23], v[180:183], v[212:215], v[20:23]
	v_mfma_f32_16x16x32_bf16 v[16:19], v[188:191], v[212:215], v[16:19]
	v_mfma_f32_16x16x32_bf16 v[4:7], v[180:183], v[220:223], v[4:7]
	v_mfma_f32_16x16x32_bf16 v[0:3], v[188:191], v[220:223], v[0:3]
	s_barrier
	s_add_i32 s50, 0, 0x18000
	s_add_i32 s51, 0, 0x1c000
	v_add_u32_e32 v162, s50, v149
	v_add_u32_e32 v179, s51, v149
	ds_read_b128 v[142:145], v162
	ds_read_b128 v[154:157], v162 offset:1024
	ds_read_b128 v[158:161], v162 offset:2048
	ds_read_b128 v[162:165], v162 offset:3072
	ds_read_b128 v[166:169], v179
	ds_read_b128 v[180:183], v179 offset:1024
	ds_read_b128 v[184:187], v179 offset:2048
	ds_read_b128 v[188:191], v179 offset:3072
	s_add_u32 s18, s24, 0x160000
	s_addc_u32 s19, s25, 0
	s_mov_b32 m0, s31
	v_lshl_add_u64 v[228:229], s[18:19], 0, v[130:131]
	ds_read_b128 v[192:195], v153 offset:32768
	ds_read_b128 v[196:199], v153 offset:33792
	ds_read_b128 v[200:203], v153 offset:34816
	ds_read_b128 v[204:207], v153 offset:35840
	ds_read_b128 v[208:211], v153 offset:36864
	ds_read_b128 v[212:215], v153 offset:37888
	ds_read_b128 v[216:219], v153 offset:38912
	ds_read_b128 v[220:223], v153 offset:39936
	global_load_lds_dwordx4 v[228:229], off
	v_lshl_add_u64 v[228:229], s[18:19], 0, v[132:133]
	s_mov_b32 m0, s33
	s_nop 0
	global_load_lds_dwordx4 v[228:229], off
	s_waitcnt vmcnt(8)
	s_waitcnt lgkmcnt(0)
	s_barrier
	s_waitcnt lgkmcnt(0)
	v_mfma_f32_16x16x32_bf16 v[124:127], v[142:145], v[192:195], v[124:127]
	v_mfma_f32_16x16x32_bf16 v[120:123], v[158:161], v[192:195], v[120:123]
	v_mfma_f32_16x16x32_bf16 v[108:111], v[142:145], v[200:203], v[108:111]
	v_mfma_f32_16x16x32_bf16 v[104:107], v[158:161], v[200:203], v[104:107]
	v_mfma_f32_16x16x32_bf16 v[92:95], v[142:145], v[208:211], v[92:95]
	v_mfma_f32_16x16x32_bf16 v[88:91], v[158:161], v[208:211], v[88:91]
	v_mfma_f32_16x16x32_bf16 v[76:79], v[142:145], v[216:219], v[76:79]
	v_mfma_f32_16x16x32_bf16 v[72:75], v[158:161], v[216:219], v[72:75]
	v_mfma_f32_16x16x32_bf16 v[124:127], v[154:157], v[196:199], v[124:127]
	v_mfma_f32_16x16x32_bf16 v[120:123], v[162:165], v[196:199], v[120:123]
	v_mfma_f32_16x16x32_bf16 v[108:111], v[154:157], v[204:207], v[108:111]
	v_mfma_f32_16x16x32_bf16 v[104:107], v[162:165], v[204:207], v[104:107]
	v_mfma_f32_16x16x32_bf16 v[92:95], v[154:157], v[212:215], v[92:95]
	v_mfma_f32_16x16x32_bf16 v[88:91], v[162:165], v[212:215], v[88:91]
	v_mfma_f32_16x16x32_bf16 v[76:79], v[154:157], v[220:223], v[76:79]
	v_mfma_f32_16x16x32_bf16 v[72:75], v[162:165], v[220:223], v[72:75]
	v_mfma_f32_16x16x32_bf16 v[116:119], v[166:169], v[192:195], v[116:119]
	v_mfma_f32_16x16x32_bf16 v[112:115], v[184:187], v[192:195], v[112:115]
	v_mfma_f32_16x16x32_bf16 v[100:103], v[166:169], v[200:203], v[100:103]
	v_mfma_f32_16x16x32_bf16 v[96:99], v[184:187], v[200:203], v[96:99]
	v_mfma_f32_16x16x32_bf16 v[84:87], v[166:169], v[208:211], v[84:87]
	v_mfma_f32_16x16x32_bf16 v[80:83], v[184:187], v[208:211], v[80:83]
	v_mfma_f32_16x16x32_bf16 v[68:71], v[166:169], v[216:219], v[68:71]
	v_mfma_f32_16x16x32_bf16 v[64:67], v[184:187], v[216:219], v[64:67]
	v_mfma_f32_16x16x32_bf16 v[116:119], v[180:183], v[196:199], v[116:119]
	v_mfma_f32_16x16x32_bf16 v[112:115], v[188:191], v[196:199], v[112:115]
	v_mfma_f32_16x16x32_bf16 v[100:103], v[180:183], v[204:207], v[100:103]
	v_mfma_f32_16x16x32_bf16 v[96:99], v[188:191], v[204:207], v[96:99]
	v_mfma_f32_16x16x32_bf16 v[84:87], v[180:183], v[212:215], v[84:87]
	v_mfma_f32_16x16x32_bf16 v[80:83], v[188:191], v[212:215], v[80:83]
	v_mfma_f32_16x16x32_bf16 v[68:71], v[180:183], v[220:223], v[68:71]
	v_mfma_f32_16x16x32_bf16 v[64:67], v[188:191], v[220:223], v[64:67]
	s_barrier
; #define PG8_STAGE(bufoff, gbase, voff) do { _Pragma("unroll") for (int _i = 0; _i < 2; ++_i) \
;         __builtin_amdgcn_global_load_lds((const unsigned*)((const char*)(gbase) + (voff)[_i]), (PG8_LAS unsigned*)(lds + (bufoff) + ldsw + _i * 8192), 16, 0, 0); } while (0)
; #define PG8_LDA(dst, b, h) do { _Pragma("unroll") for (int m = 0; m < 4; ++m) _Pragma("unroll") for (int k = 0; k < 2; ++k) dst[m][k] = *(const PG8_LAS bf16x8*)(lds + PG8_SA(b, h) + aoff + m * 2048 + k * 1024); } while (0)
; #define PG8_MMA(ai, bj, At, Bt) do { __builtin_amdgcn_s_setprio(1); _Pragma("unroll") for (int m = 0; m < 4; ++m) _Pragma("unroll") for (int n = 0; n < 2; ++n) _Pragma("unroll") for (int k = 0; k < 2; ++k) \
;         acc[ai][bj][m][n] = __builtin_amdgcn_mfma_f32_16x16x32_bf16(Bt[n][k], At[m][k], acc[ai][bj][m][n], 0, 0, 0); __builtin_amdgcn_s_setprio(0); } while (0)
; #define PG8_WAIT_V(n) asm volatile("s_waitcnt vmcnt(" #n ")" ::: "memory")
; #define PG8_WAIT_L(n) asm volatile("s_waitcnt lgkmcnt(" #n ")" ::: "memory")
; #define PG8_BAR __builtin_amdgcn_s_barrier()
; #define PG8_SCHED __builtin_amdgcn_sched_barrier(0)
; template <class Epi, class Sched, bool ALIGN_EPI = false, bool SP2 = false>
; __device__ __forceinline__ void gemm_phase(PG8_LAS unsigned char* lds, const Gemm g, const Sched& S, const Epi& E) {
;     ...
;             PG8_LDA(At, 1, 1); PG8_STAGE(PG8_SB(1, 0), b3, voffB); PG8_STAGE(PG8_SB(1, 1), b3 + hstep, voffB); PG8_STAGE(PG8_SA(1, 0), a3, voffA);
;             PG8_WAIT_V(8); PG8_WAIT_L(0); PG8_BAR; PG8_MMA(1, 0, At, B0); PG8_MMA(1, 1, At, B1); PG8_BAR; PG8_SCHED;
;     ...
;         if constexpr (ALIGN_EPI) { if (wr == 0) PG8_BAR; }
	s_add_i32 s18, s50, s28
	v_lshl_add_u64 v[146:147], v[146:147], 0, s[4:5]
	s_mov_b32 m0, s18
	ds_read_b128 v[192:195], v153 offset:49152
	ds_read_b128 v[196:199], v153 offset:50176
	ds_read_b128 v[200:203], v153 offset:51200
	ds_read_b128 v[204:207], v153 offset:52224
	ds_read_b128 v[208:211], v153 offset:53248
	ds_read_b128 v[212:215], v153 offset:54272
	ds_read_b128 v[216:219], v153 offset:55296
	ds_read_b128 v[220:223], v153 offset:56320
	global_load_lds_dwordx4 v[146:147], off
	s_add_i32 m0, s18, 0x2000
	s_add_u32 s18, s22, 0x160080
	v_lshl_add_u64 v[146:147], v[170:171], 0, s[4:5]
	s_addc_u32 s19, s23, 0
	s_add_i32 s22, s51, s28
	global_load_lds_dwordx4 v[146:147], off
	v_lshl_add_u64 v[146:147], s[18:19], 0, v[130:131]
	s_mov_b32 m0, s22
	s_nop 0
	global_load_lds_dwordx4 v[146:147], off
	v_lshl_add_u64 v[146:147], s[18:19], 0, v[132:133]
	s_add_i32 m0, s22, 0x2000
	s_nop 0
	global_load_lds_dwordx4 v[146:147], off
	v_lshl_add_u64 v[146:147], v[224:225], 0, s[4:5]
	s_mov_b32 m0, s35
	s_nop 0
	global_load_lds_dwordx4 v[146:147], off
	v_lshl_add_u64 v[146:147], v[226:227], 0, s[4:5]
	s_mov_b32 m0, s36
	s_nop 0
	global_load_lds_dwordx4 v[146:147], off
	s_waitcnt vmcnt(8)
	s_waitcnt lgkmcnt(0)
	s_barrier
	s_waitcnt lgkmcnt(0)
	v_mfma_f32_16x16x32_bf16 v[60:63], v[142:145], v[192:195], v[60:63]
	v_mfma_f32_16x16x32_bf16 v[56:59], v[158:161], v[192:195], v[56:59]
	v_mfma_f32_16x16x32_bf16 v[44:47], v[142:145], v[200:203], v[44:47]
	v_mfma_f32_16x16x32_bf16 v[40:43], v[158:161], v[200:203], v[40:43]
	v_mfma_f32_16x16x32_bf16 v[28:31], v[142:145], v[208:211], v[28:31]
	v_mfma_f32_16x16x32_bf16 v[24:27], v[158:161], v[208:211], v[24:27]
	v_mfma_f32_16x16x32_bf16 v[12:15], v[142:145], v[216:219], v[12:15]
	v_mfma_f32_16x16x32_bf16 v[8:11], v[158:161], v[216:219], v[8:11]
	v_mfma_f32_16x16x32_bf16 v[60:63], v[154:157], v[196:199], v[60:63]
	v_mfma_f32_16x16x32_bf16 v[56:59], v[162:165], v[196:199], v[56:59]
	v_mfma_f32_16x16x32_bf16 v[44:47], v[154:157], v[204:207], v[44:47]
	v_mfma_f32_16x16x32_bf16 v[40:43], v[162:165], v[204:207], v[40:43]
	v_mfma_f32_16x16x32_bf16 v[28:31], v[154:157], v[212:215], v[28:31]
	v_mfma_f32_16x16x32_bf16 v[24:27], v[162:165], v[212:215], v[24:27]
	v_mfma_f32_16x16x32_bf16 v[12:15], v[154:157], v[220:223], v[12:15]
	v_mfma_f32_16x16x32_bf16 v[8:11], v[162:165], v[220:223], v[8:11]
	v_mfma_f32_16x16x32_bf16 v[52:55], v[166:169], v[192:195], v[52:55]
	v_mfma_f32_16x16x32_bf16 v[48:51], v[184:187], v[192:195], v[48:51]
	v_mfma_f32_16x16x32_bf16 v[36:39], v[166:169], v[200:203], v[36:39]
	v_mfma_f32_16x16x32_bf16 v[32:35], v[184:187], v[200:203], v[32:35]
	v_mfma_f32_16x16x32_bf16 v[20:23], v[166:169], v[208:211], v[20:23]
	v_mfma_f32_16x16x32_bf16 v[16:19], v[184:187], v[208:211], v[16:19]
	v_mfma_f32_16x16x32_bf16 v[4:7], v[166:169], v[216:219], v[4:7]
	v_mfma_f32_16x16x32_bf16 v[0:3], v[184:187], v[216:219], v[0:3]
	v_mfma_f32_16x16x32_bf16 v[52:55], v[180:183], v[196:199], v[52:55]
	v_mfma_f32_16x16x32_bf16 v[48:51], v[188:191], v[196:199], v[48:51]
	v_mfma_f32_16x16x32_bf16 v[36:39], v[180:183], v[204:207], v[36:39]
	v_mfma_f32_16x16x32_bf16 v[32:35], v[188:191], v[204:207], v[32:35]
	v_mfma_f32_16x16x32_bf16 v[20:23], v[180:183], v[212:215], v[20:23]
	v_mfma_f32_16x16x32_bf16 v[16:19], v[188:191], v[212:215], v[16:19]
	v_mfma_f32_16x16x32_bf16 v[4:7], v[180:183], v[220:223], v[4:7]
	v_mfma_f32_16x16x32_bf16 v[0:3], v[188:191], v[220:223], v[0:3]
	s_barrier
	s_add_i32 s49, s49, 2
	s_add_u32 s47, s47, 0x100
	s_addc_u32 s48, s48, 0
	s_cmpk_gt_u32 s49, 0x55
	s_mov_b64 s[18:19], s[20:21]
	s_cbranch_scc0 .LBB0_1080
	s_and_b64 vcc, exec, s[6:7]
	s_cbranch_vccz .LBB0_1083
	s_barrier

; #define PG8_STAGE(bufoff, gbase, voff) do { _Pragma("unroll") for (int _i = 0; _i < 2; ++_i) \
;         __builtin_amdgcn_global_load_lds((const unsigned*)((const char*)(gbase) + (voff)[_i]), (PG8_LAS unsigned*)(lds + (bufoff) + ldsw + _i * 8192), 16, 0, 0); } while (0)
; #define PG8_LDA(dst, b, h) do { _Pragma("unroll") for (int m = 0; m < 4; ++m) _Pragma("unroll") for (int k = 0; k < 2; ++k) dst[m][k] = *(const PG8_LAS bf16x8*)(lds + PG8_SA(b, h) + aoff + m * 2048 + k * 1024); } while (0)
; #define PG8_LDB(dst, b, h) do { _Pragma("unroll") for (int n = 0; n < 2; ++n) _Pragma("unroll") for (int k = 0; k < 2; ++k) dst[n][k] = *(const PG8_LAS bf16x8*)(lds + PG8_SB(b, h) + boff + n * 2048 + k * 1024); } while (0)
; #define PG8_MMA(ai, bj, At, Bt) do { __builtin_amdgcn_s_setprio(1); _Pragma("unroll") for (int m = 0; m < 4; ++m) _Pragma("unroll") for (int n = 0; n < 2; ++n) _Pragma("unroll") for (int k = 0; k < 2; ++k) \
;         acc[ai][bj][m][n] = __builtin_amdgcn_mfma_f32_16x16x32_bf16(Bt[n][k], At[m][k], acc[ai][bj][m][n], 0, 0, 0); __builtin_amdgcn_s_setprio(0); } while (0)
; #define PG8_WAIT_V(n) asm volatile("s_waitcnt vmcnt(" #n ")" ::: "memory")
; #define PG8_BAR __builtin_amdgcn_s_barrier()
; template <class Epi, class Sched, bool ALIGN_EPI = false, bool SP2 = false>
; __device__ __forceinline__ void gemm_phase(PG8_LAS unsigned char* lds, const Gemm g, const Sched& S, const Epi& E) {
;     ...
;         for (int t = 0; t < nt; t += 2) {
;             const bool last = (t == nt - 2);
;             const char* a1 = cA + (size_t)(t + 1) * kstep;
;             const char* a2 = last ? nA : cA + (size_t)(t + 2) * kstep; const char* b2 = last ? nB : cB + (size_t)(t + 2) * kstep;
;             const char* a3 = a2 + kstep; const char* b3 = b2 + kstep;
;             if (last && has_next) S.a_ready(nxt);
;             if constexpr (SP2) {
;             PG8_LDB(B0, 0, 0); PG8_LDB(B1, 0, 1); PG8_SCHED; PG8_LDA(At, 0, 0); PG8_STAGE(PG8_SA(1, 1), a1 + hstep, voffA);
;             PG8_WAIT_V(8); PG8_WAIT_L(0); PG8_BAR; PG8_MMA(0, 0, At, B0); PG8_MMA(0, 1, At, B1); PG8_BAR; PG8_SCHED;
;             PG8_LDA(At, 0, 1); PG8_STAGE(PG8_SB(0, 0), b2, voffB); PG8_STAGE(PG8_SB(0, 1), b2 + hstep, voffB); PG8_STAGE(PG8_SA(0, 0), a2, voffA);
;             PG8_WAIT_V(8); PG8_WAIT_L(0); PG8_BAR; PG8_MMA(1, 0, At, B0); PG8_MMA(1, 1, At, B1); PG8_BAR; PG8_SCHED;
.LBB0_1181:
	ds_read_b128 v[146:149], v154
	ds_read_b128 v[158:161], v154 offset:1024
	ds_read_b128 v[162:165], v154 offset:2048
	ds_read_b128 v[166:169], v154 offset:3072
	ds_read_b128 v[180:183], v155
	ds_read_b128 v[184:187], v155 offset:1024
	ds_read_b128 v[188:191], v155 offset:2048
	ds_read_b128 v[192:195], v155 offset:3072
	s_add_u32 s22, s20, 0xfff80080
	s_addc_u32 s23, s21, -1
	s_cmp_eq_u32 s48, 28
	s_cselect_b32 s25, s11, s23
	s_cselect_b32 s24, s44, s22
	s_cselect_b32 s23, s7, s47
	s_cselect_b32 s22, s45, s46
	v_lshl_add_u64 v[170:171], s[20:21], 0, v[138:139]
	s_add_i32 m0, s17, 0xc000
	ds_read_b128 v[196:199], v156
	ds_read_b128 v[200:203], v156 offset:1024
	ds_read_b128 v[204:207], v156 offset:2048
	ds_read_b128 v[208:211], v156 offset:3072
	ds_read_b128 v[212:215], v156 offset:4096
	ds_read_b128 v[216:219], v156 offset:5120
	ds_read_b128 v[220:223], v156 offset:6144
	ds_read_b128 v[224:227], v156 offset:7168
	global_load_lds_dwordx4 v[170:171], off
	v_lshl_add_u64 v[170:171], s[20:21], 0, v[140:141]
	s_add_i32 m0, s17, 0xe000
	s_nop 0
	global_load_lds_dwordx4 v[170:171], off
	s_waitcnt vmcnt(8)
	s_waitcnt lgkmcnt(0)
	s_barrier
	s_waitcnt lgkmcnt(0)
	v_mfma_f32_16x16x32_bf16 v[124:127], v[146:149], v[196:199], v[124:127]
	v_mfma_f32_16x16x32_bf16 v[120:123], v[162:165], v[196:199], v[120:123]
	v_mfma_f32_16x16x32_bf16 v[112:115], v[146:149], v[204:207], v[112:115]
	v_mfma_f32_16x16x32_bf16 v[104:107], v[162:165], v[204:207], v[104:107]
	v_mfma_f32_16x16x32_bf16 v[96:99], v[146:149], v[212:215], v[96:99]
	v_mfma_f32_16x16x32_bf16 v[88:91], v[162:165], v[212:215], v[88:91]
	v_mfma_f32_16x16x32_bf16 v[80:83], v[146:149], v[220:223], v[80:83]
	v_mfma_f32_16x16x32_bf16 v[72:75], v[162:165], v[220:223], v[72:75]
	v_mfma_f32_16x16x32_bf16 v[124:127], v[158:161], v[200:203], v[124:127]
	v_mfma_f32_16x16x32_bf16 v[120:123], v[166:169], v[200:203], v[120:123]
	v_mfma_f32_16x16x32_bf16 v[112:115], v[158:161], v[208:211], v[112:115]
	v_mfma_f32_16x16x32_bf16 v[104:107], v[166:169], v[208:211], v[104:107]
	v_mfma_f32_16x16x32_bf16 v[96:99], v[158:161], v[216:219], v[96:99]
	v_mfma_f32_16x16x32_bf16 v[88:91], v[166:169], v[216:219], v[88:91]
	v_mfma_f32_16x16x32_bf16 v[80:83], v[158:161], v[224:227], v[80:83]
	v_mfma_f32_16x16x32_bf16 v[72:75], v[166:169], v[224:227], v[72:75]
	v_mfma_f32_16x16x32_bf16 v[116:119], v[180:183], v[196:199], v[116:119]
	v_mfma_f32_16x16x32_bf16 v[108:111], v[188:191], v[196:199], v[108:111]
	v_mfma_f32_16x16x32_bf16 v[100:103], v[180:183], v[204:207], v[100:103]
	v_mfma_f32_16x16x32_bf16 v[92:95], v[188:191], v[204:207], v[92:95]
	v_mfma_f32_16x16x32_bf16 v[84:87], v[180:183], v[212:215], v[84:87]
	v_mfma_f32_16x16x32_bf16 v[76:79], v[188:191], v[212:215], v[76:79]
	v_mfma_f32_16x16x32_bf16 v[68:71], v[180:183], v[220:223], v[68:71]
	v_mfma_f32_16x16x32_bf16 v[64:67], v[188:191], v[220:223], v[64:67]
	v_mfma_f32_16x16x32_bf16 v[116:119], v[184:187], v[200:203], v[116:119]
	v_mfma_f32_16x16x32_bf16 v[108:111], v[192:195], v[200:203], v[108:111]
	v_mfma_f32_16x16x32_bf16 v[100:103], v[184:187], v[208:211], v[100:103]
	v_mfma_f32_16x16x32_bf16 v[92:95], v[192:195], v[208:211], v[92:95]
	v_mfma_f32_16x16x32_bf16 v[84:87], v[184:187], v[216:219], v[84:87]
	v_mfma_f32_16x16x32_bf16 v[76:79], v[192:195], v[216:219], v[76:79]
	v_mfma_f32_16x16x32_bf16 v[68:71], v[184:187], v[224:227], v[68:71]
	v_mfma_f32_16x16x32_bf16 v[64:67], v[192:195], v[224:227], v[64:67]
	s_barrier
	s_add_i32 s49, s35, s28
	v_lshl_add_u64 v[170:171], s[22:23], 0, v[132:133]
	s_mov_b32 m0, s49
	ds_read_b128 v[196:199], v156 offset:16384
	ds_read_b128 v[200:203], v156 offset:17408
	ds_read_b128 v[204:207], v156 offset:18432
	ds_read_b128 v[208:211], v156 offset:19456
	ds_read_b128 v[212:215], v156 offset:20480
	ds_read_b128 v[216:219], v156 offset:21504
	ds_read_b128 v[220:223], v156 offset:22528
	ds_read_b128 v[224:227], v156 offset:23552
	global_load_lds_dwordx4 v[170:171], off
	s_add_i32 m0, s49, 0x2000
	s_add_u32 s50, s22, 0x80000
	v_lshl_add_u64 v[228:229], s[22:23], 0, v[136:137]
	s_addc_u32 s51, s23, 0
	s_add_i32 s49, s36, s28
	global_load_lds_dwordx4 v[228:229], off
	v_lshl_add_u64 v[230:231], s[50:51], 0, v[132:133]
	s_mov_b32 m0, s49
	v_lshl_add_u64 v[232:233], s[24:25], 0, v[134:135]
	global_load_lds_dwordx4 v[230:231], off
	v_lshl_add_u64 v[230:231], s[50:51], 0, v[136:137]
	s_add_i32 m0, s49, 0x2000
	s_nop 0
	global_load_lds_dwordx4 v[230:231], off
	v_lshl_add_u64 v[230:231], s[24:25], 0, v[130:131]
	s_mov_b32 m0, s17
	s_nop 0
	global_load_lds_dwordx4 v[230:231], off
	s_mov_b32 m0, s29
	s_nop 0
	global_load_lds_dwordx4 v[232:233], off
	s_waitcnt vmcnt(8)
	s_waitcnt lgkmcnt(0)
	s_barrier
; #define PG8_STAGE(bufoff, gbase, voff) do { _Pragma("unroll") for (int _i = 0; _i < 2; ++_i) \
;         __builtin_amdgcn_global_load_lds((const unsigned*)((const char*)(gbase) + (voff)[_i]), (PG8_LAS unsigned*)(lds + (bufoff) + ldsw + _i * 8192), 16, 0, 0); } while (0)
; #define PG8_LDA(dst, b, h) do { _Pragma("unroll") for (int m = 0; m < 4; ++m) _Pragma("unroll") for (int k = 0; k < 2; ++k) dst[m][k] = *(const PG8_LAS bf16x8*)(lds + PG8_SA(b, h) + aoff + m * 2048 + k * 1024); } while (0)
; #define PG8_LDB(dst, b, h) do { _Pragma("unroll") for (int n = 0; n < 2; ++n) _Pragma("unroll") for (int k = 0; k < 2; ++k) dst[n][k] = *(const PG8_LAS bf16x8*)(lds + PG8_SB(b, h) + boff + n * 2048 + k * 1024); } while (0)
; #define PG8_MMA(ai, bj, At, Bt) do { __builtin_amdgcn_s_setprio(1); _Pragma("unroll") for (int m = 0; m < 4; ++m) _Pragma("unroll") for (int n = 0; n < 2; ++n) _Pragma("unroll") for (int k = 0; k < 2; ++k) \
;         acc[ai][bj][m][n] = __builtin_amdgcn_mfma_f32_16x16x32_bf16(Bt[n][k], At[m][k], acc[ai][bj][m][n], 0, 0, 0); __builtin_amdgcn_s_setprio(0); } while (0)
; #define PG8_WAIT_V(n) asm volatile("s_waitcnt vmcnt(" #n ")" ::: "memory")
; #define PG8_WAIT_L(n) asm volatile("s_waitcnt lgkmcnt(" #n ")" ::: "memory")
; #define PG8_BAR __builtin_amdgcn_s_barrier()
; #define PG8_SCHED __builtin_amdgcn_sched_barrier(0)
; template <class Epi, class Sched, bool ALIGN_EPI = false, bool SP2 = false>
; __device__ __forceinline__ void gemm_phase(PG8_LAS unsigned char* lds, const Gemm g, const Sched& S, const Epi& E) {
;     ...
;             PG8_WAIT_V(8); PG8_WAIT_L(0); PG8_BAR; PG8_MMA(1, 0, At, B0); PG8_MMA(1, 1, At, B1); PG8_BAR; PG8_SCHED;
;             PG8_LDB(B0, 1, 0); PG8_LDB(B1, 1, 1); PG8_SCHED; PG8_LDA(At, 1, 0); PG8_STAGE(PG8_SA(0, 1), a2 + hstep, voffA);
;             PG8_WAIT_V(8); PG8_WAIT_L(0); PG8_BAR; PG8_MMA(0, 0, At, B0); PG8_MMA(0, 1, At, B1); PG8_BAR; PG8_SCHED;
	s_waitcnt lgkmcnt(0)
	v_mfma_f32_16x16x32_bf16 v[60:63], v[146:149], v[196:199], v[60:63]
	v_mfma_f32_16x16x32_bf16 v[56:59], v[162:165], v[196:199], v[56:59]
	v_mfma_f32_16x16x32_bf16 v[52:55], v[146:149], v[204:207], v[52:55]
	v_mfma_f32_16x16x32_bf16 v[44:47], v[162:165], v[204:207], v[44:47]
	v_mfma_f32_16x16x32_bf16 v[36:39], v[146:149], v[212:215], v[36:39]
	v_mfma_f32_16x16x32_bf16 v[28:31], v[162:165], v[212:215], v[28:31]
	v_mfma_f32_16x16x32_bf16 v[20:23], v[146:149], v[220:223], v[20:23]
	v_mfma_f32_16x16x32_bf16 v[12:15], v[162:165], v[220:223], v[12:15]
	v_mfma_f32_16x16x32_bf16 v[60:63], v[158:161], v[200:203], v[60:63]
	v_mfma_f32_16x16x32_bf16 v[56:59], v[166:169], v[200:203], v[56:59]
	v_mfma_f32_16x16x32_bf16 v[52:55], v[158:161], v[208:211], v[52:55]
	v_mfma_f32_16x16x32_bf16 v[44:47], v[166:169], v[208:211], v[44:47]
	v_mfma_f32_16x16x32_bf16 v[36:39], v[158:161], v[216:219], v[36:39]
	v_mfma_f32_16x16x32_bf16 v[28:31], v[166:169], v[216:219], v[28:31]
	v_mfma_f32_16x16x32_bf16 v[20:23], v[158:161], v[224:227], v[20:23]
	v_mfma_f32_16x16x32_bf16 v[12:15], v[166:169], v[224:227], v[12:15]
	v_mfma_f32_16x16x32_bf16 v[48:51], v[180:183], v[196:199], v[48:51]
	v_mfma_f32_16x16x32_bf16 v[40:43], v[188:191], v[196:199], v[40:43]
	v_mfma_f32_16x16x32_bf16 v[32:35], v[180:183], v[204:207], v[32:35]
	v_mfma_f32_16x16x32_bf16 v[24:27], v[188:191], v[204:207], v[24:27]
	v_mfma_f32_16x16x32_bf16 v[16:19], v[180:183], v[212:215], v[16:19]
	v_mfma_f32_16x16x32_bf16 v[8:11], v[188:191], v[212:215], v[8:11]
	v_mfma_f32_16x16x32_bf16 v[4:7], v[180:183], v[220:223], v[4:7]
	v_mfma_f32_16x16x32_bf16 v[0:3], v[188:191], v[220:223], v[0:3]
	v_mfma_f32_16x16x32_bf16 v[48:51], v[184:187], v[200:203], v[48:51]
	v_mfma_f32_16x16x32_bf16 v[40:43], v[192:195], v[200:203], v[40:43]
	v_mfma_f32_16x16x32_bf16 v[32:35], v[184:187], v[208:211], v[32:35]
	v_mfma_f32_16x16x32_bf16 v[24:27], v[192:195], v[208:211], v[24:27]
	v_mfma_f32_16x16x32_bf16 v[16:19], v[184:187], v[216:219], v[16:19]
	v_mfma_f32_16x16x32_bf16 v[8:11], v[192:195], v[216:219], v[8:11]
	v_mfma_f32_16x16x32_bf16 v[4:7], v[184:187], v[224:227], v[4:7]
	v_mfma_f32_16x16x32_bf16 v[0:3], v[192:195], v[224:227], v[0:3]
	s_barrier
	s_add_i32 s49, 0, 0x18000
	v_add_u32_e32 v157, s49, v151
	s_add_i32 s50, 0, 0x1c000
	ds_read_b128 v[146:149], v157
	ds_read_b128 v[158:161], v157 offset:1024
	ds_read_b128 v[162:165], v157 offset:2048
	ds_read_b128 v[166:169], v157 offset:3072
	v_add_u32_e32 v157, s50, v151
	ds_read_b128 v[180:183], v157
	ds_read_b128 v[184:187], v157 offset:1024
	ds_read_b128 v[188:191], v157 offset:2048
	ds_read_b128 v[192:195], v157 offset:3072
	s_add_u32 s24, s24, 0x80000
	s_addc_u32 s25, s25, 0
	s_mov_b32 m0, s30
	v_lshl_add_u64 v[234:235], s[24:25], 0, v[130:131]
	ds_read_b128 v[196:199], v156 offset:32768
	ds_read_b128 v[200:203], v156 offset:33792
	ds_read_b128 v[204:207], v156 offset:34816
	ds_read_b128 v[208:211], v156 offset:35840
	ds_read_b128 v[212:215], v156 offset:36864
	ds_read_b128 v[216:219], v156 offset:37888
	ds_read_b128 v[220:223], v156 offset:38912
	ds_read_b128 v[224:227], v156 offset:39936
	global_load_lds_dwordx4 v[234:235], off
	v_lshl_add_u64 v[234:235], s[24:25], 0, v[134:135]
	s_mov_b32 m0, s31
	s_nop 0
	global_load_lds_dwordx4 v[234:235], off
	s_waitcnt vmcnt(8)
	s_waitcnt lgkmcnt(0)
	s_barrier
	s_waitcnt lgkmcnt(0)
	v_mfma_f32_16x16x32_bf16 v[124:127], v[146:149], v[196:199], v[124:127]
	v_mfma_f32_16x16x32_bf16 v[120:123], v[162:165], v[196:199], v[120:123]
	v_mfma_f32_16x16x32_bf16 v[112:115], v[146:149], v[204:207], v[112:115]
	v_mfma_f32_16x16x32_bf16 v[104:107], v[162:165], v[204:207], v[104:107]
	v_mfma_f32_16x16x32_bf16 v[96:99], v[146:149], v[212:215], v[96:99]
	v_mfma_f32_16x16x32_bf16 v[88:91], v[162:165], v[212:215], v[88:91]
	v_mfma_f32_16x16x32_bf16 v[80:83], v[146:149], v[220:223], v[80:83]
	v_mfma_f32_16x16x32_bf16 v[72:75], v[162:165], v[220:223], v[72:75]
	v_mfma_f32_16x16x32_bf16 v[124:127], v[158:161], v[200:203], v[124:127]
	v_mfma_f32_16x16x32_bf16 v[120:123], v[166:169], v[200:203], v[120:123]
	v_mfma_f32_16x16x32_bf16 v[112:115], v[158:161], v[208:211], v[112:115]
	v_mfma_f32_16x16x32_bf16 v[104:107], v[166:169], v[208:211], v[104:107]
	v_mfma_f32_16x16x32_bf16 v[96:99], v[158:161], v[216:219], v[96:99]
	v_mfma_f32_16x16x32_bf16 v[88:91], v[166:169], v[216:219], v[88:91]
	v_mfma_f32_16x16x32_bf16 v[80:83], v[158:161], v[224:227], v[80:83]
	v_mfma_f32_16x16x32_bf16 v[72:75], v[166:169], v[224:227], v[72:75]
	v_mfma_f32_16x16x32_bf16 v[116:119], v[180:183], v[196:199], v[116:119]
	v_mfma_f32_16x16x32_bf16 v[108:111], v[188:191], v[196:199], v[108:111]
	v_mfma_f32_16x16x32_bf16 v[100:103], v[180:183], v[204:207], v[100:103]
	v_mfma_f32_16x16x32_bf16 v[92:95], v[188:191], v[204:207], v[92:95]
	v_mfma_f32_16x16x32_bf16 v[84:87], v[180:183], v[212:215], v[84:87]
	v_mfma_f32_16x16x32_bf16 v[76:79], v[188:191], v[212:215], v[76:79]
	v_mfma_f32_16x16x32_bf16 v[68:71], v[180:183], v[220:223], v[68:71]
	v_mfma_f32_16x16x32_bf16 v[64:67], v[188:191], v[220:223], v[64:67]
	v_mfma_f32_16x16x32_bf16 v[116:119], v[184:187], v[200:203], v[116:119]
	v_mfma_f32_16x16x32_bf16 v[108:111], v[192:195], v[200:203], v[108:111]
	v_mfma_f32_16x16x32_bf16 v[100:103], v[184:187], v[208:211], v[100:103]
	v_mfma_f32_16x16x32_bf16 v[92:95], v[192:195], v[208:211], v[92:95]
	v_mfma_f32_16x16x32_bf16 v[84:87], v[184:187], v[216:219], v[84:87]
	v_mfma_f32_16x16x32_bf16 v[76:79], v[192:195], v[216:219], v[76:79]
	v_mfma_f32_16x16x32_bf16 v[68:71], v[184:187], v[224:227], v[68:71]
	v_mfma_f32_16x16x32_bf16 v[64:67], v[192:195], v[224:227], v[64:67]
	s_barrier
; #define PG8_STAGE(bufoff, gbase, voff) do { _Pragma("unroll") for (int _i = 0; _i < 2; ++_i) \
;         __builtin_amdgcn_global_load_lds((const unsigned*)((const char*)(gbase) + (voff)[_i]), (PG8_LAS unsigned*)(lds + (bufoff) + ldsw + _i * 8192), 16, 0, 0); } while (0)
; #define PG8_LDA(dst, b, h) do { _Pragma("unroll") for (int m = 0; m < 4; ++m) _Pragma("unroll") for (int k = 0; k < 2; ++k) dst[m][k] = *(const PG8_LAS bf16x8*)(lds + PG8_SA(b, h) + aoff + m * 2048 + k * 1024); } while (0)
; #define PG8_MMA(ai, bj, At, Bt) do { __builtin_amdgcn_s_setprio(1); _Pragma("unroll") for (int m = 0; m < 4; ++m) _Pragma("unroll") for (int n = 0; n < 2; ++n) _Pragma("unroll") for (int k = 0; k < 2; ++k) \
;         acc[ai][bj][m][n] = __builtin_amdgcn_mfma_f32_16x16x32_bf16(Bt[n][k], At[m][k], acc[ai][bj][m][n], 0, 0, 0); __builtin_amdgcn_s_setprio(0); } while (0)
; #define PG8_WAIT_V(n) asm volatile("s_waitcnt vmcnt(" #n ")" ::: "memory")
; #define PG8_WAIT_L(n) asm volatile("s_waitcnt lgkmcnt(" #n ")" ::: "memory")
; #define PG8_BAR __builtin_amdgcn_s_barrier()
; #define PG8_SCHED __builtin_amdgcn_sched_barrier(0)
; template <class Epi, class Sched, bool ALIGN_EPI = false, bool SP2 = false>
; __device__ __forceinline__ void gemm_phase(PG8_LAS unsigned char* lds, const Gemm g, const Sched& S, const Epi& E) {
;     ...
;             PG8_LDA(At, 1, 1); PG8_STAGE(PG8_SB(1, 0), b3, voffB); PG8_STAGE(PG8_SB(1, 1), b3 + hstep, voffB); PG8_STAGE(PG8_SA(1, 0), a3, voffA);
;             PG8_WAIT_V(8); PG8_WAIT_L(0); PG8_BAR; PG8_MMA(1, 0, At, B0); PG8_MMA(1, 1, At, B1); PG8_BAR; PG8_SCHED;
;     ...
;         if constexpr (ALIGN_EPI) { if (wr == 0) PG8_BAR; }
	s_add_i32 s24, s49, s28
	v_lshl_add_u64 v[170:171], v[170:171], 0, s[2:3]
	s_mov_b32 m0, s24
	ds_read_b128 v[196:199], v156 offset:49152
	ds_read_b128 v[200:203], v156 offset:50176
	ds_read_b128 v[204:207], v156 offset:51200
	ds_read_b128 v[208:211], v156 offset:52224
	ds_read_b128 v[212:215], v156 offset:53248
	ds_read_b128 v[216:219], v156 offset:54272
	ds_read_b128 v[220:223], v156 offset:55296
	ds_read_b128 v[224:227], v156 offset:56320
	global_load_lds_dwordx4 v[170:171], off
	s_add_i32 m0, s24, 0x2000
	s_add_u32 s22, s22, 0x80080
	v_lshl_add_u64 v[170:171], v[228:229], 0, s[2:3]
	s_addc_u32 s23, s23, 0
	s_add_i32 s24, s50, s28
	global_load_lds_dwordx4 v[170:171], off
	v_lshl_add_u64 v[170:171], s[22:23], 0, v[132:133]
	s_mov_b32 m0, s24
	s_nop 0
	global_load_lds_dwordx4 v[170:171], off
	v_lshl_add_u64 v[170:171], s[22:23], 0, v[136:137]
	s_add_i32 m0, s24, 0x2000
	s_nop 0
	global_load_lds_dwordx4 v[170:171], off
	v_lshl_add_u64 v[170:171], v[230:231], 0, s[2:3]
	s_mov_b32 m0, s33
	s_nop 0
	global_load_lds_dwordx4 v[170:171], off
	v_lshl_add_u64 v[170:171], v[232:233], 0, s[2:3]
	s_mov_b32 m0, s34
	s_nop 0
	global_load_lds_dwordx4 v[170:171], off
	s_waitcnt vmcnt(8)
	s_waitcnt lgkmcnt(0)
	s_barrier
	s_waitcnt lgkmcnt(0)
	v_mfma_f32_16x16x32_bf16 v[60:63], v[146:149], v[196:199], v[60:63]
	v_mfma_f32_16x16x32_bf16 v[56:59], v[162:165], v[196:199], v[56:59]
	v_mfma_f32_16x16x32_bf16 v[52:55], v[146:149], v[204:207], v[52:55]
	v_mfma_f32_16x16x32_bf16 v[44:47], v[162:165], v[204:207], v[44:47]
	v_mfma_f32_16x16x32_bf16 v[36:39], v[146:149], v[212:215], v[36:39]
	v_mfma_f32_16x16x32_bf16 v[28:31], v[162:165], v[212:215], v[28:31]
	v_mfma_f32_16x16x32_bf16 v[20:23], v[146:149], v[220:223], v[20:23]
	v_mfma_f32_16x16x32_bf16 v[12:15], v[162:165], v[220:223], v[12:15]
	v_mfma_f32_16x16x32_bf16 v[60:63], v[158:161], v[200:203], v[60:63]
	v_mfma_f32_16x16x32_bf16 v[56:59], v[166:169], v[200:203], v[56:59]
	v_mfma_f32_16x16x32_bf16 v[52:55], v[158:161], v[208:211], v[52:55]
	v_mfma_f32_16x16x32_bf16 v[44:47], v[166:169], v[208:211], v[44:47]
	v_mfma_f32_16x16x32_bf16 v[36:39], v[158:161], v[216:219], v[36:39]
	v_mfma_f32_16x16x32_bf16 v[28:31], v[166:169], v[216:219], v[28:31]
	v_mfma_f32_16x16x32_bf16 v[20:23], v[158:161], v[224:227], v[20:23]
	v_mfma_f32_16x16x32_bf16 v[12:15], v[166:169], v[224:227], v[12:15]
	v_mfma_f32_16x16x32_bf16 v[48:51], v[180:183], v[196:199], v[48:51]
	v_mfma_f32_16x16x32_bf16 v[40:43], v[188:191], v[196:199], v[40:43]
	v_mfma_f32_16x16x32_bf16 v[32:35], v[180:183], v[204:207], v[32:35]
	v_mfma_f32_16x16x32_bf16 v[24:27], v[188:191], v[204:207], v[24:27]
	v_mfma_f32_16x16x32_bf16 v[16:19], v[180:183], v[212:215], v[16:19]
	v_mfma_f32_16x16x32_bf16 v[8:11], v[188:191], v[212:215], v[8:11]
	v_mfma_f32_16x16x32_bf16 v[4:7], v[180:183], v[220:223], v[4:7]
	v_mfma_f32_16x16x32_bf16 v[0:3], v[188:191], v[220:223], v[0:3]
	v_mfma_f32_16x16x32_bf16 v[48:51], v[184:187], v[200:203], v[48:51]
	v_mfma_f32_16x16x32_bf16 v[40:43], v[192:195], v[200:203], v[40:43]
	v_mfma_f32_16x16x32_bf16 v[32:35], v[184:187], v[208:211], v[32:35]
	v_mfma_f32_16x16x32_bf16 v[24:27], v[192:195], v[208:211], v[24:27]
	v_mfma_f32_16x16x32_bf16 v[16:19], v[184:187], v[216:219], v[16:19]
	v_mfma_f32_16x16x32_bf16 v[8:11], v[192:195], v[216:219], v[8:11]
	v_mfma_f32_16x16x32_bf16 v[4:7], v[184:187], v[224:227], v[4:7]
	v_mfma_f32_16x16x32_bf16 v[0:3], v[192:195], v[224:227], v[0:3]
	s_barrier
	s_add_i32 s48, s48, 2
	s_add_u32 s20, s20, 0x100
	s_addc_u32 s21, s21, 0
	s_add_u32 s46, s46, 0x100
	s_addc_u32 s47, s47, 0
	s_cmp_gt_u32 s48, 29
	s_cbranch_scc0 .LBB0_1181
	s_and_b64 vcc, exec, s[4:5]
	s_cbranch_vccz .LBB0_1184
	s_barrier

; #define PG8_STAGE(bufoff, gbase, voff) do { _Pragma("unroll") for (int _i = 0; _i < 2; ++_i) \
;         __builtin_amdgcn_global_load_lds((const unsigned*)((const char*)(gbase) + (voff)[_i]), (PG8_LAS unsigned*)(lds + (bufoff) + ldsw + _i * 8192), 16, 0, 0); } while (0)
; #define PG8_LDA(dst, b, h) do { _Pragma("unroll") for (int m = 0; m < 4; ++m) _Pragma("unroll") for (int k = 0; k < 2; ++k) dst[m][k] = *(const PG8_LAS bf16x8*)(lds + PG8_SA(b, h) + aoff + m * 2048 + k * 1024); } while (0)
; #define PG8_LDB(dst, b, h) do { _Pragma("unroll") for (int n = 0; n < 2; ++n) _Pragma("unroll") for (int k = 0; k < 2; ++k) dst[n][k] = *(const PG8_LAS bf16x8*)(lds + PG8_SB(b, h) + boff + n * 2048 + k * 1024); } while (0)
; #define PG8_MMA(ai, bj, At, Bt) do { __builtin_amdgcn_s_setprio(1); _Pragma("unroll") for (int m = 0; m < 4; ++m) _Pragma("unroll") for (int n = 0; n < 2; ++n) _Pragma("unroll") for (int k = 0; k < 2; ++k) \
;         acc[ai][bj][m][n] = __builtin_amdgcn_mfma_f32_16x16x32_bf16(Bt[n][k], At[m][k], acc[ai][bj][m][n], 0, 0, 0); __builtin_amdgcn_s_setprio(0); } while (0)
; #define PG8_WAIT_V(n) asm volatile("s_waitcnt vmcnt(" #n ")" ::: "memory")
; #define PG8_BAR __builtin_amdgcn_s_barrier()
; template <class Epi, class Sched, bool ALIGN_EPI = false, bool SP2 = false>
; __device__ __forceinline__ void gemm_phase(PG8_LAS unsigned char* lds, const Gemm g, const Sched& S, const Epi& E) {
;     ...
;         for (int t = 0; t < nt; t += 2) {
;             const bool last = (t == nt - 2);
;             const char* a1 = cA + (size_t)(t + 1) * kstep;
;             const char* a2 = last ? nA : cA + (size_t)(t + 2) * kstep; const char* b2 = last ? nB : cB + (size_t)(t + 2) * kstep;
;             const char* a3 = a2 + kstep; const char* b3 = b2 + kstep;
;             if (last && has_next) S.a_ready(nxt);
;             if constexpr (SP2) {
;             PG8_LDB(B0, 0, 0); PG8_LDB(B1, 0, 1); PG8_SCHED; PG8_LDA(At, 0, 0); PG8_STAGE(PG8_SA(1, 1), a1 + hstep, voffA);
;             PG8_WAIT_V(8); PG8_WAIT_L(0); PG8_BAR; PG8_MMA(0, 0, At, B0); PG8_MMA(0, 1, At, B1); PG8_BAR; PG8_SCHED;
;             PG8_LDA(At, 0, 1); PG8_STAGE(PG8_SB(0, 0), b2, voffB); PG8_STAGE(PG8_SB(0, 1), b2 + hstep, voffB); PG8_STAGE(PG8_SA(0, 0), a2, voffA);
;             PG8_WAIT_V(8); PG8_WAIT_L(0); PG8_BAR; PG8_MMA(1, 0, At, B0); PG8_MMA(1, 1, At, B1); PG8_BAR; PG8_SCHED;
.LBB0_1457:
	ds_read_b128 v[142:145], v151
	ds_read_b128 v[154:157], v151 offset:1024
	ds_read_b128 v[158:161], v151 offset:2048
	ds_read_b128 v[162:165], v151 offset:3072
	ds_read_b128 v[166:169], v152
	ds_read_b128 v[178:181], v152 offset:1024
	ds_read_b128 v[182:185], v152 offset:2048
	ds_read_b128 v[186:189], v152 offset:3072
	s_add_u32 s24, s22, 0x100
	s_addc_u32 s25, s23, 0
	s_cmp_eq_u32 s47, 28
	s_cselect_b32 s29, s15, s25
	s_cselect_b32 s28, s21, s24
	s_cselect_b32 s27, s13, s46
	s_cselect_b32 s26, s44, s45
	v_lshl_add_u64 v[146:147], s[22:23], 0, v[134:135]
	s_add_i32 m0, s34, 0xc000
	ds_read_b128 v[190:193], v153
	ds_read_b128 v[194:197], v153 offset:1024
	ds_read_b128 v[198:201], v153 offset:2048
	ds_read_b128 v[202:205], v153 offset:3072
	ds_read_b128 v[206:209], v153 offset:4096
	ds_read_b128 v[210:213], v153 offset:5120
	ds_read_b128 v[214:217], v153 offset:6144
	ds_read_b128 v[218:221], v153 offset:7168
	global_load_lds_dwordx4 v[146:147], off
	v_lshl_add_u64 v[146:147], s[22:23], 0, v[136:137]
	s_add_i32 m0, s34, 0xe000
	s_nop 0
	global_load_lds_dwordx4 v[146:147], off
	s_waitcnt vmcnt(8)
	s_waitcnt lgkmcnt(0)
	s_barrier
	s_waitcnt lgkmcnt(0)
	v_mfma_f32_16x16x32_bf16 v[124:127], v[142:145], v[190:193], v[124:127]
	v_mfma_f32_16x16x32_bf16 v[120:123], v[158:161], v[190:193], v[120:123]
	v_mfma_f32_16x16x32_bf16 v[108:111], v[142:145], v[198:201], v[108:111]
	v_mfma_f32_16x16x32_bf16 v[104:107], v[158:161], v[198:201], v[104:107]
	v_mfma_f32_16x16x32_bf16 v[92:95], v[142:145], v[206:209], v[92:95]
	v_mfma_f32_16x16x32_bf16 v[88:91], v[158:161], v[206:209], v[88:91]
	v_mfma_f32_16x16x32_bf16 v[76:79], v[142:145], v[214:217], v[76:79]
	v_mfma_f32_16x16x32_bf16 v[72:75], v[158:161], v[214:217], v[72:75]
	v_mfma_f32_16x16x32_bf16 v[124:127], v[154:157], v[194:197], v[124:127]
	v_mfma_f32_16x16x32_bf16 v[120:123], v[162:165], v[194:197], v[120:123]
	v_mfma_f32_16x16x32_bf16 v[108:111], v[154:157], v[202:205], v[108:111]
	v_mfma_f32_16x16x32_bf16 v[104:107], v[162:165], v[202:205], v[104:107]
	v_mfma_f32_16x16x32_bf16 v[92:95], v[154:157], v[210:213], v[92:95]
	v_mfma_f32_16x16x32_bf16 v[88:91], v[162:165], v[210:213], v[88:91]
	v_mfma_f32_16x16x32_bf16 v[76:79], v[154:157], v[218:221], v[76:79]
	v_mfma_f32_16x16x32_bf16 v[72:75], v[162:165], v[218:221], v[72:75]
	v_mfma_f32_16x16x32_bf16 v[116:119], v[166:169], v[190:193], v[116:119]
	v_mfma_f32_16x16x32_bf16 v[112:115], v[182:185], v[190:193], v[112:115]
	v_mfma_f32_16x16x32_bf16 v[100:103], v[166:169], v[198:201], v[100:103]
	v_mfma_f32_16x16x32_bf16 v[96:99], v[182:185], v[198:201], v[96:99]
	v_mfma_f32_16x16x32_bf16 v[84:87], v[166:169], v[206:209], v[84:87]
	v_mfma_f32_16x16x32_bf16 v[80:83], v[182:185], v[206:209], v[80:83]
	v_mfma_f32_16x16x32_bf16 v[68:71], v[166:169], v[214:217], v[68:71]
	v_mfma_f32_16x16x32_bf16 v[64:67], v[182:185], v[214:217], v[64:67]
	v_mfma_f32_16x16x32_bf16 v[116:119], v[178:181], v[194:197], v[116:119]
	v_mfma_f32_16x16x32_bf16 v[112:115], v[186:189], v[194:197], v[112:115]
	v_mfma_f32_16x16x32_bf16 v[100:103], v[178:181], v[202:205], v[100:103]
	v_mfma_f32_16x16x32_bf16 v[96:99], v[186:189], v[202:205], v[96:99]
	v_mfma_f32_16x16x32_bf16 v[84:87], v[178:181], v[210:213], v[84:87]
	v_mfma_f32_16x16x32_bf16 v[80:83], v[186:189], v[210:213], v[80:83]
	v_mfma_f32_16x16x32_bf16 v[68:71], v[178:181], v[218:221], v[68:71]
	v_mfma_f32_16x16x32_bf16 v[64:67], v[186:189], v[218:221], v[64:67]
	s_barrier
	s_add_i32 s22, s41, s33
	v_lshl_add_u64 v[146:147], s[26:27], 0, v[130:131]
	s_mov_b32 m0, s22
	ds_read_b128 v[190:193], v153 offset:16384
	ds_read_b128 v[194:197], v153 offset:17408
	ds_read_b128 v[198:201], v153 offset:18432
	ds_read_b128 v[202:205], v153 offset:19456
	ds_read_b128 v[206:209], v153 offset:20480
	ds_read_b128 v[210:213], v153 offset:21504
	ds_read_b128 v[214:217], v153 offset:22528
	ds_read_b128 v[218:221], v153 offset:23552
	global_load_lds_dwordx4 v[146:147], off
	s_add_i32 m0, s22, 0x2000
	s_add_u32 s22, s26, 0x80000
	v_lshl_add_u64 v[170:171], s[26:27], 0, v[132:133]
	s_addc_u32 s23, s27, 0
	s_add_i32 s48, s42, s33
	global_load_lds_dwordx4 v[170:171], off
	v_lshl_add_u64 v[222:223], s[22:23], 0, v[130:131]
	s_mov_b32 m0, s48
	v_lshl_add_u64 v[224:225], s[28:29], 0, v[132:133]
	global_load_lds_dwordx4 v[222:223], off
	v_lshl_add_u64 v[222:223], s[22:23], 0, v[132:133]
	s_add_i32 m0, s48, 0x2000
	s_nop 0
	global_load_lds_dwordx4 v[222:223], off
	v_lshl_add_u64 v[222:223], s[28:29], 0, v[130:131]
	s_mov_b32 m0, s34
	s_nop 0
	global_load_lds_dwordx4 v[222:223], off
	s_mov_b32 m0, s35
	s_nop 0
	global_load_lds_dwordx4 v[224:225], off
	s_waitcnt vmcnt(8)
	s_waitcnt lgkmcnt(0)
	s_barrier
; #define PG8_STAGE(bufoff, gbase, voff) do { _Pragma("unroll") for (int _i = 0; _i < 2; ++_i) \
;         __builtin_amdgcn_global_load_lds((const unsigned*)((const char*)(gbase) + (voff)[_i]), (PG8_LAS unsigned*)(lds + (bufoff) + ldsw + _i * 8192), 16, 0, 0); } while (0)
; #define PG8_LDA(dst, b, h) do { _Pragma("unroll") for (int m = 0; m < 4; ++m) _Pragma("unroll") for (int k = 0; k < 2; ++k) dst[m][k] = *(const PG8_LAS bf16x8*)(lds + PG8_SA(b, h) + aoff + m * 2048 + k * 1024); } while (0)
; #define PG8_LDB(dst, b, h) do { _Pragma("unroll") for (int n = 0; n < 2; ++n) _Pragma("unroll") for (int k = 0; k < 2; ++k) dst[n][k] = *(const PG8_LAS bf16x8*)(lds + PG8_SB(b, h) + boff + n * 2048 + k * 1024); } while (0)
; #define PG8_MMA(ai, bj, At, Bt) do { __builtin_amdgcn_s_setprio(1); _Pragma("unroll") for (int m = 0; m < 4; ++m) _Pragma("unroll") for (int n = 0; n < 2; ++n) _Pragma("unroll") for (int k = 0; k < 2; ++k) \
;         acc[ai][bj][m][n] = __builtin_amdgcn_mfma_f32_16x16x32_bf16(Bt[n][k], At[m][k], acc[ai][bj][m][n], 0, 0, 0); __builtin_amdgcn_s_setprio(0); } while (0)
; #define PG8_WAIT_V(n) asm volatile("s_waitcnt vmcnt(" #n ")" ::: "memory")
; #define PG8_WAIT_L(n) asm volatile("s_waitcnt lgkmcnt(" #n ")" ::: "memory")
; #define PG8_BAR __builtin_amdgcn_s_barrier()
; #define PG8_SCHED __builtin_amdgcn_sched_barrier(0)
; template <class Epi, class Sched, bool ALIGN_EPI = false, bool SP2 = false>
; __device__ __forceinline__ void gemm_phase(PG8_LAS unsigned char* lds, const Gemm g, const Sched& S, const Epi& E) {
;     ...
;             PG8_WAIT_V(8); PG8_WAIT_L(0); PG8_BAR; PG8_MMA(1, 0, At, B0); PG8_MMA(1, 1, At, B1); PG8_BAR; PG8_SCHED;
;             PG8_LDB(B0, 1, 0); PG8_LDB(B1, 1, 1); PG8_SCHED; PG8_LDA(At, 1, 0); PG8_STAGE(PG8_SA(0, 1), a2 + hstep, voffA);
;             PG8_WAIT_V(8); PG8_WAIT_L(0); PG8_BAR; PG8_MMA(0, 0, At, B0); PG8_MMA(0, 1, At, B1); PG8_BAR; PG8_SCHED;
	s_waitcnt lgkmcnt(0)
	v_mfma_f32_16x16x32_bf16 v[60:63], v[142:145], v[190:193], v[60:63]
	v_mfma_f32_16x16x32_bf16 v[56:59], v[158:161], v[190:193], v[56:59]
	v_mfma_f32_16x16x32_bf16 v[44:47], v[142:145], v[198:201], v[44:47]
	v_mfma_f32_16x16x32_bf16 v[40:43], v[158:161], v[198:201], v[40:43]
	v_mfma_f32_16x16x32_bf16 v[28:31], v[142:145], v[206:209], v[28:31]
	v_mfma_f32_16x16x32_bf16 v[24:27], v[158:161], v[206:209], v[24:27]
	v_mfma_f32_16x16x32_bf16 v[12:15], v[142:145], v[214:217], v[12:15]
	v_mfma_f32_16x16x32_bf16 v[8:11], v[158:161], v[214:217], v[8:11]
	v_mfma_f32_16x16x32_bf16 v[60:63], v[154:157], v[194:197], v[60:63]
	v_mfma_f32_16x16x32_bf16 v[56:59], v[162:165], v[194:197], v[56:59]
	v_mfma_f32_16x16x32_bf16 v[44:47], v[154:157], v[202:205], v[44:47]
	v_mfma_f32_16x16x32_bf16 v[40:43], v[162:165], v[202:205], v[40:43]
	v_mfma_f32_16x16x32_bf16 v[28:31], v[154:157], v[210:213], v[28:31]
	v_mfma_f32_16x16x32_bf16 v[24:27], v[162:165], v[210:213], v[24:27]
	v_mfma_f32_16x16x32_bf16 v[12:15], v[154:157], v[218:221], v[12:15]
	v_mfma_f32_16x16x32_bf16 v[8:11], v[162:165], v[218:221], v[8:11]
	v_mfma_f32_16x16x32_bf16 v[52:55], v[166:169], v[190:193], v[52:55]
	v_mfma_f32_16x16x32_bf16 v[48:51], v[182:185], v[190:193], v[48:51]
	v_mfma_f32_16x16x32_bf16 v[36:39], v[166:169], v[198:201], v[36:39]
	v_mfma_f32_16x16x32_bf16 v[32:35], v[182:185], v[198:201], v[32:35]
	v_mfma_f32_16x16x32_bf16 v[20:23], v[166:169], v[206:209], v[20:23]
	v_mfma_f32_16x16x32_bf16 v[16:19], v[182:185], v[206:209], v[16:19]
	v_mfma_f32_16x16x32_bf16 v[4:7], v[166:169], v[214:217], v[4:7]
	v_mfma_f32_16x16x32_bf16 v[0:3], v[182:185], v[214:217], v[0:3]
	v_mfma_f32_16x16x32_bf16 v[52:55], v[178:181], v[194:197], v[52:55]
	v_mfma_f32_16x16x32_bf16 v[48:51], v[186:189], v[194:197], v[48:51]
	v_mfma_f32_16x16x32_bf16 v[36:39], v[178:181], v[202:205], v[36:39]
	v_mfma_f32_16x16x32_bf16 v[32:35], v[186:189], v[202:205], v[32:35]
	v_mfma_f32_16x16x32_bf16 v[20:23], v[178:181], v[210:213], v[20:23]
	v_mfma_f32_16x16x32_bf16 v[16:19], v[186:189], v[210:213], v[16:19]
	v_mfma_f32_16x16x32_bf16 v[4:7], v[178:181], v[218:221], v[4:7]
	v_mfma_f32_16x16x32_bf16 v[0:3], v[186:189], v[218:221], v[0:3]
	s_barrier
	s_add_i32 s48, 0, 0x18000
	s_add_i32 s49, 0, 0x1c000
	v_add_u32_e32 v162, s48, v149
	v_add_u32_e32 v186, s49, v149
	ds_read_b128 v[142:145], v162
	ds_read_b128 v[154:157], v162 offset:1024
	ds_read_b128 v[158:161], v162 offset:2048
	ds_read_b128 v[162:165], v162 offset:3072
	ds_read_b128 v[166:169], v186
	ds_read_b128 v[178:181], v186 offset:1024
	ds_read_b128 v[182:185], v186 offset:2048
	ds_read_b128 v[186:189], v186 offset:3072
	s_add_u32 s22, s28, 0x80000
	s_addc_u32 s23, s29, 0
	s_mov_b32 m0, s36
	v_lshl_add_u64 v[226:227], s[22:23], 0, v[130:131]
	ds_read_b128 v[190:193], v153 offset:32768
	ds_read_b128 v[194:197], v153 offset:33792
	ds_read_b128 v[198:201], v153 offset:34816
	ds_read_b128 v[202:205], v153 offset:35840
	ds_read_b128 v[206:209], v153 offset:36864
	ds_read_b128 v[210:213], v153 offset:37888
	ds_read_b128 v[214:217], v153 offset:38912
	ds_read_b128 v[218:221], v153 offset:39936
	global_load_lds_dwordx4 v[226:227], off
	v_lshl_add_u64 v[226:227], s[22:23], 0, v[132:133]
	s_mov_b32 m0, s37
	s_nop 0
	global_load_lds_dwordx4 v[226:227], off
	s_waitcnt vmcnt(8)
	s_waitcnt lgkmcnt(0)
	s_barrier
	s_waitcnt lgkmcnt(0)
	v_mfma_f32_16x16x32_bf16 v[124:127], v[142:145], v[190:193], v[124:127]
	v_mfma_f32_16x16x32_bf16 v[120:123], v[158:161], v[190:193], v[120:123]
	v_mfma_f32_16x16x32_bf16 v[108:111], v[142:145], v[198:201], v[108:111]
	v_mfma_f32_16x16x32_bf16 v[104:107], v[158:161], v[198:201], v[104:107]
	v_mfma_f32_16x16x32_bf16 v[92:95], v[142:145], v[206:209], v[92:95]
	v_mfma_f32_16x16x32_bf16 v[88:91], v[158:161], v[206:209], v[88:91]
	v_mfma_f32_16x16x32_bf16 v[76:79], v[142:145], v[214:217], v[76:79]
	v_mfma_f32_16x16x32_bf16 v[72:75], v[158:161], v[214:217], v[72:75]
	v_mfma_f32_16x16x32_bf16 v[124:127], v[154:157], v[194:197], v[124:127]
	v_mfma_f32_16x16x32_bf16 v[120:123], v[162:165], v[194:197], v[120:123]
	v_mfma_f32_16x16x32_bf16 v[108:111], v[154:157], v[202:205], v[108:111]
	v_mfma_f32_16x16x32_bf16 v[104:107], v[162:165], v[202:205], v[104:107]
	v_mfma_f32_16x16x32_bf16 v[92:95], v[154:157], v[210:213], v[92:95]
	v_mfma_f32_16x16x32_bf16 v[88:91], v[162:165], v[210:213], v[88:91]
	v_mfma_f32_16x16x32_bf16 v[76:79], v[154:157], v[218:221], v[76:79]
	v_mfma_f32_16x16x32_bf16 v[72:75], v[162:165], v[218:221], v[72:75]
	v_mfma_f32_16x16x32_bf16 v[116:119], v[166:169], v[190:193], v[116:119]
	v_mfma_f32_16x16x32_bf16 v[112:115], v[182:185], v[190:193], v[112:115]
	v_mfma_f32_16x16x32_bf16 v[100:103], v[166:169], v[198:201], v[100:103]
	v_mfma_f32_16x16x32_bf16 v[96:99], v[182:185], v[198:201], v[96:99]
	v_mfma_f32_16x16x32_bf16 v[84:87], v[166:169], v[206:209], v[84:87]
	v_mfma_f32_16x16x32_bf16 v[80:83], v[182:185], v[206:209], v[80:83]
	v_mfma_f32_16x16x32_bf16 v[68:71], v[166:169], v[214:217], v[68:71]
	v_mfma_f32_16x16x32_bf16 v[64:67], v[182:185], v[214:217], v[64:67]
	v_mfma_f32_16x16x32_bf16 v[116:119], v[178:181], v[194:197], v[116:119]
	v_mfma_f32_16x16x32_bf16 v[112:115], v[186:189], v[194:197], v[112:115]
	v_mfma_f32_16x16x32_bf16 v[100:103], v[178:181], v[202:205], v[100:103]
	v_mfma_f32_16x16x32_bf16 v[96:99], v[186:189], v[202:205], v[96:99]
	v_mfma_f32_16x16x32_bf16 v[84:87], v[178:181], v[210:213], v[84:87]
	v_mfma_f32_16x16x32_bf16 v[80:83], v[186:189], v[210:213], v[80:83]
	v_mfma_f32_16x16x32_bf16 v[68:71], v[178:181], v[218:221], v[68:71]
	v_mfma_f32_16x16x32_bf16 v[64:67], v[186:189], v[218:221], v[64:67]
	s_barrier
; #define PG8_STAGE(bufoff, gbase, voff) do { _Pragma("unroll") for (int _i = 0; _i < 2; ++_i) \
;         __builtin_amdgcn_global_load_lds((const unsigned*)((const char*)(gbase) + (voff)[_i]), (PG8_LAS unsigned*)(lds + (bufoff) + ldsw + _i * 8192), 16, 0, 0); } while (0)
; #define PG8_LDA(dst, b, h) do { _Pragma("unroll") for (int m = 0; m < 4; ++m) _Pragma("unroll") for (int k = 0; k < 2; ++k) dst[m][k] = *(const PG8_LAS bf16x8*)(lds + PG8_SA(b, h) + aoff + m * 2048 + k * 1024); } while (0)
; #define PG8_MMA(ai, bj, At, Bt) do { __builtin_amdgcn_s_setprio(1); _Pragma("unroll") for (int m = 0; m < 4; ++m) _Pragma("unroll") for (int n = 0; n < 2; ++n) _Pragma("unroll") for (int k = 0; k < 2; ++k) \
;         acc[ai][bj][m][n] = __builtin_amdgcn_mfma_f32_16x16x32_bf16(Bt[n][k], At[m][k], acc[ai][bj][m][n], 0, 0, 0); __builtin_amdgcn_s_setprio(0); } while (0)
; #define PG8_WAIT_V(n) asm volatile("s_waitcnt vmcnt(" #n ")" ::: "memory")
; #define PG8_WAIT_L(n) asm volatile("s_waitcnt lgkmcnt(" #n ")" ::: "memory")
; #define PG8_BAR __builtin_amdgcn_s_barrier()
; #define PG8_SCHED __builtin_amdgcn_sched_barrier(0)
; template <class Epi, class Sched, bool ALIGN_EPI = false, bool SP2 = false>
; __device__ __forceinline__ void gemm_phase(PG8_LAS unsigned char* lds, const Gemm g, const Sched& S, const Epi& E) {
;     ...
;             PG8_LDA(At, 1, 1); PG8_STAGE(PG8_SB(1, 0), b3, voffB); PG8_STAGE(PG8_SB(1, 1), b3 + hstep, voffB); PG8_STAGE(PG8_SA(1, 0), a3, voffA);
;             PG8_WAIT_V(8); PG8_WAIT_L(0); PG8_BAR; PG8_MMA(1, 0, At, B0); PG8_MMA(1, 1, At, B1); PG8_BAR; PG8_SCHED;
;     ...
;         if constexpr (ALIGN_EPI) { if (wr == 0) PG8_BAR; }
	s_add_i32 s22, s48, s33
	v_lshl_add_u64 v[146:147], v[146:147], 0, s[4:5]
	s_mov_b32 m0, s22
	ds_read_b128 v[190:193], v153 offset:49152
	ds_read_b128 v[194:197], v153 offset:50176
	ds_read_b128 v[198:201], v153 offset:51200
	ds_read_b128 v[202:205], v153 offset:52224
	ds_read_b128 v[206:209], v153 offset:53248
	ds_read_b128 v[210:213], v153 offset:54272
	ds_read_b128 v[214:217], v153 offset:55296
	ds_read_b128 v[218:221], v153 offset:56320
	global_load_lds_dwordx4 v[146:147], off
	s_add_i32 m0, s22, 0x2000
	s_add_u32 s22, s26, 0x80080
	v_lshl_add_u64 v[146:147], v[170:171], 0, s[4:5]
	s_addc_u32 s23, s27, 0
	s_add_i32 s26, s49, s33
	global_load_lds_dwordx4 v[146:147], off
	v_lshl_add_u64 v[146:147], s[22:23], 0, v[130:131]
	s_mov_b32 m0, s26
	s_nop 0
	global_load_lds_dwordx4 v[146:147], off
	v_lshl_add_u64 v[146:147], s[22:23], 0, v[132:133]
	s_add_i32 m0, s26, 0x2000
	s_nop 0
	global_load_lds_dwordx4 v[146:147], off
	v_lshl_add_u64 v[146:147], v[222:223], 0, s[4:5]
	s_mov_b32 m0, s39
	s_nop 0
	global_load_lds_dwordx4 v[146:147], off
	v_lshl_add_u64 v[146:147], v[224:225], 0, s[4:5]
	s_mov_b32 m0, s40
	s_nop 0
	global_load_lds_dwordx4 v[146:147], off
	s_waitcnt vmcnt(8)
	s_waitcnt lgkmcnt(0)
	s_barrier
	s_waitcnt lgkmcnt(0)
	v_mfma_f32_16x16x32_bf16 v[60:63], v[142:145], v[190:193], v[60:63]
	v_mfma_f32_16x16x32_bf16 v[56:59], v[158:161], v[190:193], v[56:59]
	v_mfma_f32_16x16x32_bf16 v[44:47], v[142:145], v[198:201], v[44:47]
	v_mfma_f32_16x16x32_bf16 v[40:43], v[158:161], v[198:201], v[40:43]
	v_mfma_f32_16x16x32_bf16 v[28:31], v[142:145], v[206:209], v[28:31]
	v_mfma_f32_16x16x32_bf16 v[24:27], v[158:161], v[206:209], v[24:27]
	v_mfma_f32_16x16x32_bf16 v[12:15], v[142:145], v[214:217], v[12:15]
	v_mfma_f32_16x16x32_bf16 v[8:11], v[158:161], v[214:217], v[8:11]
	v_mfma_f32_16x16x32_bf16 v[60:63], v[154:157], v[194:197], v[60:63]
	v_mfma_f32_16x16x32_bf16 v[56:59], v[162:165], v[194:197], v[56:59]
	v_mfma_f32_16x16x32_bf16 v[44:47], v[154:157], v[202:205], v[44:47]
	v_mfma_f32_16x16x32_bf16 v[40:43], v[162:165], v[202:205], v[40:43]
	v_mfma_f32_16x16x32_bf16 v[28:31], v[154:157], v[210:213], v[28:31]
	v_mfma_f32_16x16x32_bf16 v[24:27], v[162:165], v[210:213], v[24:27]
	v_mfma_f32_16x16x32_bf16 v[12:15], v[154:157], v[218:221], v[12:15]
	v_mfma_f32_16x16x32_bf16 v[8:11], v[162:165], v[218:221], v[8:11]
	v_mfma_f32_16x16x32_bf16 v[52:55], v[166:169], v[190:193], v[52:55]
	v_mfma_f32_16x16x32_bf16 v[48:51], v[182:185], v[190:193], v[48:51]
	v_mfma_f32_16x16x32_bf16 v[36:39], v[166:169], v[198:201], v[36:39]
	v_mfma_f32_16x16x32_bf16 v[32:35], v[182:185], v[198:201], v[32:35]
	v_mfma_f32_16x16x32_bf16 v[20:23], v[166:169], v[206:209], v[20:23]
	v_mfma_f32_16x16x32_bf16 v[16:19], v[182:185], v[206:209], v[16:19]
	v_mfma_f32_16x16x32_bf16 v[4:7], v[166:169], v[214:217], v[4:7]
	v_mfma_f32_16x16x32_bf16 v[0:3], v[182:185], v[214:217], v[0:3]
	v_mfma_f32_16x16x32_bf16 v[52:55], v[178:181], v[194:197], v[52:55]
	v_mfma_f32_16x16x32_bf16 v[48:51], v[186:189], v[194:197], v[48:51]
	v_mfma_f32_16x16x32_bf16 v[36:39], v[178:181], v[202:205], v[36:39]
	v_mfma_f32_16x16x32_bf16 v[32:35], v[186:189], v[202:205], v[32:35]
	v_mfma_f32_16x16x32_bf16 v[20:23], v[178:181], v[210:213], v[20:23]
	v_mfma_f32_16x16x32_bf16 v[16:19], v[186:189], v[210:213], v[16:19]
	v_mfma_f32_16x16x32_bf16 v[4:7], v[178:181], v[218:221], v[4:7]
	v_mfma_f32_16x16x32_bf16 v[0:3], v[186:189], v[218:221], v[0:3]
	s_barrier
	s_add_i32 s47, s47, 2
	s_add_u32 s45, s45, 0x100
	s_addc_u32 s46, s46, 0
	s_cmp_gt_u32 s47, 29
	s_mov_b64 s[22:23], s[24:25]
	s_cbranch_scc0 .LBB0_1457
	s_and_b64 vcc, exec, s[6:7]
	s_cbranch_vccz .LBB0_1460
	s_barrier

; #define PG8_STAGE(bufoff, gbase, voff) do { _Pragma("unroll") for (int _i = 0; _i < 2; ++_i) \
;         __builtin_amdgcn_global_load_lds((const unsigned*)((const char*)(gbase) + (voff)[_i]), (PG8_LAS unsigned*)(lds + (bufoff) + ldsw + _i * 8192), 16, 0, 0); } while (0)
; #define PG8_LDA(dst, b, h) do { _Pragma("unroll") for (int m = 0; m < 4; ++m) _Pragma("unroll") for (int k = 0; k < 2; ++k) dst[m][k] = *(const PG8_LAS bf16x8*)(lds + PG8_SA(b, h) + aoff + m * 2048 + k * 1024); } while (0)
; #define PG8_LDB(dst, b, h) do { _Pragma("unroll") for (int n = 0; n < 2; ++n) _Pragma("unroll") for (int k = 0; k < 2; ++k) dst[n][k] = *(const PG8_LAS bf16x8*)(lds + PG8_SB(b, h) + boff + n * 2048 + k * 1024); } while (0)
; #define PG8_MMA(ai, bj, At, Bt) do { __builtin_amdgcn_s_setprio(1); _Pragma("unroll") for (int m = 0; m < 4; ++m) _Pragma("unroll") for (int n = 0; n < 2; ++n) _Pragma("unroll") for (int k = 0; k < 2; ++k) \
;         acc[ai][bj][m][n] = __builtin_amdgcn_mfma_f32_16x16x32_bf16(Bt[n][k], At[m][k], acc[ai][bj][m][n], 0, 0, 0); __builtin_amdgcn_s_setprio(0); } while (0)
; #define PG8_WAIT_V(n) asm volatile("s_waitcnt vmcnt(" #n ")" ::: "memory")
; #define PG8_BAR __builtin_amdgcn_s_barrier()
; template <class Epi, class Sched, bool ALIGN_EPI = false, bool SP2 = false>
; __device__ __forceinline__ void gemm_phase(PG8_LAS unsigned char* lds, const Gemm g, const Sched& S, const Epi& E) {
;     ...
;         for (int t = 0; t < nt; t += 2) {
;             const bool last = (t == nt - 2);
;             const char* a1 = cA + (size_t)(t + 1) * kstep;
;             const char* a2 = last ? nA : cA + (size_t)(t + 2) * kstep; const char* b2 = last ? nB : cB + (size_t)(t + 2) * kstep;
;             const char* a3 = a2 + kstep; const char* b3 = b2 + kstep;
;             if (last && has_next) S.a_ready(nxt);
;             if constexpr (SP2) {
;             PG8_LDB(B0, 0, 0); PG8_LDB(B1, 0, 1); PG8_SCHED; PG8_LDA(At, 0, 0); PG8_STAGE(PG8_SA(1, 1), a1 + hstep, voffA);
;             PG8_WAIT_V(8); PG8_WAIT_L(0); PG8_BAR; PG8_MMA(0, 0, At, B0); PG8_MMA(0, 1, At, B1); PG8_BAR; PG8_SCHED;
;             PG8_LDA(At, 0, 1); PG8_STAGE(PG8_SB(0, 0), b2, voffB); PG8_STAGE(PG8_SB(0, 1), b2 + hstep, voffB); PG8_STAGE(PG8_SA(0, 0), a2, voffA);
;             PG8_WAIT_V(8); PG8_WAIT_L(0); PG8_BAR; PG8_MMA(1, 0, At, B0); PG8_MMA(1, 1, At, B1); PG8_BAR; PG8_SCHED;
.LBB0_1712:
	ds_read_b128 v[144:147], v156
	ds_read_b128 v[148:151], v156 offset:1024
	ds_read_b128 v[160:163], v156 offset:2048
	ds_read_b128 v[164:167], v156 offset:3072
	ds_read_b128 v[168:171], v157
	ds_read_b128 v[174:177], v157 offset:1024
	ds_read_b128 v[178:181], v157 offset:2048
	ds_read_b128 v[182:185], v157 offset:3072
	s_add_u32 s20, s18, 0xfff80080
	s_addc_u32 s21, s19, -1
	s_cmp_eq_u32 s44, 28
	s_cselect_b32 s23, s11, s21
	s_cselect_b32 s22, s40, s20
	s_cselect_b32 s21, s9, s43
	s_cselect_b32 s20, s41, s42
	v_lshl_add_u64 v[218:219], s[18:19], 0, v[136:137]
	s_add_i32 m0, s17, 0xc000
	ds_read_b128 v[186:189], v158
	ds_read_b128 v[190:193], v158 offset:1024
	ds_read_b128 v[194:197], v158 offset:2048
	ds_read_b128 v[198:201], v158 offset:3072
	ds_read_b128 v[202:205], v158 offset:4096
	ds_read_b128 v[206:209], v158 offset:5120
	ds_read_b128 v[210:213], v158 offset:6144
	ds_read_b128 v[214:217], v158 offset:7168
	global_load_lds_dwordx4 v[218:219], off
	v_lshl_add_u64 v[218:219], s[18:19], 0, v[138:139]
	s_add_i32 m0, s17, 0xe000
	s_nop 0
	global_load_lds_dwordx4 v[218:219], off
	s_waitcnt vmcnt(8)
	s_waitcnt lgkmcnt(0)
	s_barrier
	s_waitcnt lgkmcnt(0)
	v_mfma_f32_16x16x32_bf16 v[124:127], v[144:147], v[186:189], v[124:127]
	v_mfma_f32_16x16x32_bf16 v[120:123], v[160:163], v[186:189], v[120:123]
	v_mfma_f32_16x16x32_bf16 v[108:111], v[144:147], v[194:197], v[108:111]
	v_mfma_f32_16x16x32_bf16 v[104:107], v[160:163], v[194:197], v[104:107]
	v_mfma_f32_16x16x32_bf16 v[92:95], v[144:147], v[202:205], v[92:95]
	v_mfma_f32_16x16x32_bf16 v[88:91], v[160:163], v[202:205], v[88:91]
	v_mfma_f32_16x16x32_bf16 v[76:79], v[144:147], v[210:213], v[76:79]
	v_mfma_f32_16x16x32_bf16 v[72:75], v[160:163], v[210:213], v[72:75]
	v_mfma_f32_16x16x32_bf16 v[124:127], v[148:151], v[190:193], v[124:127]
	v_mfma_f32_16x16x32_bf16 v[120:123], v[164:167], v[190:193], v[120:123]
	v_mfma_f32_16x16x32_bf16 v[108:111], v[148:151], v[198:201], v[108:111]
	v_mfma_f32_16x16x32_bf16 v[104:107], v[164:167], v[198:201], v[104:107]
	v_mfma_f32_16x16x32_bf16 v[92:95], v[148:151], v[206:209], v[92:95]
	v_mfma_f32_16x16x32_bf16 v[88:91], v[164:167], v[206:209], v[88:91]
	v_mfma_f32_16x16x32_bf16 v[76:79], v[148:151], v[214:217], v[76:79]
	v_mfma_f32_16x16x32_bf16 v[72:75], v[164:167], v[214:217], v[72:75]
	v_mfma_f32_16x16x32_bf16 v[116:119], v[168:171], v[186:189], v[116:119]
	v_mfma_f32_16x16x32_bf16 v[112:115], v[178:181], v[186:189], v[112:115]
	v_mfma_f32_16x16x32_bf16 v[100:103], v[168:171], v[194:197], v[100:103]
	v_mfma_f32_16x16x32_bf16 v[96:99], v[178:181], v[194:197], v[96:99]
	v_mfma_f32_16x16x32_bf16 v[84:87], v[168:171], v[202:205], v[84:87]
	v_mfma_f32_16x16x32_bf16 v[80:83], v[178:181], v[202:205], v[80:83]
	v_mfma_f32_16x16x32_bf16 v[68:71], v[168:171], v[210:213], v[68:71]
	v_mfma_f32_16x16x32_bf16 v[64:67], v[178:181], v[210:213], v[64:67]
	v_mfma_f32_16x16x32_bf16 v[116:119], v[174:177], v[190:193], v[116:119]
	v_mfma_f32_16x16x32_bf16 v[112:115], v[182:185], v[190:193], v[112:115]
	v_mfma_f32_16x16x32_bf16 v[100:103], v[174:177], v[198:201], v[100:103]
	v_mfma_f32_16x16x32_bf16 v[96:99], v[182:185], v[198:201], v[96:99]
	v_mfma_f32_16x16x32_bf16 v[84:87], v[174:177], v[206:209], v[84:87]
	v_mfma_f32_16x16x32_bf16 v[80:83], v[182:185], v[206:209], v[80:83]
	v_mfma_f32_16x16x32_bf16 v[68:71], v[174:177], v[214:217], v[68:71]
	v_mfma_f32_16x16x32_bf16 v[64:67], v[182:185], v[214:217], v[64:67]
	s_barrier
	s_add_i32 s45, s34, s26
	v_lshl_add_u64 v[218:219], s[20:21], 0, v[132:133]
	s_mov_b32 m0, s45
	ds_read_b128 v[186:189], v158 offset:16384
	ds_read_b128 v[190:193], v158 offset:17408
	ds_read_b128 v[194:197], v158 offset:18432
	ds_read_b128 v[198:201], v158 offset:19456
	ds_read_b128 v[202:205], v158 offset:20480
	ds_read_b128 v[206:209], v158 offset:21504
	ds_read_b128 v[210:213], v158 offset:22528
	ds_read_b128 v[214:217], v158 offset:23552
	global_load_lds_dwordx4 v[218:219], off
	s_add_i32 m0, s45, 0x2000
	s_add_u32 s46, s20, 0x80000
	v_lshl_add_u64 v[220:221], s[20:21], 0, v[128:129]
	s_addc_u32 s47, s21, 0
	s_add_i32 s45, s35, s26
	global_load_lds_dwordx4 v[220:221], off
	v_lshl_add_u64 v[222:223], s[46:47], 0, v[132:133]
	s_mov_b32 m0, s45
	v_lshl_add_u64 v[224:225], s[22:23], 0, v[130:131]
	global_load_lds_dwordx4 v[222:223], off
	v_lshl_add_u64 v[222:223], s[46:47], 0, v[128:129]
	s_add_i32 m0, s45, 0x2000
	s_nop 0
	global_load_lds_dwordx4 v[222:223], off
	v_lshl_add_u64 v[222:223], s[22:23], 0, v[134:135]
	s_mov_b32 m0, s17
	s_nop 0
	global_load_lds_dwordx4 v[222:223], off
	s_mov_b32 m0, s28
	s_nop 0
	global_load_lds_dwordx4 v[224:225], off
	s_waitcnt vmcnt(8)
	s_waitcnt lgkmcnt(0)
	s_barrier
; #define PG8_STAGE(bufoff, gbase, voff) do { _Pragma("unroll") for (int _i = 0; _i < 2; ++_i) \
;         __builtin_amdgcn_global_load_lds((const unsigned*)((const char*)(gbase) + (voff)[_i]), (PG8_LAS unsigned*)(lds + (bufoff) + ldsw + _i * 8192), 16, 0, 0); } while (0)
; #define PG8_LDA(dst, b, h) do { _Pragma("unroll") for (int m = 0; m < 4; ++m) _Pragma("unroll") for (int k = 0; k < 2; ++k) dst[m][k] = *(const PG8_LAS bf16x8*)(lds + PG8_SA(b, h) + aoff + m * 2048 + k * 1024); } while (0)
; #define PG8_LDB(dst, b, h) do { _Pragma("unroll") for (int n = 0; n < 2; ++n) _Pragma("unroll") for (int k = 0; k < 2; ++k) dst[n][k] = *(const PG8_LAS bf16x8*)(lds + PG8_SB(b, h) + boff + n * 2048 + k * 1024); } while (0)
; #define PG8_MMA(ai, bj, At, Bt) do { __builtin_amdgcn_s_setprio(1); _Pragma("unroll") for (int m = 0; m < 4; ++m) _Pragma("unroll") for (int n = 0; n < 2; ++n) _Pragma("unroll") for (int k = 0; k < 2; ++k) \
;         acc[ai][bj][m][n] = __builtin_amdgcn_mfma_f32_16x16x32_bf16(Bt[n][k], At[m][k], acc[ai][bj][m][n], 0, 0, 0); __builtin_amdgcn_s_setprio(0); } while (0)
; #define PG8_WAIT_V(n) asm volatile("s_waitcnt vmcnt(" #n ")" ::: "memory")
; #define PG8_WAIT_L(n) asm volatile("s_waitcnt lgkmcnt(" #n ")" ::: "memory")
; #define PG8_BAR __builtin_amdgcn_s_barrier()
; #define PG8_SCHED __builtin_amdgcn_sched_barrier(0)
; template <class Epi, class Sched, bool ALIGN_EPI = false, bool SP2 = false>
; __device__ __forceinline__ void gemm_phase(PG8_LAS unsigned char* lds, const Gemm g, const Sched& S, const Epi& E) {
;     ...
;             PG8_WAIT_V(8); PG8_WAIT_L(0); PG8_BAR; PG8_MMA(1, 0, At, B0); PG8_MMA(1, 1, At, B1); PG8_BAR; PG8_SCHED;
;             PG8_LDB(B0, 1, 0); PG8_LDB(B1, 1, 1); PG8_SCHED; PG8_LDA(At, 1, 0); PG8_STAGE(PG8_SA(0, 1), a2 + hstep, voffA);
;             PG8_WAIT_V(8); PG8_WAIT_L(0); PG8_BAR; PG8_MMA(0, 0, At, B0); PG8_MMA(0, 1, At, B1); PG8_BAR; PG8_SCHED;
	s_waitcnt lgkmcnt(0)
	v_mfma_f32_16x16x32_bf16 v[60:63], v[144:147], v[186:189], v[60:63]
	v_mfma_f32_16x16x32_bf16 v[56:59], v[160:163], v[186:189], v[56:59]
	v_mfma_f32_16x16x32_bf16 v[44:47], v[144:147], v[194:197], v[44:47]
	v_mfma_f32_16x16x32_bf16 v[40:43], v[160:163], v[194:197], v[40:43]
	v_mfma_f32_16x16x32_bf16 v[28:31], v[144:147], v[202:205], v[28:31]
	v_mfma_f32_16x16x32_bf16 v[24:27], v[160:163], v[202:205], v[24:27]
	v_mfma_f32_16x16x32_bf16 v[12:15], v[144:147], v[210:213], v[12:15]
	v_mfma_f32_16x16x32_bf16 v[8:11], v[160:163], v[210:213], v[8:11]
	v_mfma_f32_16x16x32_bf16 v[60:63], v[148:151], v[190:193], v[60:63]
	v_mfma_f32_16x16x32_bf16 v[56:59], v[164:167], v[190:193], v[56:59]
	v_mfma_f32_16x16x32_bf16 v[44:47], v[148:151], v[198:201], v[44:47]
	v_mfma_f32_16x16x32_bf16 v[40:43], v[164:167], v[198:201], v[40:43]
	v_mfma_f32_16x16x32_bf16 v[28:31], v[148:151], v[206:209], v[28:31]
	v_mfma_f32_16x16x32_bf16 v[24:27], v[164:167], v[206:209], v[24:27]
	v_mfma_f32_16x16x32_bf16 v[12:15], v[148:151], v[214:217], v[12:15]
	v_mfma_f32_16x16x32_bf16 v[8:11], v[164:167], v[214:217], v[8:11]
	v_mfma_f32_16x16x32_bf16 v[52:55], v[168:171], v[186:189], v[52:55]
	v_mfma_f32_16x16x32_bf16 v[48:51], v[178:181], v[186:189], v[48:51]
	v_mfma_f32_16x16x32_bf16 v[36:39], v[168:171], v[194:197], v[36:39]
	v_mfma_f32_16x16x32_bf16 v[32:35], v[178:181], v[194:197], v[32:35]
	v_mfma_f32_16x16x32_bf16 v[20:23], v[168:171], v[202:205], v[20:23]
	v_mfma_f32_16x16x32_bf16 v[16:19], v[178:181], v[202:205], v[16:19]
	v_mfma_f32_16x16x32_bf16 v[4:7], v[168:171], v[210:213], v[4:7]
	v_mfma_f32_16x16x32_bf16 v[0:3], v[178:181], v[210:213], v[0:3]
	v_mfma_f32_16x16x32_bf16 v[52:55], v[174:177], v[190:193], v[52:55]
	v_mfma_f32_16x16x32_bf16 v[48:51], v[182:185], v[190:193], v[48:51]
	v_mfma_f32_16x16x32_bf16 v[36:39], v[174:177], v[198:201], v[36:39]
	v_mfma_f32_16x16x32_bf16 v[32:35], v[182:185], v[198:201], v[32:35]
	v_mfma_f32_16x16x32_bf16 v[20:23], v[174:177], v[206:209], v[20:23]
	v_mfma_f32_16x16x32_bf16 v[16:19], v[182:185], v[206:209], v[16:19]
	v_mfma_f32_16x16x32_bf16 v[4:7], v[174:177], v[214:217], v[4:7]
	v_mfma_f32_16x16x32_bf16 v[0:3], v[182:185], v[214:217], v[0:3]
	s_barrier
	s_add_i32 s45, 0, 0x18000
	v_add_u32_e32 v159, s45, v153
	s_add_i32 s46, 0, 0x1c000
	ds_read_b128 v[144:147], v159
	ds_read_b128 v[148:151], v159 offset:1024
	ds_read_b128 v[160:163], v159 offset:2048
	ds_read_b128 v[164:167], v159 offset:3072
	v_add_u32_e32 v159, s46, v153
	ds_read_b128 v[168:171], v159
	ds_read_b128 v[174:177], v159 offset:1024
	ds_read_b128 v[178:181], v159 offset:2048
	ds_read_b128 v[182:185], v159 offset:3072
	s_add_u32 s22, s22, 0x80000
	s_addc_u32 s23, s23, 0
	s_mov_b32 m0, s29
	v_lshl_add_u64 v[226:227], s[22:23], 0, v[134:135]
	ds_read_b128 v[186:189], v158 offset:32768
	ds_read_b128 v[190:193], v158 offset:33792
	ds_read_b128 v[194:197], v158 offset:34816
	ds_read_b128 v[198:201], v158 offset:35840
	ds_read_b128 v[202:205], v158 offset:36864
	ds_read_b128 v[206:209], v158 offset:37888
	ds_read_b128 v[210:213], v158 offset:38912
	ds_read_b128 v[214:217], v158 offset:39936
	global_load_lds_dwordx4 v[226:227], off
	v_lshl_add_u64 v[226:227], s[22:23], 0, v[130:131]
	s_mov_b32 m0, s30
	s_nop 0
	global_load_lds_dwordx4 v[226:227], off
	s_waitcnt vmcnt(8)
	s_waitcnt lgkmcnt(0)
	s_barrier
	s_waitcnt lgkmcnt(0)
	v_mfma_f32_16x16x32_bf16 v[124:127], v[144:147], v[186:189], v[124:127]
	v_mfma_f32_16x16x32_bf16 v[120:123], v[160:163], v[186:189], v[120:123]
	v_mfma_f32_16x16x32_bf16 v[108:111], v[144:147], v[194:197], v[108:111]
	v_mfma_f32_16x16x32_bf16 v[104:107], v[160:163], v[194:197], v[104:107]
	v_mfma_f32_16x16x32_bf16 v[92:95], v[144:147], v[202:205], v[92:95]
	v_mfma_f32_16x16x32_bf16 v[88:91], v[160:163], v[202:205], v[88:91]
	v_mfma_f32_16x16x32_bf16 v[76:79], v[144:147], v[210:213], v[76:79]
	v_mfma_f32_16x16x32_bf16 v[72:75], v[160:163], v[210:213], v[72:75]
	v_mfma_f32_16x16x32_bf16 v[124:127], v[148:151], v[190:193], v[124:127]
	v_mfma_f32_16x16x32_bf16 v[120:123], v[164:167], v[190:193], v[120:123]
	v_mfma_f32_16x16x32_bf16 v[108:111], v[148:151], v[198:201], v[108:111]
	v_mfma_f32_16x16x32_bf16 v[104:107], v[164:167], v[198:201], v[104:107]
	v_mfma_f32_16x16x32_bf16 v[92:95], v[148:151], v[206:209], v[92:95]
	v_mfma_f32_16x16x32_bf16 v[88:91], v[164:167], v[206:209], v[88:91]
	v_mfma_f32_16x16x32_bf16 v[76:79], v[148:151], v[214:217], v[76:79]
	v_mfma_f32_16x16x32_bf16 v[72:75], v[164:167], v[214:217], v[72:75]
	v_mfma_f32_16x16x32_bf16 v[116:119], v[168:171], v[186:189], v[116:119]
	v_mfma_f32_16x16x32_bf16 v[112:115], v[178:181], v[186:189], v[112:115]
	v_mfma_f32_16x16x32_bf16 v[100:103], v[168:171], v[194:197], v[100:103]
	v_mfma_f32_16x16x32_bf16 v[96:99], v[178:181], v[194:197], v[96:99]
	v_mfma_f32_16x16x32_bf16 v[84:87], v[168:171], v[202:205], v[84:87]
	v_mfma_f32_16x16x32_bf16 v[80:83], v[178:181], v[202:205], v[80:83]
	v_mfma_f32_16x16x32_bf16 v[68:71], v[168:171], v[210:213], v[68:71]
	v_mfma_f32_16x16x32_bf16 v[64:67], v[178:181], v[210:213], v[64:67]
	v_mfma_f32_16x16x32_bf16 v[116:119], v[174:177], v[190:193], v[116:119]
	v_mfma_f32_16x16x32_bf16 v[112:115], v[182:185], v[190:193], v[112:115]
	v_mfma_f32_16x16x32_bf16 v[100:103], v[174:177], v[198:201], v[100:103]
	v_mfma_f32_16x16x32_bf16 v[96:99], v[182:185], v[198:201], v[96:99]
	v_mfma_f32_16x16x32_bf16 v[84:87], v[174:177], v[206:209], v[84:87]
	v_mfma_f32_16x16x32_bf16 v[80:83], v[182:185], v[206:209], v[80:83]
	v_mfma_f32_16x16x32_bf16 v[68:71], v[174:177], v[214:217], v[68:71]
	v_mfma_f32_16x16x32_bf16 v[64:67], v[182:185], v[214:217], v[64:67]
	s_barrier
; #define PG8_STAGE(bufoff, gbase, voff) do { _Pragma("unroll") for (int _i = 0; _i < 2; ++_i) \
;         __builtin_amdgcn_global_load_lds((const unsigned*)((const char*)(gbase) + (voff)[_i]), (PG8_LAS unsigned*)(lds + (bufoff) + ldsw + _i * 8192), 16, 0, 0); } while (0)
; #define PG8_LDA(dst, b, h) do { _Pragma("unroll") for (int m = 0; m < 4; ++m) _Pragma("unroll") for (int k = 0; k < 2; ++k) dst[m][k] = *(const PG8_LAS bf16x8*)(lds + PG8_SA(b, h) + aoff + m * 2048 + k * 1024); } while (0)
; #define PG8_MMA(ai, bj, At, Bt) do { __builtin_amdgcn_s_setprio(1); _Pragma("unroll") for (int m = 0; m < 4; ++m) _Pragma("unroll") for (int n = 0; n < 2; ++n) _Pragma("unroll") for (int k = 0; k < 2; ++k) \
;         acc[ai][bj][m][n] = __builtin_amdgcn_mfma_f32_16x16x32_bf16(Bt[n][k], At[m][k], acc[ai][bj][m][n], 0, 0, 0); __builtin_amdgcn_s_setprio(0); } while (0)
; #define PG8_WAIT_V(n) asm volatile("s_waitcnt vmcnt(" #n ")" ::: "memory")
; #define PG8_WAIT_L(n) asm volatile("s_waitcnt lgkmcnt(" #n ")" ::: "memory")
; #define PG8_BAR __builtin_amdgcn_s_barrier()
; #define PG8_SCHED __builtin_amdgcn_sched_barrier(0)
; template <class Epi, class Sched, bool ALIGN_EPI = false, bool SP2 = false>
; __device__ __forceinline__ void gemm_phase(PG8_LAS unsigned char* lds, const Gemm g, const Sched& S, const Epi& E) {
;     ...
;             PG8_LDA(At, 1, 1); PG8_STAGE(PG8_SB(1, 0), b3, voffB); PG8_STAGE(PG8_SB(1, 1), b3 + hstep, voffB); PG8_STAGE(PG8_SA(1, 0), a3, voffA);
;             PG8_WAIT_V(8); PG8_WAIT_L(0); PG8_BAR; PG8_MMA(1, 0, At, B0); PG8_MMA(1, 1, At, B1); PG8_BAR; PG8_SCHED;
;     ...
;         if constexpr (ALIGN_EPI) { if (wr == 0) PG8_BAR; }
	s_add_i32 s22, s45, s26
	v_lshl_add_u64 v[218:219], v[218:219], 0, s[2:3]
	s_mov_b32 m0, s22
	ds_read_b128 v[186:189], v158 offset:49152
	ds_read_b128 v[190:193], v158 offset:50176
	ds_read_b128 v[194:197], v158 offset:51200
	ds_read_b128 v[198:201], v158 offset:52224
	ds_read_b128 v[202:205], v158 offset:53248
	ds_read_b128 v[206:209], v158 offset:54272
	ds_read_b128 v[210:213], v158 offset:55296
	ds_read_b128 v[214:217], v158 offset:56320
	global_load_lds_dwordx4 v[218:219], off
	s_add_i32 m0, s22, 0x2000
	s_add_u32 s20, s20, 0x80080
	v_lshl_add_u64 v[218:219], v[220:221], 0, s[2:3]
	s_addc_u32 s21, s21, 0
	s_add_i32 s22, s46, s26
	global_load_lds_dwordx4 v[218:219], off
	v_lshl_add_u64 v[218:219], s[20:21], 0, v[132:133]
	s_mov_b32 m0, s22
	s_nop 0
	global_load_lds_dwordx4 v[218:219], off
	v_lshl_add_u64 v[218:219], s[20:21], 0, v[128:129]
	s_add_i32 m0, s22, 0x2000
	s_nop 0
	global_load_lds_dwordx4 v[218:219], off
	v_lshl_add_u64 v[218:219], v[222:223], 0, s[2:3]
	s_mov_b32 m0, s31
	s_nop 0
	global_load_lds_dwordx4 v[218:219], off
	v_lshl_add_u64 v[218:219], v[224:225], 0, s[2:3]
	s_mov_b32 m0, s33
	s_nop 0
	global_load_lds_dwordx4 v[218:219], off
	s_waitcnt vmcnt(8)
	s_waitcnt lgkmcnt(0)
	s_barrier
	s_waitcnt lgkmcnt(0)
	v_mfma_f32_16x16x32_bf16 v[60:63], v[144:147], v[186:189], v[60:63]
	v_mfma_f32_16x16x32_bf16 v[56:59], v[160:163], v[186:189], v[56:59]
	v_mfma_f32_16x16x32_bf16 v[44:47], v[144:147], v[194:197], v[44:47]
	v_mfma_f32_16x16x32_bf16 v[40:43], v[160:163], v[194:197], v[40:43]
	v_mfma_f32_16x16x32_bf16 v[28:31], v[144:147], v[202:205], v[28:31]
	v_mfma_f32_16x16x32_bf16 v[24:27], v[160:163], v[202:205], v[24:27]
	v_mfma_f32_16x16x32_bf16 v[12:15], v[144:147], v[210:213], v[12:15]
	v_mfma_f32_16x16x32_bf16 v[8:11], v[160:163], v[210:213], v[8:11]
	v_mfma_f32_16x16x32_bf16 v[60:63], v[148:151], v[190:193], v[60:63]
	v_mfma_f32_16x16x32_bf16 v[56:59], v[164:167], v[190:193], v[56:59]
	v_mfma_f32_16x16x32_bf16 v[44:47], v[148:151], v[198:201], v[44:47]
	v_mfma_f32_16x16x32_bf16 v[40:43], v[164:167], v[198:201], v[40:43]
	v_mfma_f32_16x16x32_bf16 v[28:31], v[148:151], v[206:209], v[28:31]
	v_mfma_f32_16x16x32_bf16 v[24:27], v[164:167], v[206:209], v[24:27]
	v_mfma_f32_16x16x32_bf16 v[12:15], v[148:151], v[214:217], v[12:15]
	v_mfma_f32_16x16x32_bf16 v[8:11], v[164:167], v[214:217], v[8:11]
	v_mfma_f32_16x16x32_bf16 v[52:55], v[168:171], v[186:189], v[52:55]
	v_mfma_f32_16x16x32_bf16 v[48:51], v[178:181], v[186:189], v[48:51]
	v_mfma_f32_16x16x32_bf16 v[36:39], v[168:171], v[194:197], v[36:39]
	v_mfma_f32_16x16x32_bf16 v[32:35], v[178:181], v[194:197], v[32:35]
	v_mfma_f32_16x16x32_bf16 v[20:23], v[168:171], v[202:205], v[20:23]
	v_mfma_f32_16x16x32_bf16 v[16:19], v[178:181], v[202:205], v[16:19]
	v_mfma_f32_16x16x32_bf16 v[4:7], v[168:171], v[210:213], v[4:7]
	v_mfma_f32_16x16x32_bf16 v[0:3], v[178:181], v[210:213], v[0:3]
	v_mfma_f32_16x16x32_bf16 v[52:55], v[174:177], v[190:193], v[52:55]
	v_mfma_f32_16x16x32_bf16 v[48:51], v[182:185], v[190:193], v[48:51]
	v_mfma_f32_16x16x32_bf16 v[36:39], v[174:177], v[198:201], v[36:39]
	v_mfma_f32_16x16x32_bf16 v[32:35], v[182:185], v[198:201], v[32:35]
	v_mfma_f32_16x16x32_bf16 v[20:23], v[174:177], v[206:209], v[20:23]
	v_mfma_f32_16x16x32_bf16 v[16:19], v[182:185], v[206:209], v[16:19]
	v_mfma_f32_16x16x32_bf16 v[4:7], v[174:177], v[214:217], v[4:7]
	v_mfma_f32_16x16x32_bf16 v[0:3], v[182:185], v[214:217], v[0:3]
	s_barrier
	s_add_i32 s44, s44, 2
	s_add_u32 s18, s18, 0x100
	s_addc_u32 s19, s19, 0
	s_add_u32 s42, s42, 0x100
	s_addc_u32 s43, s43, 0
	s_cmp_gt_u32 s44, 29
	s_cbranch_scc0 .LBB0_1712
	s_and_b64 vcc, exec, s[6:7]
	s_cbranch_vccz .LBB0_1715
	s_barrier

; #define PG8_STAGE(bufoff, gbase, voff) do { _Pragma("unroll") for (int _i = 0; _i < 2; ++_i) \
;         __builtin_amdgcn_global_load_lds((const unsigned*)((const char*)(gbase) + (voff)[_i]), (PG8_LAS unsigned*)(lds + (bufoff) + ldsw + _i * 8192), 16, 0, 0); } while (0)
; #define PG8_LDA(dst, b, h) do { _Pragma("unroll") for (int m = 0; m < 4; ++m) _Pragma("unroll") for (int k = 0; k < 2; ++k) dst[m][k] = *(const PG8_LAS bf16x8*)(lds + PG8_SA(b, h) + aoff + m * 2048 + k * 1024); } while (0)
; #define PG8_LDB(dst, b, h) do { _Pragma("unroll") for (int n = 0; n < 2; ++n) _Pragma("unroll") for (int k = 0; k < 2; ++k) dst[n][k] = *(const PG8_LAS bf16x8*)(lds + PG8_SB(b, h) + boff + n * 2048 + k * 1024); } while (0)
; #define PG8_MMA(ai, bj, At, Bt) do { __builtin_amdgcn_s_setprio(1); _Pragma("unroll") for (int m = 0; m < 4; ++m) _Pragma("unroll") for (int n = 0; n < 2; ++n) _Pragma("unroll") for (int k = 0; k < 2; ++k) \
;         acc[ai][bj][m][n] = __builtin_amdgcn_mfma_f32_16x16x32_bf16(Bt[n][k], At[m][k], acc[ai][bj][m][n], 0, 0, 0); __builtin_amdgcn_s_setprio(0); } while (0)
; #define PG8_WAIT_V(n) asm volatile("s_waitcnt vmcnt(" #n ")" ::: "memory")
; #define PG8_BAR __builtin_amdgcn_s_barrier()
; template <class Epi, class Sched, bool ALIGN_EPI = false, bool SP2 = false>
; __device__ __forceinline__ void gemm_phase(PG8_LAS unsigned char* lds, const Gemm g, const Sched& S, const Epi& E) {
;     ...
;         for (int t = 0; t < nt; t += 2) {
;             const bool last = (t == nt - 2);
;             const char* a1 = cA + (size_t)(t + 1) * kstep;
;             const char* a2 = last ? nA : cA + (size_t)(t + 2) * kstep; const char* b2 = last ? nB : cB + (size_t)(t + 2) * kstep;
;             const char* a3 = a2 + kstep; const char* b3 = b2 + kstep;
;             if (last && has_next) S.a_ready(nxt);
;             if constexpr (SP2) {
;             PG8_LDB(B0, 0, 0); PG8_LDB(B1, 0, 1); PG8_SCHED; PG8_LDA(At, 0, 0); PG8_STAGE(PG8_SA(1, 1), a1 + hstep, voffA);
;             PG8_WAIT_V(8); PG8_WAIT_L(0); PG8_BAR; PG8_MMA(0, 0, At, B0); PG8_MMA(0, 1, At, B1); PG8_BAR; PG8_SCHED;
;             PG8_LDA(At, 0, 1); PG8_STAGE(PG8_SB(0, 0), b2, voffB); PG8_STAGE(PG8_SB(0, 1), b2 + hstep, voffB); PG8_STAGE(PG8_SA(0, 0), a2, voffA);
;             PG8_WAIT_V(8); PG8_WAIT_L(0); PG8_BAR; PG8_MMA(1, 0, At, B0); PG8_MMA(1, 1, At, B1); PG8_BAR; PG8_SCHED;
.LBB0_1956:
	ds_read_b128 v[140:143], v149
	ds_read_b128 v[152:155], v149 offset:1024
	ds_read_b128 v[156:159], v149 offset:2048
	ds_read_b128 v[160:163], v149 offset:3072
	ds_read_b128 v[164:167], v150
	ds_read_b128 v[168:171], v150 offset:1024
	ds_read_b128 v[172:175], v150 offset:2048
	ds_read_b128 v[176:179], v150 offset:3072
	s_add_u32 s22, s20, 0x100
	s_addc_u32 s23, s21, 0
	s_cmpk_eq_i32 s47, 0x54
	s_cselect_b32 s27, s5, s23
	s_cselect_b32 s26, s4, s22
	s_cselect_b32 s25, s19, s46
	s_cselect_b32 s24, s18, s45
	v_lshl_add_u64 v[144:145], s[20:21], 0, v[132:133]
	s_add_i32 m0, s31, 0xc000
	ds_read_b128 v[180:183], v151
	ds_read_b128 v[184:187], v151 offset:1024
	ds_read_b128 v[188:191], v151 offset:2048
	ds_read_b128 v[192:195], v151 offset:3072
	ds_read_b128 v[196:199], v151 offset:4096
	ds_read_b128 v[200:203], v151 offset:5120
	ds_read_b128 v[204:207], v151 offset:6144
	ds_read_b128 v[208:211], v151 offset:7168
	global_load_lds_dwordx4 v[144:145], off
	v_lshl_add_u64 v[144:145], s[20:21], 0, v[134:135]
	s_add_i32 m0, s31, 0xe000
	s_nop 0
	global_load_lds_dwordx4 v[144:145], off
	s_waitcnt vmcnt(8)
	s_waitcnt lgkmcnt(0)
	s_barrier
	s_waitcnt lgkmcnt(0)
	v_mfma_f32_16x16x32_bf16 v[124:127], v[140:143], v[180:183], v[124:127]
	v_mfma_f32_16x16x32_bf16 v[120:123], v[156:159], v[180:183], v[120:123]
	v_mfma_f32_16x16x32_bf16 v[108:111], v[140:143], v[188:191], v[108:111]
	v_mfma_f32_16x16x32_bf16 v[104:107], v[156:159], v[188:191], v[104:107]
	v_mfma_f32_16x16x32_bf16 v[92:95], v[140:143], v[196:199], v[92:95]
	v_mfma_f32_16x16x32_bf16 v[88:91], v[156:159], v[196:199], v[88:91]
	v_mfma_f32_16x16x32_bf16 v[76:79], v[140:143], v[204:207], v[76:79]
	v_mfma_f32_16x16x32_bf16 v[72:75], v[156:159], v[204:207], v[72:75]
	v_mfma_f32_16x16x32_bf16 v[124:127], v[152:155], v[184:187], v[124:127]
	v_mfma_f32_16x16x32_bf16 v[120:123], v[160:163], v[184:187], v[120:123]
	v_mfma_f32_16x16x32_bf16 v[108:111], v[152:155], v[192:195], v[108:111]
	v_mfma_f32_16x16x32_bf16 v[104:107], v[160:163], v[192:195], v[104:107]
	v_mfma_f32_16x16x32_bf16 v[92:95], v[152:155], v[200:203], v[92:95]
	v_mfma_f32_16x16x32_bf16 v[88:91], v[160:163], v[200:203], v[88:91]
	v_mfma_f32_16x16x32_bf16 v[76:79], v[152:155], v[208:211], v[76:79]
	v_mfma_f32_16x16x32_bf16 v[72:75], v[160:163], v[208:211], v[72:75]
	v_mfma_f32_16x16x32_bf16 v[116:119], v[164:167], v[180:183], v[116:119]
	v_mfma_f32_16x16x32_bf16 v[112:115], v[172:175], v[180:183], v[112:115]
	v_mfma_f32_16x16x32_bf16 v[100:103], v[164:167], v[188:191], v[100:103]
	v_mfma_f32_16x16x32_bf16 v[96:99], v[172:175], v[188:191], v[96:99]
	v_mfma_f32_16x16x32_bf16 v[84:87], v[164:167], v[196:199], v[84:87]
	v_mfma_f32_16x16x32_bf16 v[80:83], v[172:175], v[196:199], v[80:83]
	v_mfma_f32_16x16x32_bf16 v[68:71], v[164:167], v[204:207], v[68:71]
	v_mfma_f32_16x16x32_bf16 v[64:67], v[172:175], v[204:207], v[64:67]
	v_mfma_f32_16x16x32_bf16 v[116:119], v[168:171], v[184:187], v[116:119]
	v_mfma_f32_16x16x32_bf16 v[112:115], v[176:179], v[184:187], v[112:115]
	v_mfma_f32_16x16x32_bf16 v[100:103], v[168:171], v[192:195], v[100:103]
	v_mfma_f32_16x16x32_bf16 v[96:99], v[176:179], v[192:195], v[96:99]
	v_mfma_f32_16x16x32_bf16 v[84:87], v[168:171], v[200:203], v[84:87]
	v_mfma_f32_16x16x32_bf16 v[80:83], v[176:179], v[200:203], v[80:83]
	v_mfma_f32_16x16x32_bf16 v[68:71], v[168:171], v[208:211], v[68:71]
	v_mfma_f32_16x16x32_bf16 v[64:67], v[176:179], v[208:211], v[64:67]
	s_barrier
	s_add_i32 s20, s39, s30
	v_lshl_add_u64 v[144:145], s[24:25], 0, v[128:129]
	s_mov_b32 m0, s20
	ds_read_b128 v[180:183], v151 offset:16384
	ds_read_b128 v[184:187], v151 offset:17408
	ds_read_b128 v[188:191], v151 offset:18432
	ds_read_b128 v[192:195], v151 offset:19456
	ds_read_b128 v[196:199], v151 offset:20480
	ds_read_b128 v[200:203], v151 offset:21504
	ds_read_b128 v[204:207], v151 offset:22528
	ds_read_b128 v[208:211], v151 offset:23552
	global_load_lds_dwordx4 v[144:145], off
	s_add_i32 m0, s20, 0x2000
	s_add_u32 s20, s24, 0x160000
	v_lshl_add_u64 v[212:213], s[24:25], 0, v[130:131]
	s_addc_u32 s21, s25, 0
	s_add_i32 s48, s40, s30
	global_load_lds_dwordx4 v[212:213], off
	v_lshl_add_u64 v[214:215], s[20:21], 0, v[128:129]
	s_mov_b32 m0, s48
	v_lshl_add_u64 v[216:217], s[26:27], 0, v[130:131]
	global_load_lds_dwordx4 v[214:215], off
	v_lshl_add_u64 v[214:215], s[20:21], 0, v[130:131]
	s_add_i32 m0, s48, 0x2000
	s_nop 0
	global_load_lds_dwordx4 v[214:215], off
	v_lshl_add_u64 v[214:215], s[26:27], 0, v[128:129]
	s_mov_b32 m0, s31
	s_nop 0
	global_load_lds_dwordx4 v[214:215], off
	s_mov_b32 m0, s33
	s_nop 0
	global_load_lds_dwordx4 v[216:217], off
	s_waitcnt vmcnt(8)
	s_waitcnt lgkmcnt(0)
	s_barrier
; #define PG8_STAGE(bufoff, gbase, voff) do { _Pragma("unroll") for (int _i = 0; _i < 2; ++_i) \
;         __builtin_amdgcn_global_load_lds((const unsigned*)((const char*)(gbase) + (voff)[_i]), (PG8_LAS unsigned*)(lds + (bufoff) + ldsw + _i * 8192), 16, 0, 0); } while (0)
; #define PG8_LDA(dst, b, h) do { _Pragma("unroll") for (int m = 0; m < 4; ++m) _Pragma("unroll") for (int k = 0; k < 2; ++k) dst[m][k] = *(const PG8_LAS bf16x8*)(lds + PG8_SA(b, h) + aoff + m * 2048 + k * 1024); } while (0)
; #define PG8_LDB(dst, b, h) do { _Pragma("unroll") for (int n = 0; n < 2; ++n) _Pragma("unroll") for (int k = 0; k < 2; ++k) dst[n][k] = *(const PG8_LAS bf16x8*)(lds + PG8_SB(b, h) + boff + n * 2048 + k * 1024); } while (0)
; #define PG8_MMA(ai, bj, At, Bt) do { __builtin_amdgcn_s_setprio(1); _Pragma("unroll") for (int m = 0; m < 4; ++m) _Pragma("unroll") for (int n = 0; n < 2; ++n) _Pragma("unroll") for (int k = 0; k < 2; ++k) \
;         acc[ai][bj][m][n] = __builtin_amdgcn_mfma_f32_16x16x32_bf16(Bt[n][k], At[m][k], acc[ai][bj][m][n], 0, 0, 0); __builtin_amdgcn_s_setprio(0); } while (0)
; #define PG8_WAIT_V(n) asm volatile("s_waitcnt vmcnt(" #n ")" ::: "memory")
; #define PG8_WAIT_L(n) asm volatile("s_waitcnt lgkmcnt(" #n ")" ::: "memory")
; #define PG8_BAR __builtin_amdgcn_s_barrier()
; #define PG8_SCHED __builtin_amdgcn_sched_barrier(0)
; template <class Epi, class Sched, bool ALIGN_EPI = false, bool SP2 = false>
; __device__ __forceinline__ void gemm_phase(PG8_LAS unsigned char* lds, const Gemm g, const Sched& S, const Epi& E) {
;     ...
;             PG8_WAIT_V(8); PG8_WAIT_L(0); PG8_BAR; PG8_MMA(1, 0, At, B0); PG8_MMA(1, 1, At, B1); PG8_BAR; PG8_SCHED;
;             PG8_LDB(B0, 1, 0); PG8_LDB(B1, 1, 1); PG8_SCHED; PG8_LDA(At, 1, 0); PG8_STAGE(PG8_SA(0, 1), a2 + hstep, voffA);
;             PG8_WAIT_V(8); PG8_WAIT_L(0); PG8_BAR; PG8_MMA(0, 0, At, B0); PG8_MMA(0, 1, At, B1); PG8_BAR; PG8_SCHED;
	s_waitcnt lgkmcnt(0)
	v_mfma_f32_16x16x32_bf16 v[60:63], v[140:143], v[180:183], v[60:63]
	v_mfma_f32_16x16x32_bf16 v[56:59], v[156:159], v[180:183], v[56:59]
	v_mfma_f32_16x16x32_bf16 v[44:47], v[140:143], v[188:191], v[44:47]
	v_mfma_f32_16x16x32_bf16 v[40:43], v[156:159], v[188:191], v[40:43]
	v_mfma_f32_16x16x32_bf16 v[28:31], v[140:143], v[196:199], v[28:31]
	v_mfma_f32_16x16x32_bf16 v[24:27], v[156:159], v[196:199], v[24:27]
	v_mfma_f32_16x16x32_bf16 v[12:15], v[140:143], v[204:207], v[12:15]
	v_mfma_f32_16x16x32_bf16 v[8:11], v[156:159], v[204:207], v[8:11]
	v_mfma_f32_16x16x32_bf16 v[60:63], v[152:155], v[184:187], v[60:63]
	v_mfma_f32_16x16x32_bf16 v[56:59], v[160:163], v[184:187], v[56:59]
	v_mfma_f32_16x16x32_bf16 v[44:47], v[152:155], v[192:195], v[44:47]
	v_mfma_f32_16x16x32_bf16 v[40:43], v[160:163], v[192:195], v[40:43]
	v_mfma_f32_16x16x32_bf16 v[28:31], v[152:155], v[200:203], v[28:31]
	v_mfma_f32_16x16x32_bf16 v[24:27], v[160:163], v[200:203], v[24:27]
	v_mfma_f32_16x16x32_bf16 v[12:15], v[152:155], v[208:211], v[12:15]
	v_mfma_f32_16x16x32_bf16 v[8:11], v[160:163], v[208:211], v[8:11]
	v_mfma_f32_16x16x32_bf16 v[52:55], v[164:167], v[180:183], v[52:55]
	v_mfma_f32_16x16x32_bf16 v[48:51], v[172:175], v[180:183], v[48:51]
	v_mfma_f32_16x16x32_bf16 v[36:39], v[164:167], v[188:191], v[36:39]
	v_mfma_f32_16x16x32_bf16 v[32:35], v[172:175], v[188:191], v[32:35]
	v_mfma_f32_16x16x32_bf16 v[20:23], v[164:167], v[196:199], v[20:23]
	v_mfma_f32_16x16x32_bf16 v[16:19], v[172:175], v[196:199], v[16:19]
	v_mfma_f32_16x16x32_bf16 v[4:7], v[164:167], v[204:207], v[4:7]
	v_mfma_f32_16x16x32_bf16 v[0:3], v[172:175], v[204:207], v[0:3]
	v_mfma_f32_16x16x32_bf16 v[52:55], v[168:171], v[184:187], v[52:55]
	v_mfma_f32_16x16x32_bf16 v[48:51], v[176:179], v[184:187], v[48:51]
	v_mfma_f32_16x16x32_bf16 v[36:39], v[168:171], v[192:195], v[36:39]
	v_mfma_f32_16x16x32_bf16 v[32:35], v[176:179], v[192:195], v[32:35]
	v_mfma_f32_16x16x32_bf16 v[20:23], v[168:171], v[200:203], v[20:23]
	v_mfma_f32_16x16x32_bf16 v[16:19], v[176:179], v[200:203], v[16:19]
	v_mfma_f32_16x16x32_bf16 v[4:7], v[168:171], v[208:211], v[4:7]
	v_mfma_f32_16x16x32_bf16 v[0:3], v[176:179], v[208:211], v[0:3]
	s_barrier
	s_add_i32 s48, 0, 0x18000
	s_add_i32 s49, 0, 0x1c000
	v_add_u32_e32 v160, s48, v147
	v_add_u32_e32 v176, s49, v147
	ds_read_b128 v[140:143], v160
	ds_read_b128 v[152:155], v160 offset:1024
	ds_read_b128 v[156:159], v160 offset:2048
	ds_read_b128 v[160:163], v160 offset:3072
	ds_read_b128 v[164:167], v176
	ds_read_b128 v[168:171], v176 offset:1024
	ds_read_b128 v[172:175], v176 offset:2048
	ds_read_b128 v[176:179], v176 offset:3072
	s_add_u32 s20, s26, 0x160000
	s_addc_u32 s21, s27, 0
	s_mov_b32 m0, s34
	v_lshl_add_u64 v[218:219], s[20:21], 0, v[128:129]
	ds_read_b128 v[180:183], v151 offset:32768
	ds_read_b128 v[184:187], v151 offset:33792
	ds_read_b128 v[188:191], v151 offset:34816
	ds_read_b128 v[192:195], v151 offset:35840
	ds_read_b128 v[196:199], v151 offset:36864
	ds_read_b128 v[200:203], v151 offset:37888
	ds_read_b128 v[204:207], v151 offset:38912
	ds_read_b128 v[208:211], v151 offset:39936
	global_load_lds_dwordx4 v[218:219], off
	v_lshl_add_u64 v[218:219], s[20:21], 0, v[130:131]
	s_mov_b32 m0, s35
	s_nop 0
	global_load_lds_dwordx4 v[218:219], off
	s_waitcnt vmcnt(8)
	s_waitcnt lgkmcnt(0)
	s_barrier
	s_waitcnt lgkmcnt(0)
	v_mfma_f32_16x16x32_bf16 v[124:127], v[140:143], v[180:183], v[124:127]
	v_mfma_f32_16x16x32_bf16 v[120:123], v[156:159], v[180:183], v[120:123]
	v_mfma_f32_16x16x32_bf16 v[108:111], v[140:143], v[188:191], v[108:111]
	v_mfma_f32_16x16x32_bf16 v[104:107], v[156:159], v[188:191], v[104:107]
	v_mfma_f32_16x16x32_bf16 v[92:95], v[140:143], v[196:199], v[92:95]
	v_mfma_f32_16x16x32_bf16 v[88:91], v[156:159], v[196:199], v[88:91]
	v_mfma_f32_16x16x32_bf16 v[76:79], v[140:143], v[204:207], v[76:79]
	v_mfma_f32_16x16x32_bf16 v[72:75], v[156:159], v[204:207], v[72:75]
	v_mfma_f32_16x16x32_bf16 v[124:127], v[152:155], v[184:187], v[124:127]
	v_mfma_f32_16x16x32_bf16 v[120:123], v[160:163], v[184:187], v[120:123]
	v_mfma_f32_16x16x32_bf16 v[108:111], v[152:155], v[192:195], v[108:111]
	v_mfma_f32_16x16x32_bf16 v[104:107], v[160:163], v[192:195], v[104:107]
	v_mfma_f32_16x16x32_bf16 v[92:95], v[152:155], v[200:203], v[92:95]
	v_mfma_f32_16x16x32_bf16 v[88:91], v[160:163], v[200:203], v[88:91]
	v_mfma_f32_16x16x32_bf16 v[76:79], v[152:155], v[208:211], v[76:79]
	v_mfma_f32_16x16x32_bf16 v[72:75], v[160:163], v[208:211], v[72:75]
	v_mfma_f32_16x16x32_bf16 v[116:119], v[164:167], v[180:183], v[116:119]
	v_mfma_f32_16x16x32_bf16 v[112:115], v[172:175], v[180:183], v[112:115]
	v_mfma_f32_16x16x32_bf16 v[100:103], v[164:167], v[188:191], v[100:103]
	v_mfma_f32_16x16x32_bf16 v[96:99], v[172:175], v[188:191], v[96:99]
	v_mfma_f32_16x16x32_bf16 v[84:87], v[164:167], v[196:199], v[84:87]
	v_mfma_f32_16x16x32_bf16 v[80:83], v[172:175], v[196:199], v[80:83]
	v_mfma_f32_16x16x32_bf16 v[68:71], v[164:167], v[204:207], v[68:71]
	v_mfma_f32_16x16x32_bf16 v[64:67], v[172:175], v[204:207], v[64:67]
	v_mfma_f32_16x16x32_bf16 v[116:119], v[168:171], v[184:187], v[116:119]
	v_mfma_f32_16x16x32_bf16 v[112:115], v[176:179], v[184:187], v[112:115]
	v_mfma_f32_16x16x32_bf16 v[100:103], v[168:171], v[192:195], v[100:103]
	v_mfma_f32_16x16x32_bf16 v[96:99], v[176:179], v[192:195], v[96:99]
	v_mfma_f32_16x16x32_bf16 v[84:87], v[168:171], v[200:203], v[84:87]
	v_mfma_f32_16x16x32_bf16 v[80:83], v[176:179], v[200:203], v[80:83]
	v_mfma_f32_16x16x32_bf16 v[68:71], v[168:171], v[208:211], v[68:71]
	v_mfma_f32_16x16x32_bf16 v[64:67], v[176:179], v[208:211], v[64:67]
	s_barrier
; #define PG8_STAGE(bufoff, gbase, voff) do { _Pragma("unroll") for (int _i = 0; _i < 2; ++_i) \
;         __builtin_amdgcn_global_load_lds((const unsigned*)((const char*)(gbase) + (voff)[_i]), (PG8_LAS unsigned*)(lds + (bufoff) + ldsw + _i * 8192), 16, 0, 0); } while (0)
; #define PG8_LDA(dst, b, h) do { _Pragma("unroll") for (int m = 0; m < 4; ++m) _Pragma("unroll") for (int k = 0; k < 2; ++k) dst[m][k] = *(const PG8_LAS bf16x8*)(lds + PG8_SA(b, h) + aoff + m * 2048 + k * 1024); } while (0)
; #define PG8_MMA(ai, bj, At, Bt) do { __builtin_amdgcn_s_setprio(1); _Pragma("unroll") for (int m = 0; m < 4; ++m) _Pragma("unroll") for (int n = 0; n < 2; ++n) _Pragma("unroll") for (int k = 0; k < 2; ++k) \
;         acc[ai][bj][m][n] = __builtin_amdgcn_mfma_f32_16x16x32_bf16(Bt[n][k], At[m][k], acc[ai][bj][m][n], 0, 0, 0); __builtin_amdgcn_s_setprio(0); } while (0)
; #define PG8_WAIT_V(n) asm volatile("s_waitcnt vmcnt(" #n ")" ::: "memory")
; #define PG8_WAIT_L(n) asm volatile("s_waitcnt lgkmcnt(" #n ")" ::: "memory")
; #define PG8_BAR __builtin_amdgcn_s_barrier()
; #define PG8_SCHED __builtin_amdgcn_sched_barrier(0)
; template <class Epi, class Sched, bool ALIGN_EPI = false, bool SP2 = false>
; __device__ __forceinline__ void gemm_phase(PG8_LAS unsigned char* lds, const Gemm g, const Sched& S, const Epi& E) {
;     ...
;             PG8_LDA(At, 1, 1); PG8_STAGE(PG8_SB(1, 0), b3, voffB); PG8_STAGE(PG8_SB(1, 1), b3 + hstep, voffB); PG8_STAGE(PG8_SA(1, 0), a3, voffA);
;             PG8_WAIT_V(8); PG8_WAIT_L(0); PG8_BAR; PG8_MMA(1, 0, At, B0); PG8_MMA(1, 1, At, B1); PG8_BAR; PG8_SCHED;
;     ...
;         if constexpr (ALIGN_EPI) { if (wr == 0) PG8_BAR; }
	s_add_i32 s20, s48, s30
	v_lshl_add_u64 v[144:145], v[144:145], 0, s[6:7]
	s_mov_b32 m0, s20
	ds_read_b128 v[180:183], v151 offset:49152
	ds_read_b128 v[184:187], v151 offset:50176
	ds_read_b128 v[188:191], v151 offset:51200
	ds_read_b128 v[192:195], v151 offset:52224
	ds_read_b128 v[196:199], v151 offset:53248
	ds_read_b128 v[200:203], v151 offset:54272
	ds_read_b128 v[204:207], v151 offset:55296
	ds_read_b128 v[208:211], v151 offset:56320
	global_load_lds_dwordx4 v[144:145], off
	s_add_i32 m0, s20, 0x2000
	s_add_u32 s20, s24, 0x160080
	v_lshl_add_u64 v[144:145], v[212:213], 0, s[6:7]
	s_addc_u32 s21, s25, 0
	s_add_i32 s24, s49, s30
	global_load_lds_dwordx4 v[144:145], off
	v_lshl_add_u64 v[144:145], s[20:21], 0, v[128:129]
	s_mov_b32 m0, s24
	s_nop 0
	global_load_lds_dwordx4 v[144:145], off
	v_lshl_add_u64 v[144:145], s[20:21], 0, v[130:131]
	s_add_i32 m0, s24, 0x2000
	s_nop 0
	global_load_lds_dwordx4 v[144:145], off
	v_lshl_add_u64 v[144:145], v[214:215], 0, s[6:7]
	s_mov_b32 m0, s37
	s_nop 0
	global_load_lds_dwordx4 v[144:145], off
	v_lshl_add_u64 v[144:145], v[216:217], 0, s[6:7]
	s_mov_b32 m0, s38
	s_nop 0
	global_load_lds_dwordx4 v[144:145], off
	s_waitcnt vmcnt(8)
	s_waitcnt lgkmcnt(0)
	s_barrier
	s_waitcnt lgkmcnt(0)
	v_mfma_f32_16x16x32_bf16 v[60:63], v[140:143], v[180:183], v[60:63]
	v_mfma_f32_16x16x32_bf16 v[56:59], v[156:159], v[180:183], v[56:59]
	v_mfma_f32_16x16x32_bf16 v[44:47], v[140:143], v[188:191], v[44:47]
	v_mfma_f32_16x16x32_bf16 v[40:43], v[156:159], v[188:191], v[40:43]
	v_mfma_f32_16x16x32_bf16 v[28:31], v[140:143], v[196:199], v[28:31]
	v_mfma_f32_16x16x32_bf16 v[24:27], v[156:159], v[196:199], v[24:27]
	v_mfma_f32_16x16x32_bf16 v[12:15], v[140:143], v[204:207], v[12:15]
	v_mfma_f32_16x16x32_bf16 v[8:11], v[156:159], v[204:207], v[8:11]
	v_mfma_f32_16x16x32_bf16 v[60:63], v[152:155], v[184:187], v[60:63]
	v_mfma_f32_16x16x32_bf16 v[56:59], v[160:163], v[184:187], v[56:59]
	v_mfma_f32_16x16x32_bf16 v[44:47], v[152:155], v[192:195], v[44:47]
	v_mfma_f32_16x16x32_bf16 v[40:43], v[160:163], v[192:195], v[40:43]
	v_mfma_f32_16x16x32_bf16 v[28:31], v[152:155], v[200:203], v[28:31]
	v_mfma_f32_16x16x32_bf16 v[24:27], v[160:163], v[200:203], v[24:27]
	v_mfma_f32_16x16x32_bf16 v[12:15], v[152:155], v[208:211], v[12:15]
	v_mfma_f32_16x16x32_bf16 v[8:11], v[160:163], v[208:211], v[8:11]
	v_mfma_f32_16x16x32_bf16 v[52:55], v[164:167], v[180:183], v[52:55]
	v_mfma_f32_16x16x32_bf16 v[48:51], v[172:175], v[180:183], v[48:51]
	v_mfma_f32_16x16x32_bf16 v[36:39], v[164:167], v[188:191], v[36:39]
	v_mfma_f32_16x16x32_bf16 v[32:35], v[172:175], v[188:191], v[32:35]
	v_mfma_f32_16x16x32_bf16 v[20:23], v[164:167], v[196:199], v[20:23]
	v_mfma_f32_16x16x32_bf16 v[16:19], v[172:175], v[196:199], v[16:19]
	v_mfma_f32_16x16x32_bf16 v[4:7], v[164:167], v[204:207], v[4:7]
	v_mfma_f32_16x16x32_bf16 v[0:3], v[172:175], v[204:207], v[0:3]
	v_mfma_f32_16x16x32_bf16 v[52:55], v[168:171], v[184:187], v[52:55]
	v_mfma_f32_16x16x32_bf16 v[48:51], v[176:179], v[184:187], v[48:51]
	v_mfma_f32_16x16x32_bf16 v[36:39], v[168:171], v[192:195], v[36:39]
	v_mfma_f32_16x16x32_bf16 v[32:35], v[176:179], v[192:195], v[32:35]
	v_mfma_f32_16x16x32_bf16 v[20:23], v[168:171], v[200:203], v[20:23]
	v_mfma_f32_16x16x32_bf16 v[16:19], v[176:179], v[200:203], v[16:19]
	v_mfma_f32_16x16x32_bf16 v[4:7], v[168:171], v[208:211], v[4:7]
	v_mfma_f32_16x16x32_bf16 v[0:3], v[176:179], v[208:211], v[0:3]
	s_barrier
	s_add_i32 s47, s47, 2
	s_add_u32 s45, s45, 0x100
	s_addc_u32 s46, s46, 0
	s_cmpk_gt_u32 s47, 0x55
	s_mov_b64 s[20:21], s[22:23]
	s_cbranch_scc0 .LBB0_1956
	s_and_b64 vcc, exec, s[8:9]
	s_cbranch_vccz .LBB0_1959
	s_barrier
